# v21 + the 48 back-to-back s_setprio 0/1 pairs between the two MFMA blocks removed
# speedup vs baseline: 1.0160x; 1.0008x over previous
; #define PG8_STAGE(bufoff, gbase, voff) do { _Pragma("unroll") for (int _i = 0; _i < 2; ++_i) \
;         __builtin_amdgcn_global_load_lds((const unsigned*)((const char*)(gbase) + (voff)[_i]), (PG8_LAS unsigned*)(lds + (bufoff) + ldsw + _i * 8192), 16, 0, 0); } while (0)
; #define PG8_WAIT_V(n) asm volatile("s_waitcnt vmcnt(" #n ")" ::: "memory")
; #define PG8_WAIT_L(n) asm volatile("s_waitcnt lgkmcnt(" #n ")" ::: "memory")
; #define PG8_BAR __builtin_amdgcn_s_barrier()
; #define PG8_SCHED __builtin_amdgcn_sched_barrier(0)
;     __device__ __forceinline__ int nt(const pg8::Unit& u) const { return u.kind == 0 ? ntiles : q_nt(u.kind - 1); }
; template <class Epi, class Sched, bool ALIGN_EPI = true, bool SP2 = true>
; __device__ __forceinline__ void gemm_phase(PG8_LAS unsigned char* lds, const int K  , const Sched& S, const Epi& E) {
;     ...
;         for (int t = 0; t < nt; t += 2) {
;             const bool last = (t == nt - 2);
;             const char* a1 = cA + (size_t)(t + 1) * kstep;
;             const char* a2 = last ? nA : cA + (size_t)(t + 2) * kstep; const char* b2 = last ? nB : cB + (size_t)(t + 2) * kstep;
;             const char* a3 = a2 + kstep; const char* b3 = b2 + kstep;
;             if constexpr (SP2) {
;             PG8_LDB(B0, 0, 0); PG8_LDB(B1, 0, 1); PG8_SCHED; PG8_LDA(At, 0, 0); PG8_STAGE(PG8_SA(1, 1), a1 + hstep, voffA);
;             PG8_WAIT_V(8); PG8_WAIT_L(0); PG8_BAR; PG8_MMA(0, 0, At, B0); PG8_MMA(0, 1, At, B1); PG8_BAR; PG8_SCHED;
;             PG8_LDA(At, 0, 1); PG8_STAGE(PG8_SB(0, 0), b2, voffB); PG8_STAGE(PG8_SB(0, 1), b2 + hstep, voffB); PG8_STAGE(PG8_SA(0, 0), a2, voffA);
.LBB0_219:
	ds_read_b128 v[148:151], v154
	ds_read_b128 v[160:163], v154 offset:1024
	ds_read_b128 v[164:167], v154 offset:2048
	ds_read_b128 v[168:171], v154 offset:3072
	ds_read_b128 v[172:175], v155
	ds_read_b128 v[176:179], v155 offset:1024
	ds_read_b128 v[180:183], v155 offset:2048
	ds_read_b128 v[184:187], v155 offset:3072
	s_add_u32 s22, s20, 0xfff80080
	s_addc_u32 s23, s21, -1
	s_cmp_eq_u32 s48, 28
	s_cselect_b32 s25, s13, s23
	s_cselect_b32 s24, s44, s22
	s_cselect_b32 s23, s11, s47
	s_cselect_b32 s22, s45, s46
	v_lshl_add_u64 v[220:221], s[20:21], 0, v[140:141]
	s_add_i32 m0, s19, 0xc000
	ds_read_b128 v[188:191], v156
	ds_read_b128 v[192:195], v156 offset:1024
	ds_read_b128 v[196:199], v156 offset:2048
	ds_read_b128 v[200:203], v156 offset:3072
	ds_read_b128 v[204:207], v156 offset:4096
	ds_read_b128 v[208:211], v156 offset:5120
	ds_read_b128 v[212:215], v156 offset:6144
	ds_read_b128 v[216:219], v156 offset:7168
	global_load_lds_dwordx4 v[220:221], off
	v_lshl_add_u64 v[220:221], s[20:21], 0, v[142:143]
	s_add_i32 m0, s19, 0xe000
	s_nop 0
	global_load_lds_dwordx4 v[220:221], off
	s_waitcnt vmcnt(8)
	s_waitcnt lgkmcnt(0)
	s_setprio 1
	s_barrier
	v_mfma_f32_16x16x32_bf16 v[126:129], v[148:151], v[188:191], v[126:129]
	v_mfma_f32_16x16x32_bf16 v[118:121], v[164:167], v[188:191], v[118:121]
	v_mfma_f32_16x16x32_bf16 v[110:113], v[148:151], v[196:199], v[110:113]
	v_mfma_f32_16x16x32_bf16 v[102:105], v[164:167], v[196:199], v[102:105]
	v_mfma_f32_16x16x32_bf16 v[94:97], v[148:151], v[204:207], v[94:97]
	v_mfma_f32_16x16x32_bf16 v[86:89], v[164:167], v[204:207], v[86:89]
	v_mfma_f32_16x16x32_bf16 v[78:81], v[148:151], v[212:215], v[78:81]
	v_mfma_f32_16x16x32_bf16 v[70:73], v[164:167], v[212:215], v[70:73]
	v_mfma_f32_16x16x32_bf16 v[126:129], v[160:163], v[192:195], v[126:129]
	v_mfma_f32_16x16x32_bf16 v[118:121], v[168:171], v[192:195], v[118:121]
	v_mfma_f32_16x16x32_bf16 v[110:113], v[160:163], v[200:203], v[110:113]
	v_mfma_f32_16x16x32_bf16 v[102:105], v[168:171], v[200:203], v[102:105]
	v_mfma_f32_16x16x32_bf16 v[94:97], v[160:163], v[208:211], v[94:97]
	v_mfma_f32_16x16x32_bf16 v[86:89], v[168:171], v[208:211], v[86:89]
	v_mfma_f32_16x16x32_bf16 v[78:81], v[160:163], v[216:219], v[78:81]
	v_mfma_f32_16x16x32_bf16 v[70:73], v[168:171], v[216:219], v[70:73]
	v_mfma_f32_16x16x32_bf16 v[122:125], v[172:175], v[188:191], v[122:125]
	v_mfma_f32_16x16x32_bf16 v[114:117], v[180:183], v[188:191], v[114:117]
	v_mfma_f32_16x16x32_bf16 v[106:109], v[172:175], v[196:199], v[106:109]
	v_mfma_f32_16x16x32_bf16 v[98:101], v[180:183], v[196:199], v[98:101]
	v_mfma_f32_16x16x32_bf16 v[90:93], v[172:175], v[204:207], v[90:93]
	v_mfma_f32_16x16x32_bf16 v[82:85], v[180:183], v[204:207], v[82:85]
	v_mfma_f32_16x16x32_bf16 v[74:77], v[172:175], v[212:215], v[74:77]
	v_mfma_f32_16x16x32_bf16 v[66:69], v[180:183], v[212:215], v[66:69]
	v_mfma_f32_16x16x32_bf16 v[122:125], v[176:179], v[192:195], v[122:125]
	v_mfma_f32_16x16x32_bf16 v[114:117], v[184:187], v[192:195], v[114:117]
	v_mfma_f32_16x16x32_bf16 v[106:109], v[176:179], v[200:203], v[106:109]
	v_mfma_f32_16x16x32_bf16 v[98:101], v[184:187], v[200:203], v[98:101]
	v_mfma_f32_16x16x32_bf16 v[90:93], v[176:179], v[208:211], v[90:93]
	v_mfma_f32_16x16x32_bf16 v[82:85], v[184:187], v[208:211], v[82:85]
	v_mfma_f32_16x16x32_bf16 v[74:77], v[176:179], v[216:219], v[74:77]
	v_mfma_f32_16x16x32_bf16 v[66:69], v[184:187], v[216:219], v[66:69]
	s_barrier
	s_setprio 0
	s_add_i32 s49, s39, s29
	v_lshl_add_u64 v[220:221], s[22:23], 0, v[136:137]
	s_mov_b32 m0, s49
	ds_read_b128 v[188:191], v156 offset:16384
	ds_read_b128 v[192:195], v156 offset:17408
	ds_read_b128 v[196:199], v156 offset:18432
	ds_read_b128 v[200:203], v156 offset:19456
	ds_read_b128 v[204:207], v156 offset:20480
	ds_read_b128 v[208:211], v156 offset:21504
	ds_read_b128 v[212:215], v156 offset:22528
	ds_read_b128 v[216:219], v156 offset:23552
	global_load_lds_dwordx4 v[220:221], off
	s_add_i32 m0, s49, 0x2000
	s_add_u32 s50, s22, 0x80000
	v_lshl_add_u64 v[222:223], s[22:23], 0, v[132:133]
	s_addc_u32 s51, s23, 0
	s_add_i32 s49, s40, s29
	global_load_lds_dwordx4 v[222:223], off
	v_lshl_add_u64 v[224:225], s[50:51], 0, v[136:137]
	s_mov_b32 m0, s49
	v_lshl_add_u64 v[226:227], s[24:25], 0, v[134:135]
	global_load_lds_dwordx4 v[224:225], off
	v_lshl_add_u64 v[224:225], s[50:51], 0, v[132:133]
	s_add_i32 m0, s49, 0x2000
	s_nop 0
	global_load_lds_dwordx4 v[224:225], off
	v_lshl_add_u64 v[224:225], s[24:25], 0, v[138:139]
	s_mov_b32 m0, s19
	s_nop 0
	global_load_lds_dwordx4 v[224:225], off
	s_mov_b32 m0, s31
	s_nop 0
	global_load_lds_dwordx4 v[226:227], off
	s_waitcnt vmcnt(8)
	s_waitcnt lgkmcnt(0)
	s_setprio 1
	s_barrier
; #define PG8_STAGE(bufoff, gbase, voff) do { _Pragma("unroll") for (int _i = 0; _i < 2; ++_i) \
;         __builtin_amdgcn_global_load_lds((const unsigned*)((const char*)(gbase) + (voff)[_i]), (PG8_LAS unsigned*)(lds + (bufoff) + ldsw + _i * 8192), 16, 0, 0); } while (0)
; #define PG8_WAIT_V(n) asm volatile("s_waitcnt vmcnt(" #n ")" ::: "memory")
; #define PG8_WAIT_L(n) asm volatile("s_waitcnt lgkmcnt(" #n ")" ::: "memory")
; #define PG8_BAR __builtin_amdgcn_s_barrier()
; #define PG8_SCHED __builtin_amdgcn_sched_barrier(0)
; template <class Epi, class Sched, bool ALIGN_EPI = true, bool SP2 = true>
; __device__ __forceinline__ void gemm_phase(PG8_LAS unsigned char* lds, const int K  , const Sched& S, const Epi& E) {
;     ...
;             PG8_WAIT_V(8); PG8_WAIT_L(0); PG8_BAR; PG8_MMA(1, 0, At, B0); PG8_MMA(1, 1, At, B1); PG8_BAR; PG8_SCHED;
;             PG8_LDB(B0, 1, 0); PG8_LDB(B1, 1, 1); PG8_SCHED; PG8_LDA(At, 1, 0); PG8_STAGE(PG8_SA(0, 1), a2 + hstep, voffA);
;             PG8_WAIT_V(8); PG8_WAIT_L(0); PG8_BAR; PG8_MMA(0, 0, At, B0); PG8_MMA(0, 1, At, B1); PG8_BAR; PG8_SCHED;
	v_mfma_f32_16x16x32_bf16 v[62:65], v[148:151], v[188:191], v[62:65]
	v_mfma_f32_16x16x32_bf16 v[54:57], v[164:167], v[188:191], v[54:57]
	v_mfma_f32_16x16x32_bf16 v[46:49], v[148:151], v[196:199], v[46:49]
	v_mfma_f32_16x16x32_bf16 v[38:41], v[164:167], v[196:199], v[38:41]
	v_mfma_f32_16x16x32_bf16 v[30:33], v[148:151], v[204:207], v[30:33]
	v_mfma_f32_16x16x32_bf16 v[22:25], v[164:167], v[204:207], v[22:25]
	v_mfma_f32_16x16x32_bf16 v[14:17], v[148:151], v[212:215], v[14:17]
	v_mfma_f32_16x16x32_bf16 v[6:9], v[164:167], v[212:215], v[6:9]
	v_mfma_f32_16x16x32_bf16 v[62:65], v[160:163], v[192:195], v[62:65]
	v_mfma_f32_16x16x32_bf16 v[54:57], v[168:171], v[192:195], v[54:57]
	v_mfma_f32_16x16x32_bf16 v[46:49], v[160:163], v[200:203], v[46:49]
	v_mfma_f32_16x16x32_bf16 v[38:41], v[168:171], v[200:203], v[38:41]
	v_mfma_f32_16x16x32_bf16 v[30:33], v[160:163], v[208:211], v[30:33]
	v_mfma_f32_16x16x32_bf16 v[22:25], v[168:171], v[208:211], v[22:25]
	v_mfma_f32_16x16x32_bf16 v[14:17], v[160:163], v[216:219], v[14:17]
	v_mfma_f32_16x16x32_bf16 v[6:9], v[168:171], v[216:219], v[6:9]
	v_mfma_f32_16x16x32_bf16 v[58:61], v[172:175], v[188:191], v[58:61]
	v_mfma_f32_16x16x32_bf16 v[50:53], v[180:183], v[188:191], v[50:53]
	v_mfma_f32_16x16x32_bf16 v[42:45], v[172:175], v[196:199], v[42:45]
	v_mfma_f32_16x16x32_bf16 v[34:37], v[180:183], v[196:199], v[34:37]
	v_mfma_f32_16x16x32_bf16 v[26:29], v[172:175], v[204:207], v[26:29]
	v_mfma_f32_16x16x32_bf16 v[18:21], v[180:183], v[204:207], v[18:21]
	v_mfma_f32_16x16x32_bf16 v[10:13], v[172:175], v[212:215], v[10:13]
	v_mfma_f32_16x16x32_bf16 v[2:5], v[180:183], v[212:215], v[2:5]
	v_mfma_f32_16x16x32_bf16 v[58:61], v[176:179], v[192:195], v[58:61]
	v_mfma_f32_16x16x32_bf16 v[50:53], v[184:187], v[192:195], v[50:53]
	v_mfma_f32_16x16x32_bf16 v[42:45], v[176:179], v[200:203], v[42:45]
	v_mfma_f32_16x16x32_bf16 v[34:37], v[184:187], v[200:203], v[34:37]
	v_mfma_f32_16x16x32_bf16 v[26:29], v[176:179], v[208:211], v[26:29]
	v_mfma_f32_16x16x32_bf16 v[18:21], v[184:187], v[208:211], v[18:21]
	v_mfma_f32_16x16x32_bf16 v[10:13], v[176:179], v[216:219], v[10:13]
	v_mfma_f32_16x16x32_bf16 v[2:5], v[184:187], v[216:219], v[2:5]
	s_barrier
	s_setprio 0
	s_add_i32 s49, 0, 0x18000
	v_add_u32_e32 v159, s49, v152
	s_add_i32 s50, 0, 0x1c000
	ds_read_b128 v[148:151], v159
	ds_read_b128 v[160:163], v159 offset:1024
	ds_read_b128 v[164:167], v159 offset:2048
	ds_read_b128 v[168:171], v159 offset:3072
	v_add_u32_e32 v159, s50, v152
	ds_read_b128 v[172:175], v159
	ds_read_b128 v[176:179], v159 offset:1024
	ds_read_b128 v[180:183], v159 offset:2048
	ds_read_b128 v[184:187], v159 offset:3072
	s_add_u32 s24, s24, 0x80000
	s_addc_u32 s25, s25, 0
	s_mov_b32 m0, s33
	v_lshl_add_u64 v[230:231], s[24:25], 0, v[138:139]
	ds_read_b128 v[188:191], v156 offset:32768
	ds_read_b128 v[192:195], v156 offset:33792
	ds_read_b128 v[196:199], v156 offset:34816
	ds_read_b128 v[200:203], v156 offset:35840
	ds_read_b128 v[204:207], v156 offset:36864
	ds_read_b128 v[208:211], v156 offset:37888
	ds_read_b128 v[212:215], v156 offset:38912
	ds_read_b128 v[216:219], v156 offset:39936
	global_load_lds_dwordx4 v[230:231], off
	v_lshl_add_u64 v[230:231], s[24:25], 0, v[134:135]
	s_mov_b32 m0, s34
	s_nop 0
	global_load_lds_dwordx4 v[230:231], off
	s_waitcnt vmcnt(8)
	s_waitcnt lgkmcnt(0)
	s_setprio 1
	s_barrier
	v_mfma_f32_16x16x32_bf16 v[126:129], v[148:151], v[188:191], v[126:129]
	v_mfma_f32_16x16x32_bf16 v[118:121], v[164:167], v[188:191], v[118:121]
	v_mfma_f32_16x16x32_bf16 v[110:113], v[148:151], v[196:199], v[110:113]
	v_mfma_f32_16x16x32_bf16 v[102:105], v[164:167], v[196:199], v[102:105]
	v_mfma_f32_16x16x32_bf16 v[94:97], v[148:151], v[204:207], v[94:97]
	v_mfma_f32_16x16x32_bf16 v[86:89], v[164:167], v[204:207], v[86:89]
	v_mfma_f32_16x16x32_bf16 v[78:81], v[148:151], v[212:215], v[78:81]
	v_mfma_f32_16x16x32_bf16 v[70:73], v[164:167], v[212:215], v[70:73]
	v_mfma_f32_16x16x32_bf16 v[126:129], v[160:163], v[192:195], v[126:129]
	v_mfma_f32_16x16x32_bf16 v[118:121], v[168:171], v[192:195], v[118:121]
	v_mfma_f32_16x16x32_bf16 v[110:113], v[160:163], v[200:203], v[110:113]
	v_mfma_f32_16x16x32_bf16 v[102:105], v[168:171], v[200:203], v[102:105]
	v_mfma_f32_16x16x32_bf16 v[94:97], v[160:163], v[208:211], v[94:97]
	v_mfma_f32_16x16x32_bf16 v[86:89], v[168:171], v[208:211], v[86:89]
	v_mfma_f32_16x16x32_bf16 v[78:81], v[160:163], v[216:219], v[78:81]
	v_mfma_f32_16x16x32_bf16 v[70:73], v[168:171], v[216:219], v[70:73]
	v_mfma_f32_16x16x32_bf16 v[122:125], v[172:175], v[188:191], v[122:125]
	v_mfma_f32_16x16x32_bf16 v[114:117], v[180:183], v[188:191], v[114:117]
	v_mfma_f32_16x16x32_bf16 v[106:109], v[172:175], v[196:199], v[106:109]
	v_mfma_f32_16x16x32_bf16 v[98:101], v[180:183], v[196:199], v[98:101]
	v_mfma_f32_16x16x32_bf16 v[90:93], v[172:175], v[204:207], v[90:93]
	v_mfma_f32_16x16x32_bf16 v[82:85], v[180:183], v[204:207], v[82:85]
	v_mfma_f32_16x16x32_bf16 v[74:77], v[172:175], v[212:215], v[74:77]
	v_mfma_f32_16x16x32_bf16 v[66:69], v[180:183], v[212:215], v[66:69]
	v_mfma_f32_16x16x32_bf16 v[122:125], v[176:179], v[192:195], v[122:125]
	v_mfma_f32_16x16x32_bf16 v[114:117], v[184:187], v[192:195], v[114:117]
	v_mfma_f32_16x16x32_bf16 v[106:109], v[176:179], v[200:203], v[106:109]
	v_mfma_f32_16x16x32_bf16 v[98:101], v[184:187], v[200:203], v[98:101]
	v_mfma_f32_16x16x32_bf16 v[90:93], v[176:179], v[208:211], v[90:93]
	v_mfma_f32_16x16x32_bf16 v[82:85], v[184:187], v[208:211], v[82:85]
	v_mfma_f32_16x16x32_bf16 v[74:77], v[176:179], v[216:219], v[74:77]
	v_mfma_f32_16x16x32_bf16 v[66:69], v[184:187], v[216:219], v[66:69]
	s_barrier
; #define PG8_STAGE(bufoff, gbase, voff) do { _Pragma("unroll") for (int _i = 0; _i < 2; ++_i) \
;         __builtin_amdgcn_global_load_lds((const unsigned*)((const char*)(gbase) + (voff)[_i]), (PG8_LAS unsigned*)(lds + (bufoff) + ldsw + _i * 8192), 16, 0, 0); } while (0)
; #define PG8_WAIT_V(n) asm volatile("s_waitcnt vmcnt(" #n ")" ::: "memory")
; #define PG8_WAIT_L(n) asm volatile("s_waitcnt lgkmcnt(" #n ")" ::: "memory")
; #define PG8_BAR __builtin_amdgcn_s_barrier()
; #define PG8_SCHED __builtin_amdgcn_sched_barrier(0)
; template <class Epi, class Sched, bool ALIGN_EPI = true, bool SP2 = true>
; __device__ __forceinline__ void gemm_phase(PG8_LAS unsigned char* lds, const int K  , const Sched& S, const Epi& E) {
;     ...
;             PG8_LDA(At, 1, 1); PG8_STAGE(PG8_SB(1, 0), b3, voffB); PG8_STAGE(PG8_SB(1, 1), b3 + hstep, voffB); PG8_STAGE(PG8_SA(1, 0), a3, voffA);
;             PG8_WAIT_V(8); PG8_WAIT_L(0); PG8_BAR; PG8_MMA(1, 0, At, B0); PG8_MMA(1, 1, At, B1); PG8_BAR; PG8_SCHED;
;     ...
;         }
;         if constexpr (Epi::FP8) asm volatile("s_nop 15\n\ts_nop 15\n\ts_nop 15\n\ts_nop 15\n\ts_nop 15" ::: "memory");
;         if constexpr (ALIGN_EPI) { if (wr == 0) PG8_BAR; }
	s_setprio 0
	s_add_i32 s24, s49, s29
	v_lshl_add_u64 v[220:221], v[220:221], 0, s[6:7]
	s_mov_b32 m0, s24
	ds_read_b128 v[188:191], v156 offset:49152
	ds_read_b128 v[192:195], v156 offset:50176
	ds_read_b128 v[196:199], v156 offset:51200
	ds_read_b128 v[200:203], v156 offset:52224
	ds_read_b128 v[204:207], v156 offset:53248
	ds_read_b128 v[208:211], v156 offset:54272
	ds_read_b128 v[212:215], v156 offset:55296
	ds_read_b128 v[216:219], v156 offset:56320
	global_load_lds_dwordx4 v[220:221], off
	s_add_i32 m0, s24, 0x2000
	s_add_u32 s22, s22, 0x80080
	v_lshl_add_u64 v[220:221], v[222:223], 0, s[6:7]
	s_addc_u32 s23, s23, 0
	s_add_i32 s24, s50, s29
	global_load_lds_dwordx4 v[220:221], off
	v_lshl_add_u64 v[220:221], s[22:23], 0, v[136:137]
	s_mov_b32 m0, s24
	s_nop 0
	global_load_lds_dwordx4 v[220:221], off
	v_lshl_add_u64 v[220:221], s[22:23], 0, v[132:133]
	s_add_i32 m0, s24, 0x2000
	s_nop 0
	global_load_lds_dwordx4 v[220:221], off
	v_lshl_add_u64 v[220:221], v[224:225], 0, s[6:7]
	s_mov_b32 m0, s36
	s_nop 0
	global_load_lds_dwordx4 v[220:221], off
	v_lshl_add_u64 v[220:221], v[226:227], 0, s[6:7]
	s_mov_b32 m0, s37
	s_nop 0
	global_load_lds_dwordx4 v[220:221], off
	s_waitcnt vmcnt(8)
	s_waitcnt lgkmcnt(0)
	s_setprio 1
	s_barrier
	v_mfma_f32_16x16x32_bf16 v[62:65], v[148:151], v[188:191], v[62:65]
	v_mfma_f32_16x16x32_bf16 v[54:57], v[164:167], v[188:191], v[54:57]
	v_mfma_f32_16x16x32_bf16 v[46:49], v[148:151], v[196:199], v[46:49]
	v_mfma_f32_16x16x32_bf16 v[38:41], v[164:167], v[196:199], v[38:41]
	v_mfma_f32_16x16x32_bf16 v[30:33], v[148:151], v[204:207], v[30:33]
	v_mfma_f32_16x16x32_bf16 v[22:25], v[164:167], v[204:207], v[22:25]
	v_mfma_f32_16x16x32_bf16 v[14:17], v[148:151], v[212:215], v[14:17]
	v_mfma_f32_16x16x32_bf16 v[6:9], v[164:167], v[212:215], v[6:9]
	v_mfma_f32_16x16x32_bf16 v[62:65], v[160:163], v[192:195], v[62:65]
	v_mfma_f32_16x16x32_bf16 v[54:57], v[168:171], v[192:195], v[54:57]
	v_mfma_f32_16x16x32_bf16 v[46:49], v[160:163], v[200:203], v[46:49]
	v_mfma_f32_16x16x32_bf16 v[38:41], v[168:171], v[200:203], v[38:41]
	v_mfma_f32_16x16x32_bf16 v[30:33], v[160:163], v[208:211], v[30:33]
	v_mfma_f32_16x16x32_bf16 v[22:25], v[168:171], v[208:211], v[22:25]
	v_mfma_f32_16x16x32_bf16 v[14:17], v[160:163], v[216:219], v[14:17]
	v_mfma_f32_16x16x32_bf16 v[6:9], v[168:171], v[216:219], v[6:9]
	v_mfma_f32_16x16x32_bf16 v[58:61], v[172:175], v[188:191], v[58:61]
	v_mfma_f32_16x16x32_bf16 v[50:53], v[180:183], v[188:191], v[50:53]
	v_mfma_f32_16x16x32_bf16 v[42:45], v[172:175], v[196:199], v[42:45]
	v_mfma_f32_16x16x32_bf16 v[34:37], v[180:183], v[196:199], v[34:37]
	v_mfma_f32_16x16x32_bf16 v[26:29], v[172:175], v[204:207], v[26:29]
	v_mfma_f32_16x16x32_bf16 v[18:21], v[180:183], v[204:207], v[18:21]
	v_mfma_f32_16x16x32_bf16 v[10:13], v[172:175], v[212:215], v[10:13]
	v_mfma_f32_16x16x32_bf16 v[2:5], v[180:183], v[212:215], v[2:5]
	v_mfma_f32_16x16x32_bf16 v[58:61], v[176:179], v[192:195], v[58:61]
	v_mfma_f32_16x16x32_bf16 v[50:53], v[184:187], v[192:195], v[50:53]
	v_mfma_f32_16x16x32_bf16 v[42:45], v[176:179], v[200:203], v[42:45]
	v_mfma_f32_16x16x32_bf16 v[34:37], v[184:187], v[200:203], v[34:37]
	v_mfma_f32_16x16x32_bf16 v[26:29], v[176:179], v[208:211], v[26:29]
	v_mfma_f32_16x16x32_bf16 v[18:21], v[184:187], v[208:211], v[18:21]
	v_mfma_f32_16x16x32_bf16 v[10:13], v[176:179], v[216:219], v[10:13]
	v_mfma_f32_16x16x32_bf16 v[2:5], v[184:187], v[216:219], v[2:5]
	s_barrier
	s_setprio 0
	s_add_i32 s48, s48, 2
	s_add_u32 s20, s20, 0x100
	s_addc_u32 s21, s21, 0
	s_add_u32 s46, s46, 0x100
	s_addc_u32 s47, s47, 0
	s_cmp_gt_u32 s48, 29
	s_cbranch_scc0 .LBB0_219
	s_and_b64 vcc, exec, s[8:9]
	s_cbranch_vccz .LBB0_222
	s_barrier

; #define PG8_STAGE(bufoff, gbase, voff) do { _Pragma("unroll") for (int _i = 0; _i < 2; ++_i) \
;         __builtin_amdgcn_global_load_lds((const unsigned*)((const char*)(gbase) + (voff)[_i]), (PG8_LAS unsigned*)(lds + (bufoff) + ldsw + _i * 8192), 16, 0, 0); } while (0)
; #define PG8_WAIT_V(n) asm volatile("s_waitcnt vmcnt(" #n ")" ::: "memory")
; #define PG8_WAIT_L(n) asm volatile("s_waitcnt lgkmcnt(" #n ")" ::: "memory")
; #define PG8_BAR __builtin_amdgcn_s_barrier()
; #define PG8_SCHED __builtin_amdgcn_sched_barrier(0)
;     __device__ __forceinline__ int nt(const pg8::Unit& u) const { return u.kind == 0 ? ntiles : q_nt(u.kind - 1); }
; template <class Epi, class Sched, bool ALIGN_EPI = true, bool SP2 = true>
; __device__ __forceinline__ void gemm_phase(PG8_LAS unsigned char* lds, const int K  , const Sched& S, const Epi& E) {
;     ...
;             const bool last = (t == nt - 2);
;             const char* a1 = cA + (size_t)(t + 1) * kstep;
;             const char* a2 = last ? nA : cA + (size_t)(t + 2) * kstep; const char* b2 = last ? nB : cB + (size_t)(t + 2) * kstep;
;             const char* a3 = a2 + kstep; const char* b3 = b2 + kstep;
;             if constexpr (SP2) {
;             PG8_LDB(B0, 0, 0); PG8_LDB(B1, 0, 1); PG8_SCHED; PG8_LDA(At, 0, 0); PG8_STAGE(PG8_SA(1, 1), a1 + hstep, voffA);
;             PG8_WAIT_V(8); PG8_WAIT_L(0); PG8_BAR; PG8_MMA(0, 0, At, B0); PG8_MMA(0, 1, At, B1); PG8_BAR; PG8_SCHED;
;             PG8_LDA(At, 0, 1); PG8_STAGE(PG8_SB(0, 0), b2, voffB); PG8_STAGE(PG8_SB(0, 1), b2 + hstep, voffB); PG8_STAGE(PG8_SA(0, 0), a2, voffA);
;             PG8_WAIT_V(8); PG8_WAIT_L(0); PG8_BAR; PG8_MMA(1, 0, At, B0); PG8_MMA(1, 1, At, B1); PG8_BAR; PG8_SCHED;
.LBB0_393:
	ds_read_b128 v[18:21], v190
	ds_read_b128 v[22:25], v190 offset:1024
	ds_read_b128 v[26:29], v190 offset:2048
	ds_read_b128 v[30:33], v190 offset:3072
	ds_read_b128 v[2:5], v191
	ds_read_b128 v[6:9], v191 offset:1024
	ds_read_b128 v[10:13], v191 offset:2048
	ds_read_b128 v[14:17], v191 offset:3072
	s_add_i32 s50, s22, 2
	s_add_u32 s20, s18, 0xfff50080
	s_addc_u32 s21, s19, -1
	s_cmp_eq_u32 s47, s22
	s_cselect_b32 s22, s14, s20
	s_cselect_b32 s23, s15, s21
	s_cselect_b32 s21, s17, s49
	s_cselect_b32 s20, s16, s48
	v_lshl_add_u64 v[218:219], s[18:19], 0, v[170:171]
	s_add_i32 m0, s26, 0xc000
	ds_read_b128 v[178:181], v192
	ds_read_b128 v[182:185], v192 offset:1024
	ds_read_b128 v[194:197], v192 offset:2048
	ds_read_b128 v[198:201], v192 offset:3072
	ds_read_b128 v[202:205], v192 offset:4096
	ds_read_b128 v[206:209], v192 offset:5120
	ds_read_b128 v[210:213], v192 offset:6144
	ds_read_b128 v[214:217], v192 offset:7168
	global_load_lds_dwordx4 v[218:219], off
	v_lshl_add_u64 v[218:219], s[18:19], 0, v[172:173]
	s_add_i32 m0, s26, 0xe000
	s_nop 0
	global_load_lds_dwordx4 v[218:219], off
	s_waitcnt vmcnt(8)
	s_waitcnt lgkmcnt(0)
	s_setprio 1
	s_barrier
	v_mfma_scale_f32_16x16x128_f8f6f4 v[158:161], v[18:25], v[178:185], v[158:161], v186, v186 op_sel_hi:[0,0,0]
	v_mfma_scale_f32_16x16x128_f8f6f4 v[154:157], v[26:33], v[178:185], v[154:157], v186, v186 op_sel_hi:[0,0,0]
	v_mfma_scale_f32_16x16x128_f8f6f4 v[150:153], v[18:25], v[194:201], v[150:153], v186, v186 op_sel_hi:[0,0,0]
	v_mfma_scale_f32_16x16x128_f8f6f4 v[142:145], v[26:33], v[194:201], v[142:145], v186, v186 op_sel_hi:[0,0,0]
	v_mfma_scale_f32_16x16x128_f8f6f4 v[134:137], v[18:25], v[202:209], v[134:137], v186, v186 op_sel_hi:[0,0,0]
	v_mfma_scale_f32_16x16x128_f8f6f4 v[126:129], v[26:33], v[202:209], v[126:129], v186, v186 op_sel_hi:[0,0,0]
	v_mfma_scale_f32_16x16x128_f8f6f4 v[118:121], v[18:25], v[210:217], v[118:121], v186, v186 op_sel_hi:[0,0,0]
	v_mfma_scale_f32_16x16x128_f8f6f4 v[110:113], v[26:33], v[210:217], v[110:113], v186, v186 op_sel_hi:[0,0,0]
	v_mfma_scale_f32_16x16x128_f8f6f4 v[146:149], v[2:9], v[178:185], v[146:149], v186, v186 op_sel_hi:[0,0,0]
	v_mfma_scale_f32_16x16x128_f8f6f4 v[138:141], v[10:17], v[178:185], v[138:141], v186, v186 op_sel_hi:[0,0,0]
	v_mfma_scale_f32_16x16x128_f8f6f4 v[130:133], v[2:9], v[194:201], v[130:133], v186, v186 op_sel_hi:[0,0,0]
	v_mfma_scale_f32_16x16x128_f8f6f4 v[122:125], v[10:17], v[194:201], v[122:125], v186, v186 op_sel_hi:[0,0,0]
	v_mfma_scale_f32_16x16x128_f8f6f4 v[114:117], v[2:9], v[202:209], v[114:117], v186, v186 op_sel_hi:[0,0,0]
	v_mfma_scale_f32_16x16x128_f8f6f4 v[106:109], v[10:17], v[202:209], v[106:109], v186, v186 op_sel_hi:[0,0,0]
	v_mfma_scale_f32_16x16x128_f8f6f4 v[102:105], v[2:9], v[210:217], v[102:105], v186, v186 op_sel_hi:[0,0,0]
	v_mfma_scale_f32_16x16x128_f8f6f4 v[98:101], v[10:17], v[210:217], v[98:101], v186, v186 op_sel_hi:[0,0,0]
	s_barrier
	s_setprio 0
	s_add_i32 s51, s37, s25
	v_lshl_add_u64 v[178:179], s[20:21], 0, v[164:165]
	s_mov_b32 m0, s51
	ds_read_b128 v[194:197], v192 offset:16384
	ds_read_b128 v[198:201], v192 offset:17408
	ds_read_b128 v[202:205], v192 offset:18432
	ds_read_b128 v[206:209], v192 offset:19456
	ds_read_b128 v[210:213], v192 offset:20480
	ds_read_b128 v[214:217], v192 offset:21504
	ds_read_b128 v[218:221], v192 offset:22528
	ds_read_b128 v[222:225], v192 offset:23552
	global_load_lds_dwordx4 v[178:179], off
	s_add_i32 m0, s51, 0x2000
	s_add_u32 s68, s20, 0xb0000
	v_lshl_add_u64 v[180:181], s[20:21], 0, v[168:169]
	s_addc_u32 s69, s21, 0
	s_add_i32 s51, s38, s25
	global_load_lds_dwordx4 v[180:181], off
	v_lshl_add_u64 v[182:183], s[68:69], 0, v[164:165]
	s_mov_b32 m0, s51
	v_lshl_add_u64 v[184:185], s[22:23], 0, v[166:167]
	global_load_lds_dwordx4 v[182:183], off
	v_lshl_add_u64 v[182:183], s[68:69], 0, v[168:169]
	s_add_i32 m0, s51, 0x2000
	s_nop 0
	global_load_lds_dwordx4 v[182:183], off
	v_lshl_add_u64 v[182:183], s[22:23], 0, v[162:163]
	s_mov_b32 m0, s26
	s_nop 0
	global_load_lds_dwordx4 v[182:183], off
	s_mov_b32 m0, s27
	s_nop 0
	global_load_lds_dwordx4 v[184:185], off
	s_waitcnt vmcnt(8)
	s_waitcnt lgkmcnt(0)
	s_setprio 1
	s_barrier
	v_mfma_scale_f32_16x16x128_f8f6f4 v[94:97], v[18:25], v[194:201], v[94:97], v186, v186 op_sel_hi:[0,0,0]
	v_mfma_scale_f32_16x16x128_f8f6f4 v[90:93], v[26:33], v[194:201], v[90:93], v186, v186 op_sel_hi:[0,0,0]
	v_mfma_scale_f32_16x16x128_f8f6f4 v[86:89], v[18:25], v[202:209], v[86:89], v186, v186 op_sel_hi:[0,0,0]
	v_mfma_scale_f32_16x16x128_f8f6f4 v[78:81], v[26:33], v[202:209], v[78:81], v186, v186 op_sel_hi:[0,0,0]
	v_mfma_scale_f32_16x16x128_f8f6f4 v[70:73], v[18:25], v[210:217], v[70:73], v186, v186 op_sel_hi:[0,0,0]
	v_mfma_scale_f32_16x16x128_f8f6f4 v[62:65], v[26:33], v[210:217], v[62:65], v186, v186 op_sel_hi:[0,0,0]
	v_mfma_scale_f32_16x16x128_f8f6f4 v[54:57], v[18:25], v[218:225], v[54:57], v186, v186 op_sel_hi:[0,0,0]
	v_mfma_scale_f32_16x16x128_f8f6f4 v[46:49], v[26:33], v[218:225], v[46:49], v186, v186 op_sel_hi:[0,0,0]
	v_mfma_scale_f32_16x16x128_f8f6f4 v[82:85], v[2:9], v[194:201], v[82:85], v186, v186 op_sel_hi:[0,0,0]
	v_mfma_scale_f32_16x16x128_f8f6f4 v[74:77], v[10:17], v[194:201], v[74:77], v186, v186 op_sel_hi:[0,0,0]
	v_mfma_scale_f32_16x16x128_f8f6f4 v[66:69], v[2:9], v[202:209], v[66:69], v186, v186 op_sel_hi:[0,0,0]
	v_mfma_scale_f32_16x16x128_f8f6f4 v[58:61], v[10:17], v[202:209], v[58:61], v186, v186 op_sel_hi:[0,0,0]
	v_mfma_scale_f32_16x16x128_f8f6f4 v[50:53], v[2:9], v[210:217], v[50:53], v186, v186 op_sel_hi:[0,0,0]
	v_mfma_scale_f32_16x16x128_f8f6f4 v[42:45], v[10:17], v[210:217], v[42:45], v186, v186 op_sel_hi:[0,0,0]
	v_mfma_scale_f32_16x16x128_f8f6f4 v[38:41], v[2:9], v[218:225], v[38:41], v186, v186 op_sel_hi:[0,0,0]
	v_mfma_scale_f32_16x16x128_f8f6f4 v[34:37], v[10:17], v[218:225], v[34:37], v186, v186 op_sel_hi:[0,0,0]
	s_barrier
; #define PG8_STAGE(bufoff, gbase, voff) do { _Pragma("unroll") for (int _i = 0; _i < 2; ++_i) \
;         __builtin_amdgcn_global_load_lds((const unsigned*)((const char*)(gbase) + (voff)[_i]), (PG8_LAS unsigned*)(lds + (bufoff) + ldsw + _i * 8192), 16, 0, 0); } while (0)
; #define PG8_WAIT_V(n) asm volatile("s_waitcnt vmcnt(" #n ")" ::: "memory")
; #define PG8_WAIT_L(n) asm volatile("s_waitcnt lgkmcnt(" #n ")" ::: "memory")
; #define PG8_BAR __builtin_amdgcn_s_barrier()
; #define PG8_SCHED __builtin_amdgcn_sched_barrier(0)
; template <class Epi, class Sched, bool ALIGN_EPI = true, bool SP2 = true>
; __device__ __forceinline__ void gemm_phase(PG8_LAS unsigned char* lds, const int K  , const Sched& S, const Epi& E) {
;     ...
;             PG8_LDB(B0, 1, 0); PG8_LDB(B1, 1, 1); PG8_SCHED; PG8_LDA(At, 1, 0); PG8_STAGE(PG8_SA(0, 1), a2 + hstep, voffA);
;             PG8_WAIT_V(8); PG8_WAIT_L(0); PG8_BAR; PG8_MMA(0, 0, At, B0); PG8_MMA(0, 1, At, B1); PG8_BAR; PG8_SCHED;
;             PG8_LDA(At, 1, 1); PG8_STAGE(PG8_SB(1, 0), b3, voffB); PG8_STAGE(PG8_SB(1, 1), b3 + hstep, voffB); PG8_STAGE(PG8_SA(1, 0), a3, voffA);
;             PG8_WAIT_V(8); PG8_WAIT_L(0); PG8_BAR; PG8_MMA(1, 0, At, B0); PG8_MMA(1, 1, At, B1); PG8_BAR; PG8_SCHED;
;     ...
;         if constexpr (Epi::FP8) asm volatile("s_nop 15\n\ts_nop 15\n\ts_nop 15\n\ts_nop 15\n\ts_nop 15" ::: "memory");
;         if constexpr (ALIGN_EPI) { if (wr == 0) PG8_BAR; }
	s_setprio 0
	s_add_i32 s51, 0, 0x18000
	s_add_i32 s68, 0, 0x1c000
	v_add_u32_e32 v14, s51, v188
	v_add_u32_e32 v30, s68, v188
	ds_read_b128 v[2:5], v14
	ds_read_b128 v[6:9], v14 offset:1024
	ds_read_b128 v[10:13], v14 offset:2048
	ds_read_b128 v[14:17], v14 offset:3072
	ds_read_b128 v[18:21], v30
	ds_read_b128 v[22:25], v30 offset:1024
	ds_read_b128 v[26:29], v30 offset:2048
	ds_read_b128 v[30:33], v30 offset:3072
	s_add_u32 s22, s22, 0xb0000
	s_addc_u32 s23, s23, 0
	s_mov_b32 m0, s28
	v_lshl_add_u64 v[226:227], s[22:23], 0, v[162:163]
	ds_read_b128 v[194:197], v192 offset:32768
	ds_read_b128 v[198:201], v192 offset:33792
	ds_read_b128 v[202:205], v192 offset:34816
	ds_read_b128 v[206:209], v192 offset:35840
	ds_read_b128 v[210:213], v192 offset:36864
	ds_read_b128 v[214:217], v192 offset:37888
	ds_read_b128 v[218:221], v192 offset:38912
	ds_read_b128 v[222:225], v192 offset:39936
	global_load_lds_dwordx4 v[226:227], off
	v_lshl_add_u64 v[226:227], s[22:23], 0, v[166:167]
	s_mov_b32 m0, s29
	s_nop 0
	global_load_lds_dwordx4 v[226:227], off
	s_waitcnt vmcnt(8)
	s_waitcnt lgkmcnt(0)
	s_setprio 1
	s_barrier
	v_mfma_scale_f32_16x16x128_f8f6f4 v[158:161], v[2:9], v[194:201], v[158:161], v186, v186 op_sel_hi:[0,0,0]
	v_mfma_scale_f32_16x16x128_f8f6f4 v[154:157], v[10:17], v[194:201], v[154:157], v186, v186 op_sel_hi:[0,0,0]
	v_mfma_scale_f32_16x16x128_f8f6f4 v[150:153], v[2:9], v[202:209], v[150:153], v186, v186 op_sel_hi:[0,0,0]
	v_mfma_scale_f32_16x16x128_f8f6f4 v[142:145], v[10:17], v[202:209], v[142:145], v186, v186 op_sel_hi:[0,0,0]
	v_mfma_scale_f32_16x16x128_f8f6f4 v[134:137], v[2:9], v[210:217], v[134:137], v186, v186 op_sel_hi:[0,0,0]
	v_mfma_scale_f32_16x16x128_f8f6f4 v[126:129], v[10:17], v[210:217], v[126:129], v186, v186 op_sel_hi:[0,0,0]
	v_mfma_scale_f32_16x16x128_f8f6f4 v[118:121], v[2:9], v[218:225], v[118:121], v186, v186 op_sel_hi:[0,0,0]
	v_mfma_scale_f32_16x16x128_f8f6f4 v[110:113], v[10:17], v[218:225], v[110:113], v186, v186 op_sel_hi:[0,0,0]
	v_mfma_scale_f32_16x16x128_f8f6f4 v[146:149], v[18:25], v[194:201], v[146:149], v186, v186 op_sel_hi:[0,0,0]
	v_mfma_scale_f32_16x16x128_f8f6f4 v[138:141], v[26:33], v[194:201], v[138:141], v186, v186 op_sel_hi:[0,0,0]
	v_mfma_scale_f32_16x16x128_f8f6f4 v[130:133], v[18:25], v[202:209], v[130:133], v186, v186 op_sel_hi:[0,0,0]
	v_mfma_scale_f32_16x16x128_f8f6f4 v[122:125], v[26:33], v[202:209], v[122:125], v186, v186 op_sel_hi:[0,0,0]
	v_mfma_scale_f32_16x16x128_f8f6f4 v[114:117], v[18:25], v[210:217], v[114:117], v186, v186 op_sel_hi:[0,0,0]
	v_mfma_scale_f32_16x16x128_f8f6f4 v[106:109], v[26:33], v[210:217], v[106:109], v186, v186 op_sel_hi:[0,0,0]
	v_mfma_scale_f32_16x16x128_f8f6f4 v[102:105], v[18:25], v[218:225], v[102:105], v186, v186 op_sel_hi:[0,0,0]
	v_mfma_scale_f32_16x16x128_f8f6f4 v[98:101], v[26:33], v[218:225], v[98:101], v186, v186 op_sel_hi:[0,0,0]
	s_barrier
	s_setprio 0
	s_add_i32 s22, s51, s25
	v_lshl_add_u64 v[178:179], v[178:179], 0, s[8:9]
	s_mov_b32 m0, s22
	ds_read_b128 v[194:197], v192 offset:49152
	ds_read_b128 v[198:201], v192 offset:50176
	ds_read_b128 v[202:205], v192 offset:51200
	ds_read_b128 v[206:209], v192 offset:52224
	ds_read_b128 v[210:213], v192 offset:53248
	ds_read_b128 v[214:217], v192 offset:54272
	ds_read_b128 v[218:221], v192 offset:55296
	ds_read_b128 v[222:225], v192 offset:56320
	global_load_lds_dwordx4 v[178:179], off
	s_add_i32 m0, s22, 0x2000
	s_add_u32 s20, s20, 0xb0080
	v_lshl_add_u64 v[178:179], v[180:181], 0, s[8:9]
	s_addc_u32 s21, s21, 0
	s_add_i32 s22, s68, s25
	global_load_lds_dwordx4 v[178:179], off
	v_lshl_add_u64 v[178:179], s[20:21], 0, v[164:165]
	s_mov_b32 m0, s22
	s_nop 0
	global_load_lds_dwordx4 v[178:179], off
	v_lshl_add_u64 v[178:179], s[20:21], 0, v[168:169]
	s_add_i32 m0, s22, 0x2000
	s_nop 0
	global_load_lds_dwordx4 v[178:179], off
	v_lshl_add_u64 v[178:179], v[182:183], 0, s[8:9]
	s_mov_b32 m0, s33
	s_nop 0
	global_load_lds_dwordx4 v[178:179], off
	v_lshl_add_u64 v[178:179], v[184:185], 0, s[8:9]
	s_mov_b32 m0, s34
	s_nop 0
	global_load_lds_dwordx4 v[178:179], off
	s_waitcnt vmcnt(8)
	s_waitcnt lgkmcnt(0)
	s_setprio 1
	s_barrier
	v_mfma_scale_f32_16x16x128_f8f6f4 v[94:97], v[2:9], v[194:201], v[94:97], v186, v186 op_sel_hi:[0,0,0]
	v_mfma_scale_f32_16x16x128_f8f6f4 v[90:93], v[10:17], v[194:201], v[90:93], v186, v186 op_sel_hi:[0,0,0]
	v_mfma_scale_f32_16x16x128_f8f6f4 v[86:89], v[2:9], v[202:209], v[86:89], v186, v186 op_sel_hi:[0,0,0]
	v_mfma_scale_f32_16x16x128_f8f6f4 v[78:81], v[10:17], v[202:209], v[78:81], v186, v186 op_sel_hi:[0,0,0]
	v_mfma_scale_f32_16x16x128_f8f6f4 v[70:73], v[2:9], v[210:217], v[70:73], v186, v186 op_sel_hi:[0,0,0]
	v_mfma_scale_f32_16x16x128_f8f6f4 v[62:65], v[10:17], v[210:217], v[62:65], v186, v186 op_sel_hi:[0,0,0]
	v_mfma_scale_f32_16x16x128_f8f6f4 v[54:57], v[2:9], v[218:225], v[54:57], v186, v186 op_sel_hi:[0,0,0]
	v_mfma_scale_f32_16x16x128_f8f6f4 v[46:49], v[10:17], v[218:225], v[46:49], v186, v186 op_sel_hi:[0,0,0]
	v_mfma_scale_f32_16x16x128_f8f6f4 v[82:85], v[18:25], v[194:201], v[82:85], v186, v186 op_sel_hi:[0,0,0]
	v_mfma_scale_f32_16x16x128_f8f6f4 v[74:77], v[26:33], v[194:201], v[74:77], v186, v186 op_sel_hi:[0,0,0]
	v_mfma_scale_f32_16x16x128_f8f6f4 v[66:69], v[18:25], v[202:209], v[66:69], v186, v186 op_sel_hi:[0,0,0]
	v_mfma_scale_f32_16x16x128_f8f6f4 v[58:61], v[26:33], v[202:209], v[58:61], v186, v186 op_sel_hi:[0,0,0]
	v_mfma_scale_f32_16x16x128_f8f6f4 v[50:53], v[18:25], v[210:217], v[50:53], v186, v186 op_sel_hi:[0,0,0]
	v_mfma_scale_f32_16x16x128_f8f6f4 v[42:45], v[26:33], v[210:217], v[42:45], v186, v186 op_sel_hi:[0,0,0]
	v_mfma_scale_f32_16x16x128_f8f6f4 v[38:41], v[18:25], v[218:225], v[38:41], v186, v186 op_sel_hi:[0,0,0]
	v_mfma_scale_f32_16x16x128_f8f6f4 v[34:37], v[26:33], v[218:225], v[34:37], v186, v186 op_sel_hi:[0,0,0]
	s_barrier
	s_setprio 0
	s_add_u32 s18, s18, 0x100
	s_addc_u32 s19, s19, 0
	s_add_u32 s48, s48, 0x100
	s_addc_u32 s49, s49, 0
	s_cmp_ge_u32 s50, s4
	s_mov_b32 s22, s50
	s_cbranch_scc0 .LBB0_393
	s_nop 15
	s_nop 15
	s_nop 15
	s_nop 15
	s_nop 15
	s_and_b64 vcc, exec, s[10:11]
	s_cbranch_vccz .LBB0_396
	s_barrier

; #define PG8_STAGE(bufoff, gbase, voff) do { _Pragma("unroll") for (int _i = 0; _i < 2; ++_i) \
;         __builtin_amdgcn_global_load_lds((const unsigned*)((const char*)(gbase) + (voff)[_i]), (PG8_LAS unsigned*)(lds + (bufoff) + ldsw + _i * 8192), 16, 0, 0); } while (0)
; #define PG8_WAIT_V(n) asm volatile("s_waitcnt vmcnt(" #n ")" ::: "memory")
; #define PG8_WAIT_L(n) asm volatile("s_waitcnt lgkmcnt(" #n ")" ::: "memory")
; #define PG8_BAR __builtin_amdgcn_s_barrier()
; #define PG8_SCHED __builtin_amdgcn_sched_barrier(0)
;     __device__ __forceinline__ int nt(const pg8::Unit& u) const { return u.kind == 0 ? ntiles : q_nt(u.kind - 1); }
; template <class Epi, class Sched, bool ALIGN_EPI = true, bool SP2 = true>
; __device__ __forceinline__ void gemm_phase(PG8_LAS unsigned char* lds, const int K  , const Sched& S, const Epi& E) {
;     ...
;             const bool last = (t == nt - 2);
;             const char* a1 = cA + (size_t)(t + 1) * kstep;
;             const char* a2 = last ? nA : cA + (size_t)(t + 2) * kstep; const char* b2 = last ? nB : cB + (size_t)(t + 2) * kstep;
;             const char* a3 = a2 + kstep; const char* b3 = b2 + kstep;
;             if constexpr (SP2) {
;             PG8_LDB(B0, 0, 0); PG8_LDB(B1, 0, 1); PG8_SCHED; PG8_LDA(At, 0, 0); PG8_STAGE(PG8_SA(1, 1), a1 + hstep, voffA);
;             PG8_WAIT_V(8); PG8_WAIT_L(0); PG8_BAR; PG8_MMA(0, 0, At, B0); PG8_MMA(0, 1, At, B1); PG8_BAR; PG8_SCHED;
;             PG8_LDA(At, 0, 1); PG8_STAGE(PG8_SB(0, 0), b2, voffB); PG8_STAGE(PG8_SB(0, 1), b2 + hstep, voffB); PG8_STAGE(PG8_SA(0, 0), a2, voffA);
.LBB0_537:
	ds_read_b128 v[150:153], v156
	ds_read_b128 v[160:163], v156 offset:1024
	ds_read_b128 v[164:167], v156 offset:2048
	ds_read_b128 v[168:171], v156 offset:3072
	ds_read_b128 v[172:175], v157
	ds_read_b128 v[176:179], v157 offset:1024
	ds_read_b128 v[180:183], v157 offset:2048
	ds_read_b128 v[184:187], v157 offset:3072
	s_add_u32 s22, s20, 0xfff80080
	s_addc_u32 s23, s21, -1
	s_cmp_eq_u32 s47, 28
	s_cselect_b32 s25, s13, s23
	s_cselect_b32 s24, s19, s22
	s_cselect_b32 s23, s11, s46
	s_cselect_b32 s22, s44, s45
	v_lshl_add_u64 v[220:221], s[20:21], 0, v[142:143]
	s_add_i32 m0, s31, 0xc000
	ds_read_b128 v[188:191], v158
	ds_read_b128 v[192:195], v158 offset:1024
	ds_read_b128 v[196:199], v158 offset:2048
	ds_read_b128 v[200:203], v158 offset:3072
	ds_read_b128 v[204:207], v158 offset:4096
	ds_read_b128 v[208:211], v158 offset:5120
	ds_read_b128 v[212:215], v158 offset:6144
	ds_read_b128 v[216:219], v158 offset:7168
	global_load_lds_dwordx4 v[220:221], off
	v_lshl_add_u64 v[220:221], s[20:21], 0, v[144:145]
	s_add_i32 m0, s31, 0xe000
	s_nop 0
	global_load_lds_dwordx4 v[220:221], off
	s_waitcnt vmcnt(8)
	s_waitcnt lgkmcnt(0)
	s_setprio 1
	s_barrier
	v_mfma_f32_16x16x32_bf16 v[126:129], v[150:153], v[188:191], v[126:129]
	v_mfma_f32_16x16x32_bf16 v[122:125], v[164:167], v[188:191], v[122:125]
	v_mfma_f32_16x16x32_bf16 v[118:121], v[150:153], v[196:199], v[118:121]
	v_mfma_f32_16x16x32_bf16 v[110:113], v[164:167], v[196:199], v[110:113]
	v_mfma_f32_16x16x32_bf16 v[102:105], v[150:153], v[204:207], v[102:105]
	v_mfma_f32_16x16x32_bf16 v[94:97], v[164:167], v[204:207], v[94:97]
	v_mfma_f32_16x16x32_bf16 v[86:89], v[150:153], v[212:215], v[86:89]
	v_mfma_f32_16x16x32_bf16 v[78:81], v[164:167], v[212:215], v[78:81]
	v_mfma_f32_16x16x32_bf16 v[126:129], v[160:163], v[192:195], v[126:129]
	v_mfma_f32_16x16x32_bf16 v[122:125], v[168:171], v[192:195], v[122:125]
	v_mfma_f32_16x16x32_bf16 v[118:121], v[160:163], v[200:203], v[118:121]
	v_mfma_f32_16x16x32_bf16 v[110:113], v[168:171], v[200:203], v[110:113]
	v_mfma_f32_16x16x32_bf16 v[102:105], v[160:163], v[208:211], v[102:105]
	v_mfma_f32_16x16x32_bf16 v[94:97], v[168:171], v[208:211], v[94:97]
	v_mfma_f32_16x16x32_bf16 v[86:89], v[160:163], v[216:219], v[86:89]
	v_mfma_f32_16x16x32_bf16 v[78:81], v[168:171], v[216:219], v[78:81]
	v_mfma_f32_16x16x32_bf16 v[114:117], v[172:175], v[188:191], v[114:117]
	v_mfma_f32_16x16x32_bf16 v[106:109], v[180:183], v[188:191], v[106:109]
	v_mfma_f32_16x16x32_bf16 v[98:101], v[172:175], v[196:199], v[98:101]
	v_mfma_f32_16x16x32_bf16 v[90:93], v[180:183], v[196:199], v[90:93]
	v_mfma_f32_16x16x32_bf16 v[82:85], v[172:175], v[204:207], v[82:85]
	v_mfma_f32_16x16x32_bf16 v[74:77], v[180:183], v[204:207], v[74:77]
	v_mfma_f32_16x16x32_bf16 v[70:73], v[172:175], v[212:215], v[70:73]
	v_mfma_f32_16x16x32_bf16 v[66:69], v[180:183], v[212:215], v[66:69]
	v_mfma_f32_16x16x32_bf16 v[114:117], v[176:179], v[192:195], v[114:117]
	v_mfma_f32_16x16x32_bf16 v[106:109], v[184:187], v[192:195], v[106:109]
	v_mfma_f32_16x16x32_bf16 v[98:101], v[176:179], v[200:203], v[98:101]
	v_mfma_f32_16x16x32_bf16 v[90:93], v[184:187], v[200:203], v[90:93]
	v_mfma_f32_16x16x32_bf16 v[82:85], v[176:179], v[208:211], v[82:85]
	v_mfma_f32_16x16x32_bf16 v[74:77], v[184:187], v[208:211], v[74:77]
	v_mfma_f32_16x16x32_bf16 v[70:73], v[176:179], v[216:219], v[70:73]
	v_mfma_f32_16x16x32_bf16 v[66:69], v[184:187], v[216:219], v[66:69]
	s_barrier
	s_setprio 0
	s_add_i32 s48, s40, s29
	v_lshl_add_u64 v[220:221], s[22:23], 0, v[136:137]
	s_mov_b32 m0, s48
	ds_read_b128 v[188:191], v158 offset:16384
	ds_read_b128 v[192:195], v158 offset:17408
	ds_read_b128 v[196:199], v158 offset:18432
	ds_read_b128 v[200:203], v158 offset:19456
	ds_read_b128 v[204:207], v158 offset:20480
	ds_read_b128 v[208:211], v158 offset:21504
	ds_read_b128 v[212:215], v158 offset:22528
	ds_read_b128 v[216:219], v158 offset:23552
	global_load_lds_dwordx4 v[220:221], off
	s_add_i32 m0, s48, 0x2000
	s_add_u32 s48, s22, 0x80000
	v_lshl_add_u64 v[222:223], s[22:23], 0, v[132:133]
	s_addc_u32 s49, s23, 0
	s_add_i32 s50, s41, s29
	global_load_lds_dwordx4 v[222:223], off
	v_lshl_add_u64 v[224:225], s[48:49], 0, v[136:137]
	s_mov_b32 m0, s50
	v_lshl_add_u64 v[226:227], s[24:25], 0, v[134:135]
	global_load_lds_dwordx4 v[224:225], off
	v_lshl_add_u64 v[224:225], s[48:49], 0, v[132:133]
	s_add_i32 m0, s50, 0x2000
	s_nop 0
	global_load_lds_dwordx4 v[224:225], off
	v_lshl_add_u64 v[224:225], s[24:25], 0, v[138:139]
	s_mov_b32 m0, s31
	s_nop 0
	global_load_lds_dwordx4 v[224:225], off
	s_mov_b32 m0, s33
	s_nop 0
	global_load_lds_dwordx4 v[226:227], off
	s_waitcnt vmcnt(8)
	s_waitcnt lgkmcnt(0)
	s_setprio 1
	s_barrier
; #define PG8_STAGE(bufoff, gbase, voff) do { _Pragma("unroll") for (int _i = 0; _i < 2; ++_i) \
;         __builtin_amdgcn_global_load_lds((const unsigned*)((const char*)(gbase) + (voff)[_i]), (PG8_LAS unsigned*)(lds + (bufoff) + ldsw + _i * 8192), 16, 0, 0); } while (0)
; #define PG8_WAIT_V(n) asm volatile("s_waitcnt vmcnt(" #n ")" ::: "memory")
; #define PG8_WAIT_L(n) asm volatile("s_waitcnt lgkmcnt(" #n ")" ::: "memory")
; #define PG8_BAR __builtin_amdgcn_s_barrier()
; #define PG8_SCHED __builtin_amdgcn_sched_barrier(0)
; template <class Epi, class Sched, bool ALIGN_EPI = true, bool SP2 = true>
; __device__ __forceinline__ void gemm_phase(PG8_LAS unsigned char* lds, const int K  , const Sched& S, const Epi& E) {
;     ...
;             PG8_WAIT_V(8); PG8_WAIT_L(0); PG8_BAR; PG8_MMA(1, 0, At, B0); PG8_MMA(1, 1, At, B1); PG8_BAR; PG8_SCHED;
;             PG8_LDB(B0, 1, 0); PG8_LDB(B1, 1, 1); PG8_SCHED; PG8_LDA(At, 1, 0); PG8_STAGE(PG8_SA(0, 1), a2 + hstep, voffA);
;             PG8_WAIT_V(8); PG8_WAIT_L(0); PG8_BAR; PG8_MMA(0, 0, At, B0); PG8_MMA(0, 1, At, B1); PG8_BAR; PG8_SCHED;
	v_mfma_f32_16x16x32_bf16 v[62:65], v[150:153], v[188:191], v[62:65]
	v_mfma_f32_16x16x32_bf16 v[58:61], v[164:167], v[188:191], v[58:61]
	v_mfma_f32_16x16x32_bf16 v[54:57], v[150:153], v[196:199], v[54:57]
	v_mfma_f32_16x16x32_bf16 v[46:49], v[164:167], v[196:199], v[46:49]
	v_mfma_f32_16x16x32_bf16 v[38:41], v[150:153], v[204:207], v[38:41]
	v_mfma_f32_16x16x32_bf16 v[30:33], v[164:167], v[204:207], v[30:33]
	v_mfma_f32_16x16x32_bf16 v[22:25], v[150:153], v[212:215], v[22:25]
	v_mfma_f32_16x16x32_bf16 v[14:17], v[164:167], v[212:215], v[14:17]
	v_mfma_f32_16x16x32_bf16 v[62:65], v[160:163], v[192:195], v[62:65]
	v_mfma_f32_16x16x32_bf16 v[58:61], v[168:171], v[192:195], v[58:61]
	v_mfma_f32_16x16x32_bf16 v[54:57], v[160:163], v[200:203], v[54:57]
	v_mfma_f32_16x16x32_bf16 v[46:49], v[168:171], v[200:203], v[46:49]
	v_mfma_f32_16x16x32_bf16 v[38:41], v[160:163], v[208:211], v[38:41]
	v_mfma_f32_16x16x32_bf16 v[30:33], v[168:171], v[208:211], v[30:33]
	v_mfma_f32_16x16x32_bf16 v[22:25], v[160:163], v[216:219], v[22:25]
	v_mfma_f32_16x16x32_bf16 v[14:17], v[168:171], v[216:219], v[14:17]
	v_mfma_f32_16x16x32_bf16 v[50:53], v[172:175], v[188:191], v[50:53]
	v_mfma_f32_16x16x32_bf16 v[42:45], v[180:183], v[188:191], v[42:45]
	v_mfma_f32_16x16x32_bf16 v[34:37], v[172:175], v[196:199], v[34:37]
	v_mfma_f32_16x16x32_bf16 v[26:29], v[180:183], v[196:199], v[26:29]
	v_mfma_f32_16x16x32_bf16 v[18:21], v[172:175], v[204:207], v[18:21]
	v_mfma_f32_16x16x32_bf16 v[10:13], v[180:183], v[204:207], v[10:13]
	v_mfma_f32_16x16x32_bf16 v[6:9], v[172:175], v[212:215], v[6:9]
	v_mfma_f32_16x16x32_bf16 v[2:5], v[180:183], v[212:215], v[2:5]
	v_mfma_f32_16x16x32_bf16 v[50:53], v[176:179], v[192:195], v[50:53]
	v_mfma_f32_16x16x32_bf16 v[42:45], v[184:187], v[192:195], v[42:45]
	v_mfma_f32_16x16x32_bf16 v[34:37], v[176:179], v[200:203], v[34:37]
	v_mfma_f32_16x16x32_bf16 v[26:29], v[184:187], v[200:203], v[26:29]
	v_mfma_f32_16x16x32_bf16 v[18:21], v[176:179], v[208:211], v[18:21]
	v_mfma_f32_16x16x32_bf16 v[10:13], v[184:187], v[208:211], v[10:13]
	v_mfma_f32_16x16x32_bf16 v[6:9], v[176:179], v[216:219], v[6:9]
	v_mfma_f32_16x16x32_bf16 v[2:5], v[184:187], v[216:219], v[2:5]
	s_barrier
	s_setprio 0
	s_add_i32 s48, 0, 0x18000
	v_add_u32_e32 v140, s48, v154
	s_add_i32 s49, 0, 0x1c000
	ds_read_b128 v[150:153], v140
	ds_read_b128 v[160:163], v140 offset:1024
	ds_read_b128 v[164:167], v140 offset:2048
	ds_read_b128 v[168:171], v140 offset:3072
	v_add_u32_e32 v140, s49, v154
	ds_read_b128 v[172:175], v140
	ds_read_b128 v[176:179], v140 offset:1024
	ds_read_b128 v[180:183], v140 offset:2048
	ds_read_b128 v[184:187], v140 offset:3072
	s_add_u32 s24, s24, 0x80000
	s_addc_u32 s25, s25, 0
	s_mov_b32 m0, s34
	v_lshl_add_u64 v[230:231], s[24:25], 0, v[138:139]
	ds_read_b128 v[188:191], v158 offset:32768
	ds_read_b128 v[192:195], v158 offset:33792
	ds_read_b128 v[196:199], v158 offset:34816
	ds_read_b128 v[200:203], v158 offset:35840
	ds_read_b128 v[204:207], v158 offset:36864
	ds_read_b128 v[208:211], v158 offset:37888
	ds_read_b128 v[212:215], v158 offset:38912
	ds_read_b128 v[216:219], v158 offset:39936
	global_load_lds_dwordx4 v[230:231], off
	v_lshl_add_u64 v[230:231], s[24:25], 0, v[134:135]
	s_mov_b32 m0, s35
	s_nop 0
	global_load_lds_dwordx4 v[230:231], off
	s_waitcnt vmcnt(8)
	s_waitcnt lgkmcnt(0)
	s_setprio 1
	s_barrier
	v_mfma_f32_16x16x32_bf16 v[126:129], v[150:153], v[188:191], v[126:129]
	v_mfma_f32_16x16x32_bf16 v[122:125], v[164:167], v[188:191], v[122:125]
	v_mfma_f32_16x16x32_bf16 v[118:121], v[150:153], v[196:199], v[118:121]
	v_mfma_f32_16x16x32_bf16 v[110:113], v[164:167], v[196:199], v[110:113]
	v_mfma_f32_16x16x32_bf16 v[102:105], v[150:153], v[204:207], v[102:105]
	v_mfma_f32_16x16x32_bf16 v[94:97], v[164:167], v[204:207], v[94:97]
	v_mfma_f32_16x16x32_bf16 v[86:89], v[150:153], v[212:215], v[86:89]
	v_mfma_f32_16x16x32_bf16 v[78:81], v[164:167], v[212:215], v[78:81]
	v_mfma_f32_16x16x32_bf16 v[126:129], v[160:163], v[192:195], v[126:129]
	v_mfma_f32_16x16x32_bf16 v[122:125], v[168:171], v[192:195], v[122:125]
	v_mfma_f32_16x16x32_bf16 v[118:121], v[160:163], v[200:203], v[118:121]
	v_mfma_f32_16x16x32_bf16 v[110:113], v[168:171], v[200:203], v[110:113]
	v_mfma_f32_16x16x32_bf16 v[102:105], v[160:163], v[208:211], v[102:105]
	v_mfma_f32_16x16x32_bf16 v[94:97], v[168:171], v[208:211], v[94:97]
	v_mfma_f32_16x16x32_bf16 v[86:89], v[160:163], v[216:219], v[86:89]
	v_mfma_f32_16x16x32_bf16 v[78:81], v[168:171], v[216:219], v[78:81]
	v_mfma_f32_16x16x32_bf16 v[114:117], v[172:175], v[188:191], v[114:117]
	v_mfma_f32_16x16x32_bf16 v[106:109], v[180:183], v[188:191], v[106:109]
	v_mfma_f32_16x16x32_bf16 v[98:101], v[172:175], v[196:199], v[98:101]
	v_mfma_f32_16x16x32_bf16 v[90:93], v[180:183], v[196:199], v[90:93]
	v_mfma_f32_16x16x32_bf16 v[82:85], v[172:175], v[204:207], v[82:85]
	v_mfma_f32_16x16x32_bf16 v[74:77], v[180:183], v[204:207], v[74:77]
	v_mfma_f32_16x16x32_bf16 v[70:73], v[172:175], v[212:215], v[70:73]
	v_mfma_f32_16x16x32_bf16 v[66:69], v[180:183], v[212:215], v[66:69]
	v_mfma_f32_16x16x32_bf16 v[114:117], v[176:179], v[192:195], v[114:117]
	v_mfma_f32_16x16x32_bf16 v[106:109], v[184:187], v[192:195], v[106:109]
	v_mfma_f32_16x16x32_bf16 v[98:101], v[176:179], v[200:203], v[98:101]
	v_mfma_f32_16x16x32_bf16 v[90:93], v[184:187], v[200:203], v[90:93]
	v_mfma_f32_16x16x32_bf16 v[82:85], v[176:179], v[208:211], v[82:85]
	v_mfma_f32_16x16x32_bf16 v[74:77], v[184:187], v[208:211], v[74:77]
	v_mfma_f32_16x16x32_bf16 v[70:73], v[176:179], v[216:219], v[70:73]
	v_mfma_f32_16x16x32_bf16 v[66:69], v[184:187], v[216:219], v[66:69]
	s_barrier
; #define PG8_STAGE(bufoff, gbase, voff) do { _Pragma("unroll") for (int _i = 0; _i < 2; ++_i) \
;         __builtin_amdgcn_global_load_lds((const unsigned*)((const char*)(gbase) + (voff)[_i]), (PG8_LAS unsigned*)(lds + (bufoff) + ldsw + _i * 8192), 16, 0, 0); } while (0)
; #define PG8_WAIT_V(n) asm volatile("s_waitcnt vmcnt(" #n ")" ::: "memory")
; #define PG8_WAIT_L(n) asm volatile("s_waitcnt lgkmcnt(" #n ")" ::: "memory")
; #define PG8_BAR __builtin_amdgcn_s_barrier()
; #define PG8_SCHED __builtin_amdgcn_sched_barrier(0)
; template <class Epi, class Sched, bool ALIGN_EPI = true, bool SP2 = true>
; __device__ __forceinline__ void gemm_phase(PG8_LAS unsigned char* lds, const int K  , const Sched& S, const Epi& E) {
;     ...
;             PG8_LDA(At, 1, 1); PG8_STAGE(PG8_SB(1, 0), b3, voffB); PG8_STAGE(PG8_SB(1, 1), b3 + hstep, voffB); PG8_STAGE(PG8_SA(1, 0), a3, voffA);
;             PG8_WAIT_V(8); PG8_WAIT_L(0); PG8_BAR; PG8_MMA(1, 0, At, B0); PG8_MMA(1, 1, At, B1); PG8_BAR; PG8_SCHED;
;     ...
;         }
;         if constexpr (Epi::FP8) asm volatile("s_nop 15\n\ts_nop 15\n\ts_nop 15\n\ts_nop 15\n\ts_nop 15" ::: "memory");
;         if constexpr (ALIGN_EPI) { if (wr == 0) PG8_BAR; }
	s_setprio 0
	s_add_i32 s24, s48, s29
	v_lshl_add_u64 v[220:221], v[220:221], 0, s[6:7]
	s_mov_b32 m0, s24
	ds_read_b128 v[188:191], v158 offset:49152
	ds_read_b128 v[192:195], v158 offset:50176
	ds_read_b128 v[196:199], v158 offset:51200
	ds_read_b128 v[200:203], v158 offset:52224
	ds_read_b128 v[204:207], v158 offset:53248
	ds_read_b128 v[208:211], v158 offset:54272
	ds_read_b128 v[212:215], v158 offset:55296
	ds_read_b128 v[216:219], v158 offset:56320
	global_load_lds_dwordx4 v[220:221], off
	s_add_i32 m0, s24, 0x2000
	s_add_u32 s22, s22, 0x80080
	v_lshl_add_u64 v[220:221], v[222:223], 0, s[6:7]
	s_addc_u32 s23, s23, 0
	s_add_i32 s24, s49, s29
	global_load_lds_dwordx4 v[220:221], off
	v_lshl_add_u64 v[220:221], s[22:23], 0, v[136:137]
	s_mov_b32 m0, s24
	s_nop 0
	global_load_lds_dwordx4 v[220:221], off
	v_lshl_add_u64 v[220:221], s[22:23], 0, v[132:133]
	s_add_i32 m0, s24, 0x2000
	s_nop 0
	global_load_lds_dwordx4 v[220:221], off
	v_lshl_add_u64 v[220:221], v[224:225], 0, s[6:7]
	s_mov_b32 m0, s37
	s_nop 0
	global_load_lds_dwordx4 v[220:221], off
	v_lshl_add_u64 v[220:221], v[226:227], 0, s[6:7]
	s_mov_b32 m0, s38
	s_nop 0
	global_load_lds_dwordx4 v[220:221], off
	s_waitcnt vmcnt(8)
	s_waitcnt lgkmcnt(0)
	s_setprio 1
	s_barrier
	v_mfma_f32_16x16x32_bf16 v[62:65], v[150:153], v[188:191], v[62:65]
	v_mfma_f32_16x16x32_bf16 v[58:61], v[164:167], v[188:191], v[58:61]
	v_mfma_f32_16x16x32_bf16 v[54:57], v[150:153], v[196:199], v[54:57]
	v_mfma_f32_16x16x32_bf16 v[46:49], v[164:167], v[196:199], v[46:49]
	v_mfma_f32_16x16x32_bf16 v[38:41], v[150:153], v[204:207], v[38:41]
	v_mfma_f32_16x16x32_bf16 v[30:33], v[164:167], v[204:207], v[30:33]
	v_mfma_f32_16x16x32_bf16 v[22:25], v[150:153], v[212:215], v[22:25]
	v_mfma_f32_16x16x32_bf16 v[14:17], v[164:167], v[212:215], v[14:17]
	v_mfma_f32_16x16x32_bf16 v[62:65], v[160:163], v[192:195], v[62:65]
	v_mfma_f32_16x16x32_bf16 v[58:61], v[168:171], v[192:195], v[58:61]
	v_mfma_f32_16x16x32_bf16 v[54:57], v[160:163], v[200:203], v[54:57]
	v_mfma_f32_16x16x32_bf16 v[46:49], v[168:171], v[200:203], v[46:49]
	v_mfma_f32_16x16x32_bf16 v[38:41], v[160:163], v[208:211], v[38:41]
	v_mfma_f32_16x16x32_bf16 v[30:33], v[168:171], v[208:211], v[30:33]
	v_mfma_f32_16x16x32_bf16 v[22:25], v[160:163], v[216:219], v[22:25]
	v_mfma_f32_16x16x32_bf16 v[14:17], v[168:171], v[216:219], v[14:17]
	v_mfma_f32_16x16x32_bf16 v[50:53], v[172:175], v[188:191], v[50:53]
	v_mfma_f32_16x16x32_bf16 v[42:45], v[180:183], v[188:191], v[42:45]
	v_mfma_f32_16x16x32_bf16 v[34:37], v[172:175], v[196:199], v[34:37]
	v_mfma_f32_16x16x32_bf16 v[26:29], v[180:183], v[196:199], v[26:29]
	v_mfma_f32_16x16x32_bf16 v[18:21], v[172:175], v[204:207], v[18:21]
	v_mfma_f32_16x16x32_bf16 v[10:13], v[180:183], v[204:207], v[10:13]
	v_mfma_f32_16x16x32_bf16 v[6:9], v[172:175], v[212:215], v[6:9]
	v_mfma_f32_16x16x32_bf16 v[2:5], v[180:183], v[212:215], v[2:5]
	v_mfma_f32_16x16x32_bf16 v[50:53], v[176:179], v[192:195], v[50:53]
	v_mfma_f32_16x16x32_bf16 v[42:45], v[184:187], v[192:195], v[42:45]
	v_mfma_f32_16x16x32_bf16 v[34:37], v[176:179], v[200:203], v[34:37]
	v_mfma_f32_16x16x32_bf16 v[26:29], v[184:187], v[200:203], v[26:29]
	v_mfma_f32_16x16x32_bf16 v[18:21], v[176:179], v[208:211], v[18:21]
	v_mfma_f32_16x16x32_bf16 v[10:13], v[184:187], v[208:211], v[10:13]
	v_mfma_f32_16x16x32_bf16 v[6:9], v[176:179], v[216:219], v[6:9]
	v_mfma_f32_16x16x32_bf16 v[2:5], v[184:187], v[216:219], v[2:5]
	s_barrier
	s_setprio 0
	s_add_i32 s47, s47, 2
	s_add_u32 s20, s20, 0x100
	s_addc_u32 s21, s21, 0
	s_add_u32 s45, s45, 0x100
	s_addc_u32 s46, s46, 0
	s_cmp_gt_u32 s47, 29
	s_cbranch_scc0 .LBB0_537
	s_and_b64 vcc, exec, s[8:9]
	s_cbranch_vccz .LBB0_540
	s_barrier

; #define PG8_STAGE(bufoff, gbase, voff) do { _Pragma("unroll") for (int _i = 0; _i < 2; ++_i) \
;         __builtin_amdgcn_global_load_lds((const unsigned*)((const char*)(gbase) + (voff)[_i]), (PG8_LAS unsigned*)(lds + (bufoff) + ldsw + _i * 8192), 16, 0, 0); } while (0)
; #define PG8_WAIT_V(n) asm volatile("s_waitcnt vmcnt(" #n ")" ::: "memory")
; #define PG8_WAIT_L(n) asm volatile("s_waitcnt lgkmcnt(" #n ")" ::: "memory")
; #define PG8_BAR __builtin_amdgcn_s_barrier()
; #define PG8_SCHED __builtin_amdgcn_sched_barrier(0)
;     __device__ __forceinline__ int nt(const pg8::Unit& u) const { return u.kind == 0 ? ntiles : q_nt(u.kind - 1); }
; template <class Epi, class Sched, bool ALIGN_EPI = true, bool SP2 = true>
; __device__ __forceinline__ void gemm_phase(PG8_LAS unsigned char* lds, const int K  , const Sched& S, const Epi& E) {
;     ...
;             const bool last = (t == nt - 2);
;             const char* a1 = cA + (size_t)(t + 1) * kstep;
;             const char* a2 = last ? nA : cA + (size_t)(t + 2) * kstep; const char* b2 = last ? nB : cB + (size_t)(t + 2) * kstep;
;             const char* a3 = a2 + kstep; const char* b3 = b2 + kstep;
;             if constexpr (SP2) {
;             PG8_LDB(B0, 0, 0); PG8_LDB(B1, 0, 1); PG8_SCHED; PG8_LDA(At, 0, 0); PG8_STAGE(PG8_SA(1, 1), a1 + hstep, voffA);
;             PG8_WAIT_V(8); PG8_WAIT_L(0); PG8_BAR; PG8_MMA(0, 0, At, B0); PG8_MMA(0, 1, At, B1); PG8_BAR; PG8_SCHED;
;             PG8_LDA(At, 0, 1); PG8_STAGE(PG8_SB(0, 0), b2, voffB); PG8_STAGE(PG8_SB(0, 1), b2 + hstep, voffB); PG8_STAGE(PG8_SA(0, 0), a2, voffA);
.LBB0_955:
	s_waitcnt vmcnt(0)
	ds_read_b128 v[130:133], v232
	ds_read_b128 v[134:137], v232 offset:1024
	ds_read_b128 v[138:141], v232 offset:2048
	ds_read_b128 v[142:145], v232 offset:3072
	ds_read_b128 v[146:149], v233
	ds_read_b128 v[150:153], v233 offset:1024
	ds_read_b128 v[154:157], v233 offset:2048
	ds_read_b128 v[158:161], v233 offset:3072
	s_add_i32 s73, s28, 2
	s_add_u32 s26, s24, 0xfff80080
	s_addc_u32 s27, s25, -1
	s_cmp_eq_u32 s13, s28
	s_cselect_b32 s28, s16, s26
	s_cselect_b32 s29, s17, s27
	s_cselect_b32 s27, s19, s21
	s_cselect_b32 s26, s18, s15
	v_lshl_add_u64 v[194:195], s[24:25], 0, v[214:215]
	s_add_i32 m0, s23, 0xc000
	ds_read_b128 v[162:165], v234
	ds_read_b128 v[166:169], v234 offset:1024
	ds_read_b128 v[170:173], v234 offset:2048
	ds_read_b128 v[174:177], v234 offset:3072
	ds_read_b128 v[178:181], v234 offset:4096
	ds_read_b128 v[182:185], v234 offset:5120
	ds_read_b128 v[186:189], v234 offset:6144
	ds_read_b128 v[190:193], v234 offset:7168
	global_load_lds_dwordx4 v[194:195], off
	v_lshl_add_u64 v[194:195], s[24:25], 0, v[216:217]
	s_add_i32 m0, s23, 0xe000
	s_nop 0
	global_load_lds_dwordx4 v[194:195], off
	s_waitcnt vmcnt(8)
	s_waitcnt lgkmcnt(0)
	s_setprio 1
	s_barrier
	v_mfma_f32_16x16x32_bf16 v[126:129], v[130:133], v[162:165], v[126:129]
	v_mfma_f32_16x16x32_bf16 v[122:125], v[138:141], v[162:165], v[122:125]
	v_mfma_f32_16x16x32_bf16 v[118:121], v[130:133], v[170:173], v[118:121]
	v_mfma_f32_16x16x32_bf16 v[110:113], v[138:141], v[170:173], v[110:113]
	v_mfma_f32_16x16x32_bf16 v[102:105], v[130:133], v[178:181], v[102:105]
	v_mfma_f32_16x16x32_bf16 v[94:97], v[138:141], v[178:181], v[94:97]
	v_mfma_f32_16x16x32_bf16 v[86:89], v[130:133], v[186:189], v[86:89]
	v_mfma_f32_16x16x32_bf16 v[78:81], v[138:141], v[186:189], v[78:81]
	v_mfma_f32_16x16x32_bf16 v[126:129], v[134:137], v[166:169], v[126:129]
	v_mfma_f32_16x16x32_bf16 v[122:125], v[142:145], v[166:169], v[122:125]
	v_mfma_f32_16x16x32_bf16 v[118:121], v[134:137], v[174:177], v[118:121]
	v_mfma_f32_16x16x32_bf16 v[110:113], v[142:145], v[174:177], v[110:113]
	v_mfma_f32_16x16x32_bf16 v[102:105], v[134:137], v[182:185], v[102:105]
	v_mfma_f32_16x16x32_bf16 v[94:97], v[142:145], v[182:185], v[94:97]
	v_mfma_f32_16x16x32_bf16 v[86:89], v[134:137], v[190:193], v[86:89]
	v_mfma_f32_16x16x32_bf16 v[78:81], v[142:145], v[190:193], v[78:81]
	v_mfma_f32_16x16x32_bf16 v[114:117], v[146:149], v[162:165], v[114:117]
	v_mfma_f32_16x16x32_bf16 v[106:109], v[154:157], v[162:165], v[106:109]
	v_mfma_f32_16x16x32_bf16 v[98:101], v[146:149], v[170:173], v[98:101]
	v_mfma_f32_16x16x32_bf16 v[90:93], v[154:157], v[170:173], v[90:93]
	v_mfma_f32_16x16x32_bf16 v[82:85], v[146:149], v[178:181], v[82:85]
	v_mfma_f32_16x16x32_bf16 v[74:77], v[154:157], v[178:181], v[74:77]
	v_mfma_f32_16x16x32_bf16 v[70:73], v[146:149], v[186:189], v[70:73]
	v_mfma_f32_16x16x32_bf16 v[66:69], v[154:157], v[186:189], v[66:69]
	v_mfma_f32_16x16x32_bf16 v[114:117], v[150:153], v[166:169], v[114:117]
	v_mfma_f32_16x16x32_bf16 v[106:109], v[158:161], v[166:169], v[106:109]
	v_mfma_f32_16x16x32_bf16 v[98:101], v[150:153], v[174:177], v[98:101]
	v_mfma_f32_16x16x32_bf16 v[90:93], v[158:161], v[174:177], v[90:93]
	v_mfma_f32_16x16x32_bf16 v[82:85], v[150:153], v[182:185], v[82:85]
	v_mfma_f32_16x16x32_bf16 v[74:77], v[158:161], v[182:185], v[74:77]
	v_mfma_f32_16x16x32_bf16 v[70:73], v[150:153], v[190:193], v[70:73]
	v_mfma_f32_16x16x32_bf16 v[66:69], v[158:161], v[190:193], v[66:69]
	s_barrier
	s_setprio 0
	s_add_i32 s74, s47, s33
	v_lshl_add_u64 v[194:195], s[26:27], 0, v[208:209]
	s_mov_b32 m0, s74
	ds_read_b128 v[162:165], v234 offset:16384
	ds_read_b128 v[166:169], v234 offset:17408
	ds_read_b128 v[170:173], v234 offset:18432
	ds_read_b128 v[174:177], v234 offset:19456
	ds_read_b128 v[178:181], v234 offset:20480
	ds_read_b128 v[182:185], v234 offset:21504
	ds_read_b128 v[186:189], v234 offset:22528
	ds_read_b128 v[190:193], v234 offset:23552
	global_load_lds_dwordx4 v[194:195], off
	s_add_i32 m0, s74, 0x2000
	s_add_u32 s74, s26, 0x80000
	v_lshl_add_u64 v[196:197], s[26:27], 0, v[212:213]
	s_addc_u32 s75, s27, 0
	s_add_i32 s76, s48, s33
	global_load_lds_dwordx4 v[196:197], off
	v_lshl_add_u64 v[198:199], s[74:75], 0, v[208:209]
	s_mov_b32 m0, s76
	v_lshl_add_u64 v[200:201], s[28:29], 0, v[210:211]
	global_load_lds_dwordx4 v[198:199], off
	v_lshl_add_u64 v[198:199], s[74:75], 0, v[212:213]
	s_add_i32 m0, s76, 0x2000
	s_nop 0
	global_load_lds_dwordx4 v[198:199], off
	v_lshl_add_u64 v[198:199], s[28:29], 0, v[206:207]
	s_mov_b32 m0, s23
	s_nop 0
	global_load_lds_dwordx4 v[198:199], off
	s_mov_b32 m0, s34
	s_nop 0
	global_load_lds_dwordx4 v[200:201], off
	s_waitcnt vmcnt(8)
	s_waitcnt lgkmcnt(0)
	s_setprio 1
	s_barrier
; #define PG8_STAGE(bufoff, gbase, voff) do { _Pragma("unroll") for (int _i = 0; _i < 2; ++_i) \
;         __builtin_amdgcn_global_load_lds((const unsigned*)((const char*)(gbase) + (voff)[_i]), (PG8_LAS unsigned*)(lds + (bufoff) + ldsw + _i * 8192), 16, 0, 0); } while (0)
; #define PG8_WAIT_V(n) asm volatile("s_waitcnt vmcnt(" #n ")" ::: "memory")
; #define PG8_WAIT_L(n) asm volatile("s_waitcnt lgkmcnt(" #n ")" ::: "memory")
; #define PG8_BAR __builtin_amdgcn_s_barrier()
; #define PG8_SCHED __builtin_amdgcn_sched_barrier(0)
; template <class Epi, class Sched, bool ALIGN_EPI = true, bool SP2 = true>
; __device__ __forceinline__ void gemm_phase(PG8_LAS unsigned char* lds, const int K  , const Sched& S, const Epi& E) {
;     ...
;             PG8_WAIT_V(8); PG8_WAIT_L(0); PG8_BAR; PG8_MMA(1, 0, At, B0); PG8_MMA(1, 1, At, B1); PG8_BAR; PG8_SCHED;
;             PG8_LDB(B0, 1, 0); PG8_LDB(B1, 1, 1); PG8_SCHED; PG8_LDA(At, 1, 0); PG8_STAGE(PG8_SA(0, 1), a2 + hstep, voffA);
;             PG8_WAIT_V(8); PG8_WAIT_L(0); PG8_BAR; PG8_MMA(0, 0, At, B0); PG8_MMA(0, 1, At, B1); PG8_BAR; PG8_SCHED;
	v_mfma_f32_16x16x32_bf16 v[62:65], v[130:133], v[162:165], v[62:65]
	v_mfma_f32_16x16x32_bf16 v[58:61], v[138:141], v[162:165], v[58:61]
	v_mfma_f32_16x16x32_bf16 v[54:57], v[130:133], v[170:173], v[54:57]
	v_mfma_f32_16x16x32_bf16 v[46:49], v[138:141], v[170:173], v[46:49]
	v_mfma_f32_16x16x32_bf16 v[38:41], v[130:133], v[178:181], v[38:41]
	v_mfma_f32_16x16x32_bf16 v[30:33], v[138:141], v[178:181], v[30:33]
	v_mfma_f32_16x16x32_bf16 v[22:25], v[130:133], v[186:189], v[22:25]
	v_mfma_f32_16x16x32_bf16 v[14:17], v[138:141], v[186:189], v[14:17]
	v_mfma_f32_16x16x32_bf16 v[62:65], v[134:137], v[166:169], v[62:65]
	v_mfma_f32_16x16x32_bf16 v[58:61], v[142:145], v[166:169], v[58:61]
	v_mfma_f32_16x16x32_bf16 v[54:57], v[134:137], v[174:177], v[54:57]
	v_mfma_f32_16x16x32_bf16 v[46:49], v[142:145], v[174:177], v[46:49]
	v_mfma_f32_16x16x32_bf16 v[38:41], v[134:137], v[182:185], v[38:41]
	v_mfma_f32_16x16x32_bf16 v[30:33], v[142:145], v[182:185], v[30:33]
	v_mfma_f32_16x16x32_bf16 v[22:25], v[134:137], v[190:193], v[22:25]
	v_mfma_f32_16x16x32_bf16 v[14:17], v[142:145], v[190:193], v[14:17]
	v_mfma_f32_16x16x32_bf16 v[50:53], v[146:149], v[162:165], v[50:53]
	v_mfma_f32_16x16x32_bf16 v[42:45], v[154:157], v[162:165], v[42:45]
	v_mfma_f32_16x16x32_bf16 v[34:37], v[146:149], v[170:173], v[34:37]
	v_mfma_f32_16x16x32_bf16 v[26:29], v[154:157], v[170:173], v[26:29]
	v_mfma_f32_16x16x32_bf16 v[18:21], v[146:149], v[178:181], v[18:21]
	v_mfma_f32_16x16x32_bf16 v[10:13], v[154:157], v[178:181], v[10:13]
	v_mfma_f32_16x16x32_bf16 v[6:9], v[146:149], v[186:189], v[6:9]
	v_mfma_f32_16x16x32_bf16 v[2:5], v[154:157], v[186:189], v[2:5]
	v_mfma_f32_16x16x32_bf16 v[50:53], v[150:153], v[166:169], v[50:53]
	v_mfma_f32_16x16x32_bf16 v[42:45], v[158:161], v[166:169], v[42:45]
	v_mfma_f32_16x16x32_bf16 v[34:37], v[150:153], v[174:177], v[34:37]
	v_mfma_f32_16x16x32_bf16 v[26:29], v[158:161], v[174:177], v[26:29]
	v_mfma_f32_16x16x32_bf16 v[18:21], v[150:153], v[182:185], v[18:21]
	v_mfma_f32_16x16x32_bf16 v[10:13], v[158:161], v[182:185], v[10:13]
	v_mfma_f32_16x16x32_bf16 v[6:9], v[150:153], v[190:193], v[6:9]
	v_mfma_f32_16x16x32_bf16 v[2:5], v[158:161], v[190:193], v[2:5]
	s_barrier
	s_setprio 0
	s_add_i32 s74, 0, 0x18000
	s_add_i32 s75, 0, 0x1c000
	v_add_u32_e32 v142, s74, v230
	v_add_u32_e32 v158, s75, v230
	ds_read_b128 v[130:133], v142
	ds_read_b128 v[134:137], v142 offset:1024
	ds_read_b128 v[138:141], v142 offset:2048
	ds_read_b128 v[142:145], v142 offset:3072
	ds_read_b128 v[146:149], v158
	ds_read_b128 v[150:153], v158 offset:1024
	ds_read_b128 v[154:157], v158 offset:2048
	ds_read_b128 v[158:161], v158 offset:3072
	s_add_u32 s28, s28, 0x80000
	s_addc_u32 s29, s29, 0
	s_mov_b32 m0, s35
	v_lshl_add_u64 v[202:203], s[28:29], 0, v[206:207]
	ds_read_b128 v[162:165], v234 offset:32768
	ds_read_b128 v[166:169], v234 offset:33792
	ds_read_b128 v[170:173], v234 offset:34816
	ds_read_b128 v[174:177], v234 offset:35840
	ds_read_b128 v[178:181], v234 offset:36864
	ds_read_b128 v[182:185], v234 offset:37888
	ds_read_b128 v[186:189], v234 offset:38912
	ds_read_b128 v[190:193], v234 offset:39936
	global_load_lds_dwordx4 v[202:203], off
	v_lshl_add_u64 v[202:203], s[28:29], 0, v[210:211]
	s_mov_b32 m0, s36
	s_nop 0
	global_load_lds_dwordx4 v[202:203], off
	s_waitcnt vmcnt(8)
	s_waitcnt lgkmcnt(0)
	s_setprio 1
	s_barrier
	v_mfma_f32_16x16x32_bf16 v[126:129], v[130:133], v[162:165], v[126:129]
	v_mfma_f32_16x16x32_bf16 v[122:125], v[138:141], v[162:165], v[122:125]
	v_mfma_f32_16x16x32_bf16 v[118:121], v[130:133], v[170:173], v[118:121]
	v_mfma_f32_16x16x32_bf16 v[110:113], v[138:141], v[170:173], v[110:113]
	v_mfma_f32_16x16x32_bf16 v[102:105], v[130:133], v[178:181], v[102:105]
	v_mfma_f32_16x16x32_bf16 v[94:97], v[138:141], v[178:181], v[94:97]
	v_mfma_f32_16x16x32_bf16 v[86:89], v[130:133], v[186:189], v[86:89]
	v_mfma_f32_16x16x32_bf16 v[78:81], v[138:141], v[186:189], v[78:81]
	v_mfma_f32_16x16x32_bf16 v[126:129], v[134:137], v[166:169], v[126:129]
	v_mfma_f32_16x16x32_bf16 v[122:125], v[142:145], v[166:169], v[122:125]
	v_mfma_f32_16x16x32_bf16 v[118:121], v[134:137], v[174:177], v[118:121]
	v_mfma_f32_16x16x32_bf16 v[110:113], v[142:145], v[174:177], v[110:113]
	v_mfma_f32_16x16x32_bf16 v[102:105], v[134:137], v[182:185], v[102:105]
	v_mfma_f32_16x16x32_bf16 v[94:97], v[142:145], v[182:185], v[94:97]
	v_mfma_f32_16x16x32_bf16 v[86:89], v[134:137], v[190:193], v[86:89]
	v_mfma_f32_16x16x32_bf16 v[78:81], v[142:145], v[190:193], v[78:81]
	v_mfma_f32_16x16x32_bf16 v[114:117], v[146:149], v[162:165], v[114:117]
	v_mfma_f32_16x16x32_bf16 v[106:109], v[154:157], v[162:165], v[106:109]
	v_mfma_f32_16x16x32_bf16 v[98:101], v[146:149], v[170:173], v[98:101]
	v_mfma_f32_16x16x32_bf16 v[90:93], v[154:157], v[170:173], v[90:93]
	v_mfma_f32_16x16x32_bf16 v[82:85], v[146:149], v[178:181], v[82:85]
	v_mfma_f32_16x16x32_bf16 v[74:77], v[154:157], v[178:181], v[74:77]
	v_mfma_f32_16x16x32_bf16 v[70:73], v[146:149], v[186:189], v[70:73]
	v_mfma_f32_16x16x32_bf16 v[66:69], v[154:157], v[186:189], v[66:69]
	v_mfma_f32_16x16x32_bf16 v[114:117], v[150:153], v[166:169], v[114:117]
	v_mfma_f32_16x16x32_bf16 v[106:109], v[158:161], v[166:169], v[106:109]
	v_mfma_f32_16x16x32_bf16 v[98:101], v[150:153], v[174:177], v[98:101]
	v_mfma_f32_16x16x32_bf16 v[90:93], v[158:161], v[174:177], v[90:93]
	v_mfma_f32_16x16x32_bf16 v[82:85], v[150:153], v[182:185], v[82:85]
	v_mfma_f32_16x16x32_bf16 v[74:77], v[158:161], v[182:185], v[74:77]
	v_mfma_f32_16x16x32_bf16 v[70:73], v[150:153], v[190:193], v[70:73]
	v_mfma_f32_16x16x32_bf16 v[66:69], v[158:161], v[190:193], v[66:69]
	s_barrier
; #define PG8_STAGE(bufoff, gbase, voff) do { _Pragma("unroll") for (int _i = 0; _i < 2; ++_i) \
;         __builtin_amdgcn_global_load_lds((const unsigned*)((const char*)(gbase) + (voff)[_i]), (PG8_LAS unsigned*)(lds + (bufoff) + ldsw + _i * 8192), 16, 0, 0); } while (0)
; #define PG8_WAIT_V(n) asm volatile("s_waitcnt vmcnt(" #n ")" ::: "memory")
; #define PG8_WAIT_L(n) asm volatile("s_waitcnt lgkmcnt(" #n ")" ::: "memory")
; #define PG8_BAR __builtin_amdgcn_s_barrier()
; #define PG8_SCHED __builtin_amdgcn_sched_barrier(0)
; template <class Epi, class Sched, bool ALIGN_EPI = true, bool SP2 = true>
; __device__ __forceinline__ void gemm_phase(PG8_LAS unsigned char* lds, const int K  , const Sched& S, const Epi& E) {
;     ...
;             PG8_LDA(At, 1, 1); PG8_STAGE(PG8_SB(1, 0), b3, voffB); PG8_STAGE(PG8_SB(1, 1), b3 + hstep, voffB); PG8_STAGE(PG8_SA(1, 0), a3, voffA);
;             PG8_WAIT_V(8); PG8_WAIT_L(0); PG8_BAR; PG8_MMA(1, 0, At, B0); PG8_MMA(1, 1, At, B1); PG8_BAR; PG8_SCHED;
;     ...
;         }
;         if constexpr (Epi::FP8) asm volatile("s_nop 15\n\ts_nop 15\n\ts_nop 15\n\ts_nop 15\n\ts_nop 15" ::: "memory");
;         if constexpr (ALIGN_EPI) { if (wr == 0) PG8_BAR; }
	s_setprio 0
	s_add_i32 s28, s74, s33
	v_lshl_add_u64 v[194:195], v[194:195], 0, s[8:9]
	s_mov_b32 m0, s28
	ds_read_b128 v[162:165], v234 offset:49152
	ds_read_b128 v[166:169], v234 offset:50176
	ds_read_b128 v[170:173], v234 offset:51200
	ds_read_b128 v[174:177], v234 offset:52224
	ds_read_b128 v[178:181], v234 offset:53248
	ds_read_b128 v[182:185], v234 offset:54272
	ds_read_b128 v[186:189], v234 offset:55296
	ds_read_b128 v[190:193], v234 offset:56320
	global_load_lds_dwordx4 v[194:195], off
	s_add_i32 m0, s28, 0x2000
	s_add_u32 s26, s26, 0x80080
	v_lshl_add_u64 v[194:195], v[196:197], 0, s[8:9]
	s_addc_u32 s27, s27, 0
	s_add_i32 s28, s75, s33
	global_load_lds_dwordx4 v[194:195], off
	v_lshl_add_u64 v[194:195], s[26:27], 0, v[208:209]
	s_mov_b32 m0, s28
	s_nop 0
	global_load_lds_dwordx4 v[194:195], off
	v_lshl_add_u64 v[194:195], s[26:27], 0, v[212:213]
	s_add_i32 m0, s28, 0x2000
	s_nop 0
	global_load_lds_dwordx4 v[194:195], off
	v_lshl_add_u64 v[194:195], v[198:199], 0, s[8:9]
	s_mov_b32 m0, s42
	s_nop 0
	global_load_lds_dwordx4 v[194:195], off
	v_lshl_add_u64 v[194:195], v[200:201], 0, s[8:9]
	s_mov_b32 m0, s43
	s_nop 0
	global_load_lds_dwordx4 v[194:195], off
	s_waitcnt vmcnt(8)
	s_waitcnt lgkmcnt(0)
	s_setprio 1
	s_barrier
	v_mfma_f32_16x16x32_bf16 v[62:65], v[130:133], v[162:165], v[62:65]
	v_mfma_f32_16x16x32_bf16 v[58:61], v[138:141], v[162:165], v[58:61]
	v_mfma_f32_16x16x32_bf16 v[54:57], v[130:133], v[170:173], v[54:57]
	v_mfma_f32_16x16x32_bf16 v[46:49], v[138:141], v[170:173], v[46:49]
	v_mfma_f32_16x16x32_bf16 v[38:41], v[130:133], v[178:181], v[38:41]
	v_mfma_f32_16x16x32_bf16 v[30:33], v[138:141], v[178:181], v[30:33]
	v_mfma_f32_16x16x32_bf16 v[22:25], v[130:133], v[186:189], v[22:25]
	v_mfma_f32_16x16x32_bf16 v[14:17], v[138:141], v[186:189], v[14:17]
	v_mfma_f32_16x16x32_bf16 v[62:65], v[134:137], v[166:169], v[62:65]
	v_mfma_f32_16x16x32_bf16 v[58:61], v[142:145], v[166:169], v[58:61]
	v_mfma_f32_16x16x32_bf16 v[54:57], v[134:137], v[174:177], v[54:57]
	v_mfma_f32_16x16x32_bf16 v[46:49], v[142:145], v[174:177], v[46:49]
	v_mfma_f32_16x16x32_bf16 v[38:41], v[134:137], v[182:185], v[38:41]
	v_mfma_f32_16x16x32_bf16 v[30:33], v[142:145], v[182:185], v[30:33]
	v_mfma_f32_16x16x32_bf16 v[22:25], v[134:137], v[190:193], v[22:25]
	v_mfma_f32_16x16x32_bf16 v[14:17], v[142:145], v[190:193], v[14:17]
	v_mfma_f32_16x16x32_bf16 v[50:53], v[146:149], v[162:165], v[50:53]
	v_mfma_f32_16x16x32_bf16 v[42:45], v[154:157], v[162:165], v[42:45]
	v_mfma_f32_16x16x32_bf16 v[34:37], v[146:149], v[170:173], v[34:37]
	v_mfma_f32_16x16x32_bf16 v[26:29], v[154:157], v[170:173], v[26:29]
	v_mfma_f32_16x16x32_bf16 v[18:21], v[146:149], v[178:181], v[18:21]
	v_mfma_f32_16x16x32_bf16 v[10:13], v[154:157], v[178:181], v[10:13]
	v_mfma_f32_16x16x32_bf16 v[6:9], v[146:149], v[186:189], v[6:9]
	v_mfma_f32_16x16x32_bf16 v[2:5], v[154:157], v[186:189], v[2:5]
	v_mfma_f32_16x16x32_bf16 v[50:53], v[150:153], v[166:169], v[50:53]
	v_mfma_f32_16x16x32_bf16 v[42:45], v[158:161], v[166:169], v[42:45]
	v_mfma_f32_16x16x32_bf16 v[34:37], v[150:153], v[174:177], v[34:37]
	v_mfma_f32_16x16x32_bf16 v[26:29], v[158:161], v[174:177], v[26:29]
	v_mfma_f32_16x16x32_bf16 v[18:21], v[150:153], v[182:185], v[18:21]
	v_mfma_f32_16x16x32_bf16 v[10:13], v[158:161], v[182:185], v[10:13]
	v_mfma_f32_16x16x32_bf16 v[6:9], v[150:153], v[190:193], v[6:9]
	v_mfma_f32_16x16x32_bf16 v[2:5], v[158:161], v[190:193], v[2:5]
	s_barrier
	s_setprio 0
	s_add_u32 s24, s24, 0x100
	s_addc_u32 s25, s25, 0
	s_add_u32 s15, s15, 0x100
	s_addc_u32 s21, s21, 0
	s_cmp_ge_u32 s73, s4
	s_mov_b32 s28, s73
	s_cbranch_scc0 .LBB0_955
	s_and_b64 vcc, exec, s[10:11]
	s_cbranch_vccz .LBB0_958
	s_barrier

; #define PG8_STAGE(bufoff, gbase, voff) do { _Pragma("unroll") for (int _i = 0; _i < 2; ++_i) \
;         __builtin_amdgcn_global_load_lds((const unsigned*)((const char*)(gbase) + (voff)[_i]), (PG8_LAS unsigned*)(lds + (bufoff) + ldsw + _i * 8192), 16, 0, 0); } while (0)
; #define PG8_WAIT_V(n) asm volatile("s_waitcnt vmcnt(" #n ")" ::: "memory")
; #define PG8_WAIT_L(n) asm volatile("s_waitcnt lgkmcnt(" #n ")" ::: "memory")
; #define PG8_BAR __builtin_amdgcn_s_barrier()
; #define PG8_SCHED __builtin_amdgcn_sched_barrier(0)
;     __device__ __forceinline__ int nt(const pg8::Unit& u) const { return u.kind == 0 ? ntiles : q_nt(u.kind - 1); }
; template <class Epi, class Sched, bool ALIGN_EPI = true, bool SP2 = true>
; __device__ __forceinline__ void gemm_phase(PG8_LAS unsigned char* lds, const int K  , const Sched& S, const Epi& E) {
;     ...
;             const bool last = (t == nt - 2);
;             const char* a1 = cA + (size_t)(t + 1) * kstep;
;             const char* a2 = last ? nA : cA + (size_t)(t + 2) * kstep; const char* b2 = last ? nB : cB + (size_t)(t + 2) * kstep;
;             const char* a3 = a2 + kstep; const char* b3 = b2 + kstep;
;             if constexpr (SP2) {
;             PG8_LDB(B0, 0, 0); PG8_LDB(B1, 0, 1); PG8_SCHED; PG8_LDA(At, 0, 0); PG8_STAGE(PG8_SA(1, 1), a1 + hstep, voffA);
;             PG8_WAIT_V(8); PG8_WAIT_L(0); PG8_BAR; PG8_MMA(0, 0, At, B0); PG8_MMA(0, 1, At, B1); PG8_BAR; PG8_SCHED;
;             PG8_LDA(At, 0, 1); PG8_STAGE(PG8_SB(0, 0), b2, voffB); PG8_STAGE(PG8_SB(0, 1), b2 + hstep, voffB); PG8_STAGE(PG8_SA(0, 0), a2, voffA);
.LBB0_1099:
	ds_read_b128 v[148:151], v154
	ds_read_b128 v[160:163], v154 offset:1024
	ds_read_b128 v[164:167], v154 offset:2048
	ds_read_b128 v[168:171], v154 offset:3072
	ds_read_b128 v[172:175], v155
	ds_read_b128 v[176:179], v155 offset:1024
	ds_read_b128 v[180:183], v155 offset:2048
	ds_read_b128 v[184:187], v155 offset:3072
	s_add_u32 s24, s22, 0xfff80080
	s_addc_u32 s25, s23, -1
	s_cmp_eq_u32 s48, 28
	s_cselect_b32 s27, s15, s25
	s_cselect_b32 s26, s44, s24
	s_cselect_b32 s25, s11, s47
	s_cselect_b32 s24, s45, s46
	v_lshl_add_u64 v[220:221], s[22:23], 0, v[140:141]
	s_add_i32 m0, s21, 0xc000
	ds_read_b128 v[188:191], v156
	ds_read_b128 v[192:195], v156 offset:1024
	ds_read_b128 v[196:199], v156 offset:2048
	ds_read_b128 v[200:203], v156 offset:3072
	ds_read_b128 v[204:207], v156 offset:4096
	ds_read_b128 v[208:211], v156 offset:5120
	ds_read_b128 v[212:215], v156 offset:6144
	ds_read_b128 v[216:219], v156 offset:7168
	global_load_lds_dwordx4 v[220:221], off
	v_lshl_add_u64 v[220:221], s[22:23], 0, v[142:143]
	s_add_i32 m0, s21, 0xe000
	s_nop 0
	global_load_lds_dwordx4 v[220:221], off
	s_waitcnt vmcnt(8)
	s_waitcnt lgkmcnt(0)
	s_setprio 1
	s_barrier
	v_mfma_f32_16x16x32_bf16 v[126:129], v[148:151], v[188:191], v[126:129]
	v_mfma_f32_16x16x32_bf16 v[118:121], v[164:167], v[188:191], v[118:121]
	v_mfma_f32_16x16x32_bf16 v[110:113], v[148:151], v[196:199], v[110:113]
	v_mfma_f32_16x16x32_bf16 v[102:105], v[164:167], v[196:199], v[102:105]
	v_mfma_f32_16x16x32_bf16 v[94:97], v[148:151], v[204:207], v[94:97]
	v_mfma_f32_16x16x32_bf16 v[86:89], v[164:167], v[204:207], v[86:89]
	v_mfma_f32_16x16x32_bf16 v[78:81], v[148:151], v[212:215], v[78:81]
	v_mfma_f32_16x16x32_bf16 v[70:73], v[164:167], v[212:215], v[70:73]
	v_mfma_f32_16x16x32_bf16 v[126:129], v[160:163], v[192:195], v[126:129]
	v_mfma_f32_16x16x32_bf16 v[118:121], v[168:171], v[192:195], v[118:121]
	v_mfma_f32_16x16x32_bf16 v[110:113], v[160:163], v[200:203], v[110:113]
	v_mfma_f32_16x16x32_bf16 v[102:105], v[168:171], v[200:203], v[102:105]
	v_mfma_f32_16x16x32_bf16 v[94:97], v[160:163], v[208:211], v[94:97]
	v_mfma_f32_16x16x32_bf16 v[86:89], v[168:171], v[208:211], v[86:89]
	v_mfma_f32_16x16x32_bf16 v[78:81], v[160:163], v[216:219], v[78:81]
	v_mfma_f32_16x16x32_bf16 v[70:73], v[168:171], v[216:219], v[70:73]
	v_mfma_f32_16x16x32_bf16 v[122:125], v[172:175], v[188:191], v[122:125]
	v_mfma_f32_16x16x32_bf16 v[114:117], v[180:183], v[188:191], v[114:117]
	v_mfma_f32_16x16x32_bf16 v[106:109], v[172:175], v[196:199], v[106:109]
	v_mfma_f32_16x16x32_bf16 v[98:101], v[180:183], v[196:199], v[98:101]
	v_mfma_f32_16x16x32_bf16 v[90:93], v[172:175], v[204:207], v[90:93]
	v_mfma_f32_16x16x32_bf16 v[82:85], v[180:183], v[204:207], v[82:85]
	v_mfma_f32_16x16x32_bf16 v[74:77], v[172:175], v[212:215], v[74:77]
	v_mfma_f32_16x16x32_bf16 v[66:69], v[180:183], v[212:215], v[66:69]
	v_mfma_f32_16x16x32_bf16 v[122:125], v[176:179], v[192:195], v[122:125]
	v_mfma_f32_16x16x32_bf16 v[114:117], v[184:187], v[192:195], v[114:117]
	v_mfma_f32_16x16x32_bf16 v[106:109], v[176:179], v[200:203], v[106:109]
	v_mfma_f32_16x16x32_bf16 v[98:101], v[184:187], v[200:203], v[98:101]
	v_mfma_f32_16x16x32_bf16 v[90:93], v[176:179], v[208:211], v[90:93]
	v_mfma_f32_16x16x32_bf16 v[82:85], v[184:187], v[208:211], v[82:85]
	v_mfma_f32_16x16x32_bf16 v[74:77], v[176:179], v[216:219], v[74:77]
	v_mfma_f32_16x16x32_bf16 v[66:69], v[184:187], v[216:219], v[66:69]
	s_barrier
	s_setprio 0
	s_add_i32 s49, s39, s29
	v_lshl_add_u64 v[220:221], s[24:25], 0, v[136:137]
	s_mov_b32 m0, s49
	ds_read_b128 v[188:191], v156 offset:16384
	ds_read_b128 v[192:195], v156 offset:17408
	ds_read_b128 v[196:199], v156 offset:18432
	ds_read_b128 v[200:203], v156 offset:19456
	ds_read_b128 v[204:207], v156 offset:20480
	ds_read_b128 v[208:211], v156 offset:21504
	ds_read_b128 v[212:215], v156 offset:22528
	ds_read_b128 v[216:219], v156 offset:23552
	global_load_lds_dwordx4 v[220:221], off
	s_add_i32 m0, s49, 0x2000
	s_add_u32 s50, s24, 0x80000
	v_lshl_add_u64 v[222:223], s[24:25], 0, v[132:133]
	s_addc_u32 s51, s25, 0
	s_add_i32 s49, s40, s29
	global_load_lds_dwordx4 v[222:223], off
	v_lshl_add_u64 v[224:225], s[50:51], 0, v[136:137]
	s_mov_b32 m0, s49
	v_lshl_add_u64 v[226:227], s[26:27], 0, v[134:135]
	global_load_lds_dwordx4 v[224:225], off
	v_lshl_add_u64 v[224:225], s[50:51], 0, v[132:133]
	s_add_i32 m0, s49, 0x2000
	s_nop 0
	global_load_lds_dwordx4 v[224:225], off
	v_lshl_add_u64 v[224:225], s[26:27], 0, v[138:139]
	s_mov_b32 m0, s21
	s_nop 0
	global_load_lds_dwordx4 v[224:225], off
	s_mov_b32 m0, s31
	s_nop 0
	global_load_lds_dwordx4 v[226:227], off
	s_waitcnt vmcnt(8)
	s_waitcnt lgkmcnt(0)
	s_setprio 1
	s_barrier
; #define PG8_STAGE(bufoff, gbase, voff) do { _Pragma("unroll") for (int _i = 0; _i < 2; ++_i) \
;         __builtin_amdgcn_global_load_lds((const unsigned*)((const char*)(gbase) + (voff)[_i]), (PG8_LAS unsigned*)(lds + (bufoff) + ldsw + _i * 8192), 16, 0, 0); } while (0)
; #define PG8_WAIT_V(n) asm volatile("s_waitcnt vmcnt(" #n ")" ::: "memory")
; #define PG8_WAIT_L(n) asm volatile("s_waitcnt lgkmcnt(" #n ")" ::: "memory")
; #define PG8_BAR __builtin_amdgcn_s_barrier()
; #define PG8_SCHED __builtin_amdgcn_sched_barrier(0)
; template <class Epi, class Sched, bool ALIGN_EPI = true, bool SP2 = true>
; __device__ __forceinline__ void gemm_phase(PG8_LAS unsigned char* lds, const int K  , const Sched& S, const Epi& E) {
;     ...
;             PG8_WAIT_V(8); PG8_WAIT_L(0); PG8_BAR; PG8_MMA(1, 0, At, B0); PG8_MMA(1, 1, At, B1); PG8_BAR; PG8_SCHED;
;             PG8_LDB(B0, 1, 0); PG8_LDB(B1, 1, 1); PG8_SCHED; PG8_LDA(At, 1, 0); PG8_STAGE(PG8_SA(0, 1), a2 + hstep, voffA);
;             PG8_WAIT_V(8); PG8_WAIT_L(0); PG8_BAR; PG8_MMA(0, 0, At, B0); PG8_MMA(0, 1, At, B1); PG8_BAR; PG8_SCHED;
	v_mfma_f32_16x16x32_bf16 v[62:65], v[148:151], v[188:191], v[62:65]
	v_mfma_f32_16x16x32_bf16 v[54:57], v[164:167], v[188:191], v[54:57]
	v_mfma_f32_16x16x32_bf16 v[46:49], v[148:151], v[196:199], v[46:49]
	v_mfma_f32_16x16x32_bf16 v[38:41], v[164:167], v[196:199], v[38:41]
	v_mfma_f32_16x16x32_bf16 v[30:33], v[148:151], v[204:207], v[30:33]
	v_mfma_f32_16x16x32_bf16 v[22:25], v[164:167], v[204:207], v[22:25]
	v_mfma_f32_16x16x32_bf16 v[14:17], v[148:151], v[212:215], v[14:17]
	v_mfma_f32_16x16x32_bf16 v[6:9], v[164:167], v[212:215], v[6:9]
	v_mfma_f32_16x16x32_bf16 v[62:65], v[160:163], v[192:195], v[62:65]
	v_mfma_f32_16x16x32_bf16 v[54:57], v[168:171], v[192:195], v[54:57]
	v_mfma_f32_16x16x32_bf16 v[46:49], v[160:163], v[200:203], v[46:49]
	v_mfma_f32_16x16x32_bf16 v[38:41], v[168:171], v[200:203], v[38:41]
	v_mfma_f32_16x16x32_bf16 v[30:33], v[160:163], v[208:211], v[30:33]
	v_mfma_f32_16x16x32_bf16 v[22:25], v[168:171], v[208:211], v[22:25]
	v_mfma_f32_16x16x32_bf16 v[14:17], v[160:163], v[216:219], v[14:17]
	v_mfma_f32_16x16x32_bf16 v[6:9], v[168:171], v[216:219], v[6:9]
	v_mfma_f32_16x16x32_bf16 v[58:61], v[172:175], v[188:191], v[58:61]
	v_mfma_f32_16x16x32_bf16 v[50:53], v[180:183], v[188:191], v[50:53]
	v_mfma_f32_16x16x32_bf16 v[42:45], v[172:175], v[196:199], v[42:45]
	v_mfma_f32_16x16x32_bf16 v[34:37], v[180:183], v[196:199], v[34:37]
	v_mfma_f32_16x16x32_bf16 v[26:29], v[172:175], v[204:207], v[26:29]
	v_mfma_f32_16x16x32_bf16 v[18:21], v[180:183], v[204:207], v[18:21]
	v_mfma_f32_16x16x32_bf16 v[10:13], v[172:175], v[212:215], v[10:13]
	v_mfma_f32_16x16x32_bf16 v[2:5], v[180:183], v[212:215], v[2:5]
	v_mfma_f32_16x16x32_bf16 v[58:61], v[176:179], v[192:195], v[58:61]
	v_mfma_f32_16x16x32_bf16 v[50:53], v[184:187], v[192:195], v[50:53]
	v_mfma_f32_16x16x32_bf16 v[42:45], v[176:179], v[200:203], v[42:45]
	v_mfma_f32_16x16x32_bf16 v[34:37], v[184:187], v[200:203], v[34:37]
	v_mfma_f32_16x16x32_bf16 v[26:29], v[176:179], v[208:211], v[26:29]
	v_mfma_f32_16x16x32_bf16 v[18:21], v[184:187], v[208:211], v[18:21]
	v_mfma_f32_16x16x32_bf16 v[10:13], v[176:179], v[216:219], v[10:13]
	v_mfma_f32_16x16x32_bf16 v[2:5], v[184:187], v[216:219], v[2:5]
	s_barrier
	s_setprio 0
	s_add_i32 s49, 0, 0x18000
	v_add_u32_e32 v159, s49, v152
	s_add_i32 s50, 0, 0x1c000
	ds_read_b128 v[148:151], v159
	ds_read_b128 v[160:163], v159 offset:1024
	ds_read_b128 v[164:167], v159 offset:2048
	ds_read_b128 v[168:171], v159 offset:3072
	v_add_u32_e32 v159, s50, v152
	ds_read_b128 v[172:175], v159
	ds_read_b128 v[176:179], v159 offset:1024
	ds_read_b128 v[180:183], v159 offset:2048
	ds_read_b128 v[184:187], v159 offset:3072
	s_add_u32 s26, s26, 0x80000
	s_addc_u32 s27, s27, 0
	s_mov_b32 m0, s33
	v_lshl_add_u64 v[230:231], s[26:27], 0, v[138:139]
	ds_read_b128 v[188:191], v156 offset:32768
	ds_read_b128 v[192:195], v156 offset:33792
	ds_read_b128 v[196:199], v156 offset:34816
	ds_read_b128 v[200:203], v156 offset:35840
	ds_read_b128 v[204:207], v156 offset:36864
	ds_read_b128 v[208:211], v156 offset:37888
	ds_read_b128 v[212:215], v156 offset:38912
	ds_read_b128 v[216:219], v156 offset:39936
	global_load_lds_dwordx4 v[230:231], off
	v_lshl_add_u64 v[230:231], s[26:27], 0, v[134:135]
	s_mov_b32 m0, s34
	s_nop 0
	global_load_lds_dwordx4 v[230:231], off
	s_waitcnt vmcnt(8)
	s_waitcnt lgkmcnt(0)
	s_setprio 1
	s_barrier
	v_mfma_f32_16x16x32_bf16 v[126:129], v[148:151], v[188:191], v[126:129]
	v_mfma_f32_16x16x32_bf16 v[118:121], v[164:167], v[188:191], v[118:121]
	v_mfma_f32_16x16x32_bf16 v[110:113], v[148:151], v[196:199], v[110:113]
	v_mfma_f32_16x16x32_bf16 v[102:105], v[164:167], v[196:199], v[102:105]
	v_mfma_f32_16x16x32_bf16 v[94:97], v[148:151], v[204:207], v[94:97]
	v_mfma_f32_16x16x32_bf16 v[86:89], v[164:167], v[204:207], v[86:89]
	v_mfma_f32_16x16x32_bf16 v[78:81], v[148:151], v[212:215], v[78:81]
	v_mfma_f32_16x16x32_bf16 v[70:73], v[164:167], v[212:215], v[70:73]
	v_mfma_f32_16x16x32_bf16 v[126:129], v[160:163], v[192:195], v[126:129]
	v_mfma_f32_16x16x32_bf16 v[118:121], v[168:171], v[192:195], v[118:121]
	v_mfma_f32_16x16x32_bf16 v[110:113], v[160:163], v[200:203], v[110:113]
	v_mfma_f32_16x16x32_bf16 v[102:105], v[168:171], v[200:203], v[102:105]
	v_mfma_f32_16x16x32_bf16 v[94:97], v[160:163], v[208:211], v[94:97]
	v_mfma_f32_16x16x32_bf16 v[86:89], v[168:171], v[208:211], v[86:89]
	v_mfma_f32_16x16x32_bf16 v[78:81], v[160:163], v[216:219], v[78:81]
	v_mfma_f32_16x16x32_bf16 v[70:73], v[168:171], v[216:219], v[70:73]
	v_mfma_f32_16x16x32_bf16 v[122:125], v[172:175], v[188:191], v[122:125]
	v_mfma_f32_16x16x32_bf16 v[114:117], v[180:183], v[188:191], v[114:117]
	v_mfma_f32_16x16x32_bf16 v[106:109], v[172:175], v[196:199], v[106:109]
	v_mfma_f32_16x16x32_bf16 v[98:101], v[180:183], v[196:199], v[98:101]
	v_mfma_f32_16x16x32_bf16 v[90:93], v[172:175], v[204:207], v[90:93]
	v_mfma_f32_16x16x32_bf16 v[82:85], v[180:183], v[204:207], v[82:85]
	v_mfma_f32_16x16x32_bf16 v[74:77], v[172:175], v[212:215], v[74:77]
	v_mfma_f32_16x16x32_bf16 v[66:69], v[180:183], v[212:215], v[66:69]
	v_mfma_f32_16x16x32_bf16 v[122:125], v[176:179], v[192:195], v[122:125]
	v_mfma_f32_16x16x32_bf16 v[114:117], v[184:187], v[192:195], v[114:117]
	v_mfma_f32_16x16x32_bf16 v[106:109], v[176:179], v[200:203], v[106:109]
	v_mfma_f32_16x16x32_bf16 v[98:101], v[184:187], v[200:203], v[98:101]
	v_mfma_f32_16x16x32_bf16 v[90:93], v[176:179], v[208:211], v[90:93]
	v_mfma_f32_16x16x32_bf16 v[82:85], v[184:187], v[208:211], v[82:85]
	v_mfma_f32_16x16x32_bf16 v[74:77], v[176:179], v[216:219], v[74:77]
	v_mfma_f32_16x16x32_bf16 v[66:69], v[184:187], v[216:219], v[66:69]
	s_barrier
; #define PG8_STAGE(bufoff, gbase, voff) do { _Pragma("unroll") for (int _i = 0; _i < 2; ++_i) \
;         __builtin_amdgcn_global_load_lds((const unsigned*)((const char*)(gbase) + (voff)[_i]), (PG8_LAS unsigned*)(lds + (bufoff) + ldsw + _i * 8192), 16, 0, 0); } while (0)
; #define PG8_WAIT_V(n) asm volatile("s_waitcnt vmcnt(" #n ")" ::: "memory")
; #define PG8_WAIT_L(n) asm volatile("s_waitcnt lgkmcnt(" #n ")" ::: "memory")
; #define PG8_BAR __builtin_amdgcn_s_barrier()
; #define PG8_SCHED __builtin_amdgcn_sched_barrier(0)
; template <class Epi, class Sched, bool ALIGN_EPI = true, bool SP2 = true>
; __device__ __forceinline__ void gemm_phase(PG8_LAS unsigned char* lds, const int K  , const Sched& S, const Epi& E) {
;     ...
;             PG8_LDA(At, 1, 1); PG8_STAGE(PG8_SB(1, 0), b3, voffB); PG8_STAGE(PG8_SB(1, 1), b3 + hstep, voffB); PG8_STAGE(PG8_SA(1, 0), a3, voffA);
;             PG8_WAIT_V(8); PG8_WAIT_L(0); PG8_BAR; PG8_MMA(1, 0, At, B0); PG8_MMA(1, 1, At, B1); PG8_BAR; PG8_SCHED;
;     ...
;         }
;         if constexpr (Epi::FP8) asm volatile("s_nop 15\n\ts_nop 15\n\ts_nop 15\n\ts_nop 15\n\ts_nop 15" ::: "memory");
;         if constexpr (ALIGN_EPI) { if (wr == 0) PG8_BAR; }
	s_setprio 0
	s_add_i32 s26, s49, s29
	v_lshl_add_u64 v[220:221], v[220:221], 0, s[4:5]
	s_mov_b32 m0, s26
	ds_read_b128 v[188:191], v156 offset:49152
	ds_read_b128 v[192:195], v156 offset:50176
	ds_read_b128 v[196:199], v156 offset:51200
	ds_read_b128 v[200:203], v156 offset:52224
	ds_read_b128 v[204:207], v156 offset:53248
	ds_read_b128 v[208:211], v156 offset:54272
	ds_read_b128 v[212:215], v156 offset:55296
	ds_read_b128 v[216:219], v156 offset:56320
	global_load_lds_dwordx4 v[220:221], off
	s_add_i32 m0, s26, 0x2000
	s_add_u32 s24, s24, 0x80080
	v_lshl_add_u64 v[220:221], v[222:223], 0, s[4:5]
	s_addc_u32 s25, s25, 0
	s_add_i32 s26, s50, s29
	global_load_lds_dwordx4 v[220:221], off
	v_lshl_add_u64 v[220:221], s[24:25], 0, v[136:137]
	s_mov_b32 m0, s26
	s_nop 0
	global_load_lds_dwordx4 v[220:221], off
	v_lshl_add_u64 v[220:221], s[24:25], 0, v[132:133]
	s_add_i32 m0, s26, 0x2000
	s_nop 0
	global_load_lds_dwordx4 v[220:221], off
	v_lshl_add_u64 v[220:221], v[224:225], 0, s[4:5]
	s_mov_b32 m0, s36
	s_nop 0
	global_load_lds_dwordx4 v[220:221], off
	v_lshl_add_u64 v[220:221], v[226:227], 0, s[4:5]
	s_mov_b32 m0, s37
	s_nop 0
	global_load_lds_dwordx4 v[220:221], off
	s_waitcnt vmcnt(8)
	s_waitcnt lgkmcnt(0)
	s_setprio 1
	s_barrier
	v_mfma_f32_16x16x32_bf16 v[62:65], v[148:151], v[188:191], v[62:65]
	v_mfma_f32_16x16x32_bf16 v[54:57], v[164:167], v[188:191], v[54:57]
	v_mfma_f32_16x16x32_bf16 v[46:49], v[148:151], v[196:199], v[46:49]
	v_mfma_f32_16x16x32_bf16 v[38:41], v[164:167], v[196:199], v[38:41]
	v_mfma_f32_16x16x32_bf16 v[30:33], v[148:151], v[204:207], v[30:33]
	v_mfma_f32_16x16x32_bf16 v[22:25], v[164:167], v[204:207], v[22:25]
	v_mfma_f32_16x16x32_bf16 v[14:17], v[148:151], v[212:215], v[14:17]
	v_mfma_f32_16x16x32_bf16 v[6:9], v[164:167], v[212:215], v[6:9]
	v_mfma_f32_16x16x32_bf16 v[62:65], v[160:163], v[192:195], v[62:65]
	v_mfma_f32_16x16x32_bf16 v[54:57], v[168:171], v[192:195], v[54:57]
	v_mfma_f32_16x16x32_bf16 v[46:49], v[160:163], v[200:203], v[46:49]
	v_mfma_f32_16x16x32_bf16 v[38:41], v[168:171], v[200:203], v[38:41]
	v_mfma_f32_16x16x32_bf16 v[30:33], v[160:163], v[208:211], v[30:33]
	v_mfma_f32_16x16x32_bf16 v[22:25], v[168:171], v[208:211], v[22:25]
	v_mfma_f32_16x16x32_bf16 v[14:17], v[160:163], v[216:219], v[14:17]
	v_mfma_f32_16x16x32_bf16 v[6:9], v[168:171], v[216:219], v[6:9]
	v_mfma_f32_16x16x32_bf16 v[58:61], v[172:175], v[188:191], v[58:61]
	v_mfma_f32_16x16x32_bf16 v[50:53], v[180:183], v[188:191], v[50:53]
	v_mfma_f32_16x16x32_bf16 v[42:45], v[172:175], v[196:199], v[42:45]
	v_mfma_f32_16x16x32_bf16 v[34:37], v[180:183], v[196:199], v[34:37]
	v_mfma_f32_16x16x32_bf16 v[26:29], v[172:175], v[204:207], v[26:29]
	v_mfma_f32_16x16x32_bf16 v[18:21], v[180:183], v[204:207], v[18:21]
	v_mfma_f32_16x16x32_bf16 v[10:13], v[172:175], v[212:215], v[10:13]
	v_mfma_f32_16x16x32_bf16 v[2:5], v[180:183], v[212:215], v[2:5]
	v_mfma_f32_16x16x32_bf16 v[58:61], v[176:179], v[192:195], v[58:61]
	v_mfma_f32_16x16x32_bf16 v[50:53], v[184:187], v[192:195], v[50:53]
	v_mfma_f32_16x16x32_bf16 v[42:45], v[176:179], v[200:203], v[42:45]
	v_mfma_f32_16x16x32_bf16 v[34:37], v[184:187], v[200:203], v[34:37]
	v_mfma_f32_16x16x32_bf16 v[26:29], v[176:179], v[208:211], v[26:29]
	v_mfma_f32_16x16x32_bf16 v[18:21], v[184:187], v[208:211], v[18:21]
	v_mfma_f32_16x16x32_bf16 v[10:13], v[176:179], v[216:219], v[10:13]
	v_mfma_f32_16x16x32_bf16 v[2:5], v[184:187], v[216:219], v[2:5]
	s_barrier
	s_setprio 0
	s_add_i32 s48, s48, 2
	s_add_u32 s22, s22, 0x100
	s_addc_u32 s23, s23, 0
	s_add_u32 s46, s46, 0x100
	s_addc_u32 s47, s47, 0
	s_cmp_gt_u32 s48, 29
	s_cbranch_scc0 .LBB0_1099
	s_and_b64 vcc, exec, s[8:9]
	s_cbranch_vccz .LBB0_1102
	s_barrier

; #define PG8_STAGE(bufoff, gbase, voff) do { _Pragma("unroll") for (int _i = 0; _i < 2; ++_i) \
;         __builtin_amdgcn_global_load_lds((const unsigned*)((const char*)(gbase) + (voff)[_i]), (PG8_LAS unsigned*)(lds + (bufoff) + ldsw + _i * 8192), 16, 0, 0); } while (0)
; #define PG8_WAIT_V(n) asm volatile("s_waitcnt vmcnt(" #n ")" ::: "memory")
; #define PG8_WAIT_L(n) asm volatile("s_waitcnt lgkmcnt(" #n ")" ::: "memory")
; #define PG8_BAR __builtin_amdgcn_s_barrier()
; #define PG8_SCHED __builtin_amdgcn_sched_barrier(0)
;     __device__ __forceinline__ int nt(const pg8::Unit& u) const { return u.kind == 0 ? ntiles : q_nt(u.kind - 1); }
; template <class Epi, class Sched, bool ALIGN_EPI = true, bool SP2 = true>
; __device__ __forceinline__ void gemm_phase(PG8_LAS unsigned char* lds, const int K  , const Sched& S, const Epi& E) {
;     ...
;             const bool last = (t == nt - 2);
;             const char* a1 = cA + (size_t)(t + 1) * kstep;
;             const char* a2 = last ? nA : cA + (size_t)(t + 2) * kstep; const char* b2 = last ? nB : cB + (size_t)(t + 2) * kstep;
;             const char* a3 = a2 + kstep; const char* b3 = b2 + kstep;
;             if constexpr (SP2) {
;             PG8_LDB(B0, 0, 0); PG8_LDB(B1, 0, 1); PG8_SCHED; PG8_LDA(At, 0, 0); PG8_STAGE(PG8_SA(1, 1), a1 + hstep, voffA);
;             PG8_WAIT_V(8); PG8_WAIT_L(0); PG8_BAR; PG8_MMA(0, 0, At, B0); PG8_MMA(0, 1, At, B1); PG8_BAR; PG8_SCHED;
;             PG8_LDA(At, 0, 1); PG8_STAGE(PG8_SB(0, 0), b2, voffB); PG8_STAGE(PG8_SB(0, 1), b2 + hstep, voffB); PG8_STAGE(PG8_SA(0, 0), a2, voffA);
;             PG8_WAIT_V(8); PG8_WAIT_L(0); PG8_BAR; PG8_MMA(1, 0, At, B0); PG8_MMA(1, 1, At, B1); PG8_BAR; PG8_SCHED;
.LBB0_1304:
	ds_read_b128 v[18:21], v233
	ds_read_b128 v[22:25], v233 offset:1024
	ds_read_b128 v[26:29], v233 offset:2048
	ds_read_b128 v[30:33], v233 offset:3072
	ds_read_b128 v[2:5], v234
	ds_read_b128 v[6:9], v234 offset:1024
	ds_read_b128 v[10:13], v234 offset:2048
	ds_read_b128 v[14:17], v234 offset:3072
	s_add_i32 s74, s22, 2
	s_add_u32 s20, s18, 0xfff50080
	s_addc_u32 s21, s19, -1
	s_cmp_eq_u32 s71, s22
	s_cselect_b32 s22, s14, s20
	s_cselect_b32 s23, s15, s21
	s_cselect_b32 s21, s17, s73
	s_cselect_b32 s20, s16, s72
	v_lshl_add_u64 v[186:187], s[18:19], 0, v[198:199]
	s_add_i32 m0, s26, 0xc000
	ds_read_b128 v[162:165], v235
	ds_read_b128 v[166:169], v235 offset:1024
	ds_read_b128 v[170:173], v235 offset:2048
	ds_read_b128 v[174:177], v235 offset:3072
	ds_read_b128 v[178:181], v235 offset:4096
	ds_read_b128 v[182:185], v235 offset:5120
	ds_read_b128 v[206:209], v235 offset:6144
	ds_read_b128 v[210:213], v235 offset:7168
	global_load_lds_dwordx4 v[186:187], off
	v_lshl_add_u64 v[186:187], s[18:19], 0, v[200:201]
	s_add_i32 m0, s26, 0xe000
	s_nop 0
	global_load_lds_dwordx4 v[186:187], off
	s_waitcnt vmcnt(8)
	s_waitcnt lgkmcnt(0)
	s_setprio 1
	s_barrier
	v_mfma_scale_f32_16x16x128_f8f6f4 v[158:161], v[18:25], v[162:169], v[158:161], v229, v229 op_sel_hi:[0,0,0]
	v_mfma_scale_f32_16x16x128_f8f6f4 v[154:157], v[26:33], v[162:169], v[154:157], v229, v229 op_sel_hi:[0,0,0]
	v_mfma_scale_f32_16x16x128_f8f6f4 v[150:153], v[18:25], v[170:177], v[150:153], v229, v229 op_sel_hi:[0,0,0]
	v_mfma_scale_f32_16x16x128_f8f6f4 v[142:145], v[26:33], v[170:177], v[142:145], v229, v229 op_sel_hi:[0,0,0]
	v_mfma_scale_f32_16x16x128_f8f6f4 v[134:137], v[18:25], v[178:185], v[134:137], v229, v229 op_sel_hi:[0,0,0]
	v_mfma_scale_f32_16x16x128_f8f6f4 v[126:129], v[26:33], v[178:185], v[126:129], v229, v229 op_sel_hi:[0,0,0]
	v_mfma_scale_f32_16x16x128_f8f6f4 v[118:121], v[18:25], v[206:213], v[118:121], v229, v229 op_sel_hi:[0,0,0]
	v_mfma_scale_f32_16x16x128_f8f6f4 v[110:113], v[26:33], v[206:213], v[110:113], v229, v229 op_sel_hi:[0,0,0]
	v_mfma_scale_f32_16x16x128_f8f6f4 v[146:149], v[2:9], v[162:169], v[146:149], v229, v229 op_sel_hi:[0,0,0]
	v_mfma_scale_f32_16x16x128_f8f6f4 v[138:141], v[10:17], v[162:169], v[138:141], v229, v229 op_sel_hi:[0,0,0]
	v_mfma_scale_f32_16x16x128_f8f6f4 v[130:133], v[2:9], v[170:177], v[130:133], v229, v229 op_sel_hi:[0,0,0]
	v_mfma_scale_f32_16x16x128_f8f6f4 v[122:125], v[10:17], v[170:177], v[122:125], v229, v229 op_sel_hi:[0,0,0]
	v_mfma_scale_f32_16x16x128_f8f6f4 v[114:117], v[2:9], v[178:185], v[114:117], v229, v229 op_sel_hi:[0,0,0]
	v_mfma_scale_f32_16x16x128_f8f6f4 v[106:109], v[10:17], v[178:185], v[106:109], v229, v229 op_sel_hi:[0,0,0]
	v_mfma_scale_f32_16x16x128_f8f6f4 v[102:105], v[2:9], v[206:213], v[102:105], v229, v229 op_sel_hi:[0,0,0]
	v_mfma_scale_f32_16x16x128_f8f6f4 v[98:101], v[10:17], v[206:213], v[98:101], v229, v229 op_sel_hi:[0,0,0]
	s_barrier
	s_setprio 0
	s_add_i32 s75, s40, s25
	v_lshl_add_u64 v[162:163], s[20:21], 0, v[192:193]
	s_mov_b32 m0, s75
	ds_read_b128 v[170:173], v235 offset:16384
	ds_read_b128 v[174:177], v235 offset:17408
	ds_read_b128 v[178:181], v235 offset:18432
	ds_read_b128 v[182:185], v235 offset:19456
	ds_read_b128 v[206:209], v235 offset:20480
	ds_read_b128 v[210:213], v235 offset:21504
	ds_read_b128 v[214:217], v235 offset:22528
	ds_read_b128 v[218:221], v235 offset:23552
	global_load_lds_dwordx4 v[162:163], off
	s_add_i32 m0, s75, 0x2000
	s_add_u32 s76, s20, 0xb0000
	v_lshl_add_u64 v[164:165], s[20:21], 0, v[196:197]
	s_addc_u32 s77, s21, 0
	s_add_i32 s75, s41, s25
	global_load_lds_dwordx4 v[164:165], off
	v_lshl_add_u64 v[166:167], s[76:77], 0, v[192:193]
	s_mov_b32 m0, s75
	v_lshl_add_u64 v[168:169], s[22:23], 0, v[194:195]
	global_load_lds_dwordx4 v[166:167], off
	v_lshl_add_u64 v[166:167], s[76:77], 0, v[196:197]
	s_add_i32 m0, s75, 0x2000
	s_nop 0
	global_load_lds_dwordx4 v[166:167], off
	v_lshl_add_u64 v[166:167], s[22:23], 0, v[190:191]
	s_mov_b32 m0, s26
	s_nop 0
	global_load_lds_dwordx4 v[166:167], off
	s_mov_b32 m0, s27
	s_nop 0
	global_load_lds_dwordx4 v[168:169], off
	s_waitcnt vmcnt(8)
	s_waitcnt lgkmcnt(0)
	s_setprio 1
	s_barrier
	v_mfma_scale_f32_16x16x128_f8f6f4 v[94:97], v[18:25], v[170:177], v[94:97], v229, v229 op_sel_hi:[0,0,0]
	v_mfma_scale_f32_16x16x128_f8f6f4 v[90:93], v[26:33], v[170:177], v[90:93], v229, v229 op_sel_hi:[0,0,0]
	v_mfma_scale_f32_16x16x128_f8f6f4 v[86:89], v[18:25], v[178:185], v[86:89], v229, v229 op_sel_hi:[0,0,0]
	v_mfma_scale_f32_16x16x128_f8f6f4 v[78:81], v[26:33], v[178:185], v[78:81], v229, v229 op_sel_hi:[0,0,0]
	v_mfma_scale_f32_16x16x128_f8f6f4 v[70:73], v[18:25], v[206:213], v[70:73], v229, v229 op_sel_hi:[0,0,0]
	v_mfma_scale_f32_16x16x128_f8f6f4 v[62:65], v[26:33], v[206:213], v[62:65], v229, v229 op_sel_hi:[0,0,0]
	v_mfma_scale_f32_16x16x128_f8f6f4 v[54:57], v[18:25], v[214:221], v[54:57], v229, v229 op_sel_hi:[0,0,0]
	v_mfma_scale_f32_16x16x128_f8f6f4 v[46:49], v[26:33], v[214:221], v[46:49], v229, v229 op_sel_hi:[0,0,0]
	v_mfma_scale_f32_16x16x128_f8f6f4 v[82:85], v[2:9], v[170:177], v[82:85], v229, v229 op_sel_hi:[0,0,0]
	v_mfma_scale_f32_16x16x128_f8f6f4 v[74:77], v[10:17], v[170:177], v[74:77], v229, v229 op_sel_hi:[0,0,0]
	v_mfma_scale_f32_16x16x128_f8f6f4 v[66:69], v[2:9], v[178:185], v[66:69], v229, v229 op_sel_hi:[0,0,0]
	v_mfma_scale_f32_16x16x128_f8f6f4 v[58:61], v[10:17], v[178:185], v[58:61], v229, v229 op_sel_hi:[0,0,0]
	v_mfma_scale_f32_16x16x128_f8f6f4 v[50:53], v[2:9], v[206:213], v[50:53], v229, v229 op_sel_hi:[0,0,0]
	v_mfma_scale_f32_16x16x128_f8f6f4 v[42:45], v[10:17], v[206:213], v[42:45], v229, v229 op_sel_hi:[0,0,0]
	v_mfma_scale_f32_16x16x128_f8f6f4 v[38:41], v[2:9], v[214:221], v[38:41], v229, v229 op_sel_hi:[0,0,0]
	v_mfma_scale_f32_16x16x128_f8f6f4 v[34:37], v[10:17], v[214:221], v[34:37], v229, v229 op_sel_hi:[0,0,0]
	s_barrier
; #define PG8_STAGE(bufoff, gbase, voff) do { _Pragma("unroll") for (int _i = 0; _i < 2; ++_i) \
;         __builtin_amdgcn_global_load_lds((const unsigned*)((const char*)(gbase) + (voff)[_i]), (PG8_LAS unsigned*)(lds + (bufoff) + ldsw + _i * 8192), 16, 0, 0); } while (0)
; #define PG8_WAIT_V(n) asm volatile("s_waitcnt vmcnt(" #n ")" ::: "memory")
; #define PG8_WAIT_L(n) asm volatile("s_waitcnt lgkmcnt(" #n ")" ::: "memory")
; #define PG8_BAR __builtin_amdgcn_s_barrier()
; #define PG8_SCHED __builtin_amdgcn_sched_barrier(0)
; template <class Epi, class Sched, bool ALIGN_EPI = true, bool SP2 = true>
; __device__ __forceinline__ void gemm_phase(PG8_LAS unsigned char* lds, const int K  , const Sched& S, const Epi& E) {
;     ...
;             PG8_LDB(B0, 1, 0); PG8_LDB(B1, 1, 1); PG8_SCHED; PG8_LDA(At, 1, 0); PG8_STAGE(PG8_SA(0, 1), a2 + hstep, voffA);
;             PG8_WAIT_V(8); PG8_WAIT_L(0); PG8_BAR; PG8_MMA(0, 0, At, B0); PG8_MMA(0, 1, At, B1); PG8_BAR; PG8_SCHED;
;             PG8_LDA(At, 1, 1); PG8_STAGE(PG8_SB(1, 0), b3, voffB); PG8_STAGE(PG8_SB(1, 1), b3 + hstep, voffB); PG8_STAGE(PG8_SA(1, 0), a3, voffA);
;             PG8_WAIT_V(8); PG8_WAIT_L(0); PG8_BAR; PG8_MMA(1, 0, At, B0); PG8_MMA(1, 1, At, B1); PG8_BAR; PG8_SCHED;
;     ...
;         if constexpr (Epi::FP8) asm volatile("s_nop 15\n\ts_nop 15\n\ts_nop 15\n\ts_nop 15\n\ts_nop 15" ::: "memory");
;         if constexpr (ALIGN_EPI) { if (wr == 0) PG8_BAR; }
	s_setprio 0
	s_add_i32 s75, 0, 0x18000
	s_add_i32 s76, 0, 0x1c000
	v_add_u32_e32 v14, s75, v231
	v_add_u32_e32 v30, s76, v231
	ds_read_b128 v[2:5], v14
	ds_read_b128 v[6:9], v14 offset:1024
	ds_read_b128 v[10:13], v14 offset:2048
	ds_read_b128 v[14:17], v14 offset:3072
	ds_read_b128 v[18:21], v30
	ds_read_b128 v[22:25], v30 offset:1024
	ds_read_b128 v[26:29], v30 offset:2048
	ds_read_b128 v[30:33], v30 offset:3072
	s_add_u32 s22, s22, 0xb0000
	s_addc_u32 s23, s23, 0
	s_mov_b32 m0, s28
	v_lshl_add_u64 v[186:187], s[22:23], 0, v[190:191]
	ds_read_b128 v[170:173], v235 offset:32768
	ds_read_b128 v[174:177], v235 offset:33792
	ds_read_b128 v[178:181], v235 offset:34816
	ds_read_b128 v[182:185], v235 offset:35840
	ds_read_b128 v[206:209], v235 offset:36864
	ds_read_b128 v[210:213], v235 offset:37888
	ds_read_b128 v[214:217], v235 offset:38912
	ds_read_b128 v[218:221], v235 offset:39936
	global_load_lds_dwordx4 v[186:187], off
	v_lshl_add_u64 v[186:187], s[22:23], 0, v[194:195]
	s_mov_b32 m0, s29
	s_nop 0
	global_load_lds_dwordx4 v[186:187], off
	s_waitcnt vmcnt(8)
	s_waitcnt lgkmcnt(0)
	s_setprio 1
	s_barrier
	v_mfma_scale_f32_16x16x128_f8f6f4 v[158:161], v[2:9], v[170:177], v[158:161], v229, v229 op_sel_hi:[0,0,0]
	v_mfma_scale_f32_16x16x128_f8f6f4 v[154:157], v[10:17], v[170:177], v[154:157], v229, v229 op_sel_hi:[0,0,0]
	v_mfma_scale_f32_16x16x128_f8f6f4 v[150:153], v[2:9], v[178:185], v[150:153], v229, v229 op_sel_hi:[0,0,0]
	v_mfma_scale_f32_16x16x128_f8f6f4 v[142:145], v[10:17], v[178:185], v[142:145], v229, v229 op_sel_hi:[0,0,0]
	v_mfma_scale_f32_16x16x128_f8f6f4 v[134:137], v[2:9], v[206:213], v[134:137], v229, v229 op_sel_hi:[0,0,0]
	v_mfma_scale_f32_16x16x128_f8f6f4 v[126:129], v[10:17], v[206:213], v[126:129], v229, v229 op_sel_hi:[0,0,0]
	v_mfma_scale_f32_16x16x128_f8f6f4 v[118:121], v[2:9], v[214:221], v[118:121], v229, v229 op_sel_hi:[0,0,0]
	v_mfma_scale_f32_16x16x128_f8f6f4 v[110:113], v[10:17], v[214:221], v[110:113], v229, v229 op_sel_hi:[0,0,0]
	v_mfma_scale_f32_16x16x128_f8f6f4 v[146:149], v[18:25], v[170:177], v[146:149], v229, v229 op_sel_hi:[0,0,0]
	v_mfma_scale_f32_16x16x128_f8f6f4 v[138:141], v[26:33], v[170:177], v[138:141], v229, v229 op_sel_hi:[0,0,0]
	v_mfma_scale_f32_16x16x128_f8f6f4 v[130:133], v[18:25], v[178:185], v[130:133], v229, v229 op_sel_hi:[0,0,0]
	v_mfma_scale_f32_16x16x128_f8f6f4 v[122:125], v[26:33], v[178:185], v[122:125], v229, v229 op_sel_hi:[0,0,0]
	v_mfma_scale_f32_16x16x128_f8f6f4 v[114:117], v[18:25], v[206:213], v[114:117], v229, v229 op_sel_hi:[0,0,0]
	v_mfma_scale_f32_16x16x128_f8f6f4 v[106:109], v[26:33], v[206:213], v[106:109], v229, v229 op_sel_hi:[0,0,0]
	v_mfma_scale_f32_16x16x128_f8f6f4 v[102:105], v[18:25], v[214:221], v[102:105], v229, v229 op_sel_hi:[0,0,0]
	v_mfma_scale_f32_16x16x128_f8f6f4 v[98:101], v[26:33], v[214:221], v[98:101], v229, v229 op_sel_hi:[0,0,0]
	s_barrier
	s_setprio 0
	s_add_i32 s22, s75, s25
	v_lshl_add_u64 v[162:163], v[162:163], 0, s[8:9]
	s_mov_b32 m0, s22
	ds_read_b128 v[170:173], v235 offset:49152
	ds_read_b128 v[174:177], v235 offset:50176
	ds_read_b128 v[178:181], v235 offset:51200
	ds_read_b128 v[182:185], v235 offset:52224
	ds_read_b128 v[206:209], v235 offset:53248
	ds_read_b128 v[210:213], v235 offset:54272
	ds_read_b128 v[214:217], v235 offset:55296
	ds_read_b128 v[218:221], v235 offset:56320
	global_load_lds_dwordx4 v[162:163], off
	s_add_i32 m0, s22, 0x2000
	s_add_u32 s20, s20, 0xb0080
	v_lshl_add_u64 v[162:163], v[164:165], 0, s[8:9]
	s_addc_u32 s21, s21, 0
	s_add_i32 s22, s76, s25
	global_load_lds_dwordx4 v[162:163], off
	v_lshl_add_u64 v[162:163], s[20:21], 0, v[192:193]
	s_mov_b32 m0, s22
	s_nop 0
	global_load_lds_dwordx4 v[162:163], off
	v_lshl_add_u64 v[162:163], s[20:21], 0, v[196:197]
	s_add_i32 m0, s22, 0x2000
	s_nop 0
	global_load_lds_dwordx4 v[162:163], off
	v_lshl_add_u64 v[162:163], v[166:167], 0, s[8:9]
	s_mov_b32 m0, s36
	s_nop 0
	global_load_lds_dwordx4 v[162:163], off
	v_lshl_add_u64 v[162:163], v[168:169], 0, s[8:9]
	s_mov_b32 m0, s37
	s_nop 0
	global_load_lds_dwordx4 v[162:163], off
	s_waitcnt vmcnt(8)
	s_waitcnt lgkmcnt(0)
	s_setprio 1
	s_barrier
	v_mfma_scale_f32_16x16x128_f8f6f4 v[94:97], v[2:9], v[170:177], v[94:97], v229, v229 op_sel_hi:[0,0,0]
	v_mfma_scale_f32_16x16x128_f8f6f4 v[90:93], v[10:17], v[170:177], v[90:93], v229, v229 op_sel_hi:[0,0,0]
	v_mfma_scale_f32_16x16x128_f8f6f4 v[86:89], v[2:9], v[178:185], v[86:89], v229, v229 op_sel_hi:[0,0,0]
	v_mfma_scale_f32_16x16x128_f8f6f4 v[78:81], v[10:17], v[178:185], v[78:81], v229, v229 op_sel_hi:[0,0,0]
	v_mfma_scale_f32_16x16x128_f8f6f4 v[70:73], v[2:9], v[206:213], v[70:73], v229, v229 op_sel_hi:[0,0,0]
	v_mfma_scale_f32_16x16x128_f8f6f4 v[62:65], v[10:17], v[206:213], v[62:65], v229, v229 op_sel_hi:[0,0,0]
	v_mfma_scale_f32_16x16x128_f8f6f4 v[54:57], v[2:9], v[214:221], v[54:57], v229, v229 op_sel_hi:[0,0,0]
	v_mfma_scale_f32_16x16x128_f8f6f4 v[46:49], v[10:17], v[214:221], v[46:49], v229, v229 op_sel_hi:[0,0,0]
	v_mfma_scale_f32_16x16x128_f8f6f4 v[82:85], v[18:25], v[170:177], v[82:85], v229, v229 op_sel_hi:[0,0,0]
	v_mfma_scale_f32_16x16x128_f8f6f4 v[74:77], v[26:33], v[170:177], v[74:77], v229, v229 op_sel_hi:[0,0,0]
	v_mfma_scale_f32_16x16x128_f8f6f4 v[66:69], v[18:25], v[178:185], v[66:69], v229, v229 op_sel_hi:[0,0,0]
	v_mfma_scale_f32_16x16x128_f8f6f4 v[58:61], v[26:33], v[178:185], v[58:61], v229, v229 op_sel_hi:[0,0,0]
	v_mfma_scale_f32_16x16x128_f8f6f4 v[50:53], v[18:25], v[206:213], v[50:53], v229, v229 op_sel_hi:[0,0,0]
	v_mfma_scale_f32_16x16x128_f8f6f4 v[42:45], v[26:33], v[206:213], v[42:45], v229, v229 op_sel_hi:[0,0,0]
	v_mfma_scale_f32_16x16x128_f8f6f4 v[38:41], v[18:25], v[214:221], v[38:41], v229, v229 op_sel_hi:[0,0,0]
	v_mfma_scale_f32_16x16x128_f8f6f4 v[34:37], v[26:33], v[214:221], v[34:37], v229, v229 op_sel_hi:[0,0,0]
	s_barrier
	s_setprio 0
	s_add_u32 s18, s18, 0x100
	s_addc_u32 s19, s19, 0
	s_add_u32 s72, s72, 0x100
	s_addc_u32 s73, s73, 0
	s_cmp_ge_u32 s74, s4
	s_mov_b32 s22, s74
	s_cbranch_scc0 .LBB0_1304
	s_nop 15
	s_nop 15
	s_nop 15
	s_nop 15
	s_nop 15
	s_and_b64 vcc, exec, s[10:11]
	s_cbranch_vccz .LBB0_1307
	s_barrier

; #define PG8_STAGE(bufoff, gbase, voff) do { _Pragma("unroll") for (int _i = 0; _i < 2; ++_i) \
;         __builtin_amdgcn_global_load_lds((const unsigned*)((const char*)(gbase) + (voff)[_i]), (PG8_LAS unsigned*)(lds + (bufoff) + ldsw + _i * 8192), 16, 0, 0); } while (0)
; #define PG8_WAIT_V(n) asm volatile("s_waitcnt vmcnt(" #n ")" ::: "memory")
; #define PG8_WAIT_L(n) asm volatile("s_waitcnt lgkmcnt(" #n ")" ::: "memory")
; #define PG8_BAR __builtin_amdgcn_s_barrier()
; #define PG8_SCHED __builtin_amdgcn_sched_barrier(0)
;     __device__ __forceinline__ int nt(const pg8::Unit& u) const { return u.kind == 0 ? ntiles : q_nt(u.kind - 1); }
; template <class Epi, class Sched, bool ALIGN_EPI = true, bool SP2 = true>
; __device__ __forceinline__ void gemm_phase(PG8_LAS unsigned char* lds, const int K  , const Sched& S, const Epi& E) {
;     ...
;             const bool last = (t == nt - 2);
;             const char* a1 = cA + (size_t)(t + 1) * kstep;
;             const char* a2 = last ? nA : cA + (size_t)(t + 2) * kstep; const char* b2 = last ? nB : cB + (size_t)(t + 2) * kstep;
;             const char* a3 = a2 + kstep; const char* b3 = b2 + kstep;
;             if constexpr (SP2) {
;             PG8_LDB(B0, 0, 0); PG8_LDB(B1, 0, 1); PG8_SCHED; PG8_LDA(At, 0, 0); PG8_STAGE(PG8_SA(1, 1), a1 + hstep, voffA);
;             PG8_WAIT_V(8); PG8_WAIT_L(0); PG8_BAR; PG8_MMA(0, 0, At, B0); PG8_MMA(0, 1, At, B1); PG8_BAR; PG8_SCHED;
;             PG8_LDA(At, 0, 1); PG8_STAGE(PG8_SB(0, 0), b2, voffB); PG8_STAGE(PG8_SB(0, 1), b2 + hstep, voffB); PG8_STAGE(PG8_SA(0, 0), a2, voffA);
.LBB0_1448:
	ds_read_b128 v[148:151], v154
	ds_read_b128 v[160:163], v154 offset:1024
	ds_read_b128 v[164:167], v154 offset:2048
	ds_read_b128 v[168:171], v154 offset:3072
	ds_read_b128 v[172:175], v155
	ds_read_b128 v[176:179], v155 offset:1024
	ds_read_b128 v[180:183], v155 offset:2048
	ds_read_b128 v[184:187], v155 offset:3072
	s_add_u32 s26, s24, 0xfff80080
	s_addc_u32 s27, s25, -1
	s_cmp_eq_u32 s50, 28
	s_cselect_b32 s29, s17, s27
	s_cselect_b32 s28, s46, s26
	s_cselect_b32 s27, s11, s49
	s_cselect_b32 s26, s47, s48
	v_lshl_add_u64 v[220:221], s[24:25], 0, v[140:141]
	s_add_i32 m0, s23, 0xc000
	ds_read_b128 v[188:191], v156
	ds_read_b128 v[192:195], v156 offset:1024
	ds_read_b128 v[196:199], v156 offset:2048
	ds_read_b128 v[200:203], v156 offset:3072
	ds_read_b128 v[204:207], v156 offset:4096
	ds_read_b128 v[208:211], v156 offset:5120
	ds_read_b128 v[212:215], v156 offset:6144
	ds_read_b128 v[216:219], v156 offset:7168
	global_load_lds_dwordx4 v[220:221], off
	v_lshl_add_u64 v[220:221], s[24:25], 0, v[142:143]
	s_add_i32 m0, s23, 0xe000
	s_nop 0
	global_load_lds_dwordx4 v[220:221], off
	s_waitcnt vmcnt(8)
	s_waitcnt lgkmcnt(0)
	s_setprio 1
	s_barrier
	v_mfma_f32_16x16x32_bf16 v[126:129], v[148:151], v[188:191], v[126:129]
	v_mfma_f32_16x16x32_bf16 v[118:121], v[164:167], v[188:191], v[118:121]
	v_mfma_f32_16x16x32_bf16 v[110:113], v[148:151], v[196:199], v[110:113]
	v_mfma_f32_16x16x32_bf16 v[102:105], v[164:167], v[196:199], v[102:105]
	v_mfma_f32_16x16x32_bf16 v[94:97], v[148:151], v[204:207], v[94:97]
	v_mfma_f32_16x16x32_bf16 v[86:89], v[164:167], v[204:207], v[86:89]
	v_mfma_f32_16x16x32_bf16 v[78:81], v[148:151], v[212:215], v[78:81]
	v_mfma_f32_16x16x32_bf16 v[70:73], v[164:167], v[212:215], v[70:73]
	v_mfma_f32_16x16x32_bf16 v[126:129], v[160:163], v[192:195], v[126:129]
	v_mfma_f32_16x16x32_bf16 v[118:121], v[168:171], v[192:195], v[118:121]
	v_mfma_f32_16x16x32_bf16 v[110:113], v[160:163], v[200:203], v[110:113]
	v_mfma_f32_16x16x32_bf16 v[102:105], v[168:171], v[200:203], v[102:105]
	v_mfma_f32_16x16x32_bf16 v[94:97], v[160:163], v[208:211], v[94:97]
	v_mfma_f32_16x16x32_bf16 v[86:89], v[168:171], v[208:211], v[86:89]
	v_mfma_f32_16x16x32_bf16 v[78:81], v[160:163], v[216:219], v[78:81]
	v_mfma_f32_16x16x32_bf16 v[70:73], v[168:171], v[216:219], v[70:73]
	v_mfma_f32_16x16x32_bf16 v[122:125], v[172:175], v[188:191], v[122:125]
	v_mfma_f32_16x16x32_bf16 v[114:117], v[180:183], v[188:191], v[114:117]
	v_mfma_f32_16x16x32_bf16 v[106:109], v[172:175], v[196:199], v[106:109]
	v_mfma_f32_16x16x32_bf16 v[98:101], v[180:183], v[196:199], v[98:101]
	v_mfma_f32_16x16x32_bf16 v[90:93], v[172:175], v[204:207], v[90:93]
	v_mfma_f32_16x16x32_bf16 v[82:85], v[180:183], v[204:207], v[82:85]
	v_mfma_f32_16x16x32_bf16 v[74:77], v[172:175], v[212:215], v[74:77]
	v_mfma_f32_16x16x32_bf16 v[66:69], v[180:183], v[212:215], v[66:69]
	v_mfma_f32_16x16x32_bf16 v[122:125], v[176:179], v[192:195], v[122:125]
	v_mfma_f32_16x16x32_bf16 v[114:117], v[184:187], v[192:195], v[114:117]
	v_mfma_f32_16x16x32_bf16 v[106:109], v[176:179], v[200:203], v[106:109]
	v_mfma_f32_16x16x32_bf16 v[98:101], v[184:187], v[200:203], v[98:101]
	v_mfma_f32_16x16x32_bf16 v[90:93], v[176:179], v[208:211], v[90:93]
	v_mfma_f32_16x16x32_bf16 v[82:85], v[184:187], v[208:211], v[82:85]
	v_mfma_f32_16x16x32_bf16 v[74:77], v[176:179], v[216:219], v[74:77]
	v_mfma_f32_16x16x32_bf16 v[66:69], v[184:187], v[216:219], v[66:69]
	s_barrier
	s_setprio 0
	s_add_i32 s51, s41, s31
	v_lshl_add_u64 v[220:221], s[26:27], 0, v[136:137]
	s_mov_b32 m0, s51
	ds_read_b128 v[188:191], v156 offset:16384
	ds_read_b128 v[192:195], v156 offset:17408
	ds_read_b128 v[196:199], v156 offset:18432
	ds_read_b128 v[200:203], v156 offset:19456
	ds_read_b128 v[204:207], v156 offset:20480
	ds_read_b128 v[208:211], v156 offset:21504
	ds_read_b128 v[212:215], v156 offset:22528
	ds_read_b128 v[216:219], v156 offset:23552
	global_load_lds_dwordx4 v[220:221], off
	s_add_i32 m0, s51, 0x2000
	s_add_u32 s68, s26, 0x80000
	v_lshl_add_u64 v[222:223], s[26:27], 0, v[132:133]
	s_addc_u32 s69, s27, 0
	s_add_i32 s51, s42, s31
	global_load_lds_dwordx4 v[222:223], off
	v_lshl_add_u64 v[224:225], s[68:69], 0, v[136:137]
	s_mov_b32 m0, s51
	v_lshl_add_u64 v[226:227], s[28:29], 0, v[134:135]
	global_load_lds_dwordx4 v[224:225], off
	v_lshl_add_u64 v[224:225], s[68:69], 0, v[132:133]
	s_add_i32 m0, s51, 0x2000
	s_nop 0
	global_load_lds_dwordx4 v[224:225], off
	v_lshl_add_u64 v[224:225], s[28:29], 0, v[138:139]
	s_mov_b32 m0, s23
	s_nop 0
	global_load_lds_dwordx4 v[224:225], off
	s_mov_b32 m0, s34
	s_nop 0
	global_load_lds_dwordx4 v[226:227], off
	s_waitcnt vmcnt(8)
	s_waitcnt lgkmcnt(0)
	s_setprio 1
	s_barrier
; #define PG8_STAGE(bufoff, gbase, voff) do { _Pragma("unroll") for (int _i = 0; _i < 2; ++_i) \
;         __builtin_amdgcn_global_load_lds((const unsigned*)((const char*)(gbase) + (voff)[_i]), (PG8_LAS unsigned*)(lds + (bufoff) + ldsw + _i * 8192), 16, 0, 0); } while (0)
; #define PG8_WAIT_V(n) asm volatile("s_waitcnt vmcnt(" #n ")" ::: "memory")
; #define PG8_WAIT_L(n) asm volatile("s_waitcnt lgkmcnt(" #n ")" ::: "memory")
; #define PG8_BAR __builtin_amdgcn_s_barrier()
; #define PG8_SCHED __builtin_amdgcn_sched_barrier(0)
; template <class Epi, class Sched, bool ALIGN_EPI = true, bool SP2 = true>
; __device__ __forceinline__ void gemm_phase(PG8_LAS unsigned char* lds, const int K  , const Sched& S, const Epi& E) {
;     ...
;             PG8_WAIT_V(8); PG8_WAIT_L(0); PG8_BAR; PG8_MMA(1, 0, At, B0); PG8_MMA(1, 1, At, B1); PG8_BAR; PG8_SCHED;
;             PG8_LDB(B0, 1, 0); PG8_LDB(B1, 1, 1); PG8_SCHED; PG8_LDA(At, 1, 0); PG8_STAGE(PG8_SA(0, 1), a2 + hstep, voffA);
;             PG8_WAIT_V(8); PG8_WAIT_L(0); PG8_BAR; PG8_MMA(0, 0, At, B0); PG8_MMA(0, 1, At, B1); PG8_BAR; PG8_SCHED;
	v_mfma_f32_16x16x32_bf16 v[62:65], v[148:151], v[188:191], v[62:65]
	v_mfma_f32_16x16x32_bf16 v[54:57], v[164:167], v[188:191], v[54:57]
	v_mfma_f32_16x16x32_bf16 v[46:49], v[148:151], v[196:199], v[46:49]
	v_mfma_f32_16x16x32_bf16 v[38:41], v[164:167], v[196:199], v[38:41]
	v_mfma_f32_16x16x32_bf16 v[30:33], v[148:151], v[204:207], v[30:33]
	v_mfma_f32_16x16x32_bf16 v[22:25], v[164:167], v[204:207], v[22:25]
	v_mfma_f32_16x16x32_bf16 v[14:17], v[148:151], v[212:215], v[14:17]
	v_mfma_f32_16x16x32_bf16 v[6:9], v[164:167], v[212:215], v[6:9]
	v_mfma_f32_16x16x32_bf16 v[62:65], v[160:163], v[192:195], v[62:65]
	v_mfma_f32_16x16x32_bf16 v[54:57], v[168:171], v[192:195], v[54:57]
	v_mfma_f32_16x16x32_bf16 v[46:49], v[160:163], v[200:203], v[46:49]
	v_mfma_f32_16x16x32_bf16 v[38:41], v[168:171], v[200:203], v[38:41]
	v_mfma_f32_16x16x32_bf16 v[30:33], v[160:163], v[208:211], v[30:33]
	v_mfma_f32_16x16x32_bf16 v[22:25], v[168:171], v[208:211], v[22:25]
	v_mfma_f32_16x16x32_bf16 v[14:17], v[160:163], v[216:219], v[14:17]
	v_mfma_f32_16x16x32_bf16 v[6:9], v[168:171], v[216:219], v[6:9]
	v_mfma_f32_16x16x32_bf16 v[58:61], v[172:175], v[188:191], v[58:61]
	v_mfma_f32_16x16x32_bf16 v[50:53], v[180:183], v[188:191], v[50:53]
	v_mfma_f32_16x16x32_bf16 v[42:45], v[172:175], v[196:199], v[42:45]
	v_mfma_f32_16x16x32_bf16 v[34:37], v[180:183], v[196:199], v[34:37]
	v_mfma_f32_16x16x32_bf16 v[26:29], v[172:175], v[204:207], v[26:29]
	v_mfma_f32_16x16x32_bf16 v[18:21], v[180:183], v[204:207], v[18:21]
	v_mfma_f32_16x16x32_bf16 v[10:13], v[172:175], v[212:215], v[10:13]
	v_mfma_f32_16x16x32_bf16 v[2:5], v[180:183], v[212:215], v[2:5]
	v_mfma_f32_16x16x32_bf16 v[58:61], v[176:179], v[192:195], v[58:61]
	v_mfma_f32_16x16x32_bf16 v[50:53], v[184:187], v[192:195], v[50:53]
	v_mfma_f32_16x16x32_bf16 v[42:45], v[176:179], v[200:203], v[42:45]
	v_mfma_f32_16x16x32_bf16 v[34:37], v[184:187], v[200:203], v[34:37]
	v_mfma_f32_16x16x32_bf16 v[26:29], v[176:179], v[208:211], v[26:29]
	v_mfma_f32_16x16x32_bf16 v[18:21], v[184:187], v[208:211], v[18:21]
	v_mfma_f32_16x16x32_bf16 v[10:13], v[176:179], v[216:219], v[10:13]
	v_mfma_f32_16x16x32_bf16 v[2:5], v[184:187], v[216:219], v[2:5]
	s_barrier
	s_setprio 0
	s_add_i32 s51, 0, 0x18000
	v_add_u32_e32 v159, s51, v152
	s_add_i32 s68, 0, 0x1c000
	ds_read_b128 v[148:151], v159
	ds_read_b128 v[160:163], v159 offset:1024
	ds_read_b128 v[164:167], v159 offset:2048
	ds_read_b128 v[168:171], v159 offset:3072
	v_add_u32_e32 v159, s68, v152
	ds_read_b128 v[172:175], v159
	ds_read_b128 v[176:179], v159 offset:1024
	ds_read_b128 v[180:183], v159 offset:2048
	ds_read_b128 v[184:187], v159 offset:3072
	s_add_u32 s28, s28, 0x80000
	s_addc_u32 s29, s29, 0
	s_mov_b32 m0, s35
	v_lshl_add_u64 v[230:231], s[28:29], 0, v[138:139]
	ds_read_b128 v[188:191], v156 offset:32768
	ds_read_b128 v[192:195], v156 offset:33792
	ds_read_b128 v[196:199], v156 offset:34816
	ds_read_b128 v[200:203], v156 offset:35840
	ds_read_b128 v[204:207], v156 offset:36864
	ds_read_b128 v[208:211], v156 offset:37888
	ds_read_b128 v[212:215], v156 offset:38912
	ds_read_b128 v[216:219], v156 offset:39936
	global_load_lds_dwordx4 v[230:231], off
	v_lshl_add_u64 v[230:231], s[28:29], 0, v[134:135]
	s_mov_b32 m0, s36
	s_nop 0
	global_load_lds_dwordx4 v[230:231], off
	s_waitcnt vmcnt(8)
	s_waitcnt lgkmcnt(0)
	s_setprio 1
	s_barrier
	v_mfma_f32_16x16x32_bf16 v[126:129], v[148:151], v[188:191], v[126:129]
	v_mfma_f32_16x16x32_bf16 v[118:121], v[164:167], v[188:191], v[118:121]
	v_mfma_f32_16x16x32_bf16 v[110:113], v[148:151], v[196:199], v[110:113]
	v_mfma_f32_16x16x32_bf16 v[102:105], v[164:167], v[196:199], v[102:105]
	v_mfma_f32_16x16x32_bf16 v[94:97], v[148:151], v[204:207], v[94:97]
	v_mfma_f32_16x16x32_bf16 v[86:89], v[164:167], v[204:207], v[86:89]
	v_mfma_f32_16x16x32_bf16 v[78:81], v[148:151], v[212:215], v[78:81]
	v_mfma_f32_16x16x32_bf16 v[70:73], v[164:167], v[212:215], v[70:73]
	v_mfma_f32_16x16x32_bf16 v[126:129], v[160:163], v[192:195], v[126:129]
	v_mfma_f32_16x16x32_bf16 v[118:121], v[168:171], v[192:195], v[118:121]
	v_mfma_f32_16x16x32_bf16 v[110:113], v[160:163], v[200:203], v[110:113]
	v_mfma_f32_16x16x32_bf16 v[102:105], v[168:171], v[200:203], v[102:105]
	v_mfma_f32_16x16x32_bf16 v[94:97], v[160:163], v[208:211], v[94:97]
	v_mfma_f32_16x16x32_bf16 v[86:89], v[168:171], v[208:211], v[86:89]
	v_mfma_f32_16x16x32_bf16 v[78:81], v[160:163], v[216:219], v[78:81]
	v_mfma_f32_16x16x32_bf16 v[70:73], v[168:171], v[216:219], v[70:73]
	v_mfma_f32_16x16x32_bf16 v[122:125], v[172:175], v[188:191], v[122:125]
	v_mfma_f32_16x16x32_bf16 v[114:117], v[180:183], v[188:191], v[114:117]
	v_mfma_f32_16x16x32_bf16 v[106:109], v[172:175], v[196:199], v[106:109]
	v_mfma_f32_16x16x32_bf16 v[98:101], v[180:183], v[196:199], v[98:101]
	v_mfma_f32_16x16x32_bf16 v[90:93], v[172:175], v[204:207], v[90:93]
	v_mfma_f32_16x16x32_bf16 v[82:85], v[180:183], v[204:207], v[82:85]
	v_mfma_f32_16x16x32_bf16 v[74:77], v[172:175], v[212:215], v[74:77]
	v_mfma_f32_16x16x32_bf16 v[66:69], v[180:183], v[212:215], v[66:69]
	v_mfma_f32_16x16x32_bf16 v[122:125], v[176:179], v[192:195], v[122:125]
	v_mfma_f32_16x16x32_bf16 v[114:117], v[184:187], v[192:195], v[114:117]
	v_mfma_f32_16x16x32_bf16 v[106:109], v[176:179], v[200:203], v[106:109]
	v_mfma_f32_16x16x32_bf16 v[98:101], v[184:187], v[200:203], v[98:101]
	v_mfma_f32_16x16x32_bf16 v[90:93], v[176:179], v[208:211], v[90:93]
	v_mfma_f32_16x16x32_bf16 v[82:85], v[184:187], v[208:211], v[82:85]
	v_mfma_f32_16x16x32_bf16 v[74:77], v[176:179], v[216:219], v[74:77]
	v_mfma_f32_16x16x32_bf16 v[66:69], v[184:187], v[216:219], v[66:69]
	s_barrier
; #define PG8_STAGE(bufoff, gbase, voff) do { _Pragma("unroll") for (int _i = 0; _i < 2; ++_i) \
;         __builtin_amdgcn_global_load_lds((const unsigned*)((const char*)(gbase) + (voff)[_i]), (PG8_LAS unsigned*)(lds + (bufoff) + ldsw + _i * 8192), 16, 0, 0); } while (0)
; #define PG8_WAIT_V(n) asm volatile("s_waitcnt vmcnt(" #n ")" ::: "memory")
; #define PG8_WAIT_L(n) asm volatile("s_waitcnt lgkmcnt(" #n ")" ::: "memory")
; #define PG8_BAR __builtin_amdgcn_s_barrier()
; #define PG8_SCHED __builtin_amdgcn_sched_barrier(0)
; template <class Epi, class Sched, bool ALIGN_EPI = true, bool SP2 = true>
; __device__ __forceinline__ void gemm_phase(PG8_LAS unsigned char* lds, const int K  , const Sched& S, const Epi& E) {
;     ...
;             PG8_LDA(At, 1, 1); PG8_STAGE(PG8_SB(1, 0), b3, voffB); PG8_STAGE(PG8_SB(1, 1), b3 + hstep, voffB); PG8_STAGE(PG8_SA(1, 0), a3, voffA);
;             PG8_WAIT_V(8); PG8_WAIT_L(0); PG8_BAR; PG8_MMA(1, 0, At, B0); PG8_MMA(1, 1, At, B1); PG8_BAR; PG8_SCHED;
;     ...
;         }
;         if constexpr (Epi::FP8) asm volatile("s_nop 15\n\ts_nop 15\n\ts_nop 15\n\ts_nop 15\n\ts_nop 15" ::: "memory");
;         if constexpr (ALIGN_EPI) { if (wr == 0) PG8_BAR; }
	s_setprio 0
	s_add_i32 s28, s51, s31
	v_lshl_add_u64 v[220:221], v[220:221], 0, s[4:5]
	s_mov_b32 m0, s28
	ds_read_b128 v[188:191], v156 offset:49152
	ds_read_b128 v[192:195], v156 offset:50176
	ds_read_b128 v[196:199], v156 offset:51200
	ds_read_b128 v[200:203], v156 offset:52224
	ds_read_b128 v[204:207], v156 offset:53248
	ds_read_b128 v[208:211], v156 offset:54272
	ds_read_b128 v[212:215], v156 offset:55296
	ds_read_b128 v[216:219], v156 offset:56320
	global_load_lds_dwordx4 v[220:221], off
	s_add_i32 m0, s28, 0x2000
	s_add_u32 s26, s26, 0x80080
	v_lshl_add_u64 v[220:221], v[222:223], 0, s[4:5]
	s_addc_u32 s27, s27, 0
	s_add_i32 s28, s68, s31
	global_load_lds_dwordx4 v[220:221], off
	v_lshl_add_u64 v[220:221], s[26:27], 0, v[136:137]
	s_mov_b32 m0, s28
	s_nop 0
	global_load_lds_dwordx4 v[220:221], off
	v_lshl_add_u64 v[220:221], s[26:27], 0, v[132:133]
	s_add_i32 m0, s28, 0x2000
	s_nop 0
	global_load_lds_dwordx4 v[220:221], off
	v_lshl_add_u64 v[220:221], v[224:225], 0, s[4:5]
	s_mov_b32 m0, s38
	s_nop 0
	global_load_lds_dwordx4 v[220:221], off
	v_lshl_add_u64 v[220:221], v[226:227], 0, s[4:5]
	s_mov_b32 m0, s39
	s_nop 0
	global_load_lds_dwordx4 v[220:221], off
	s_waitcnt vmcnt(8)
	s_waitcnt lgkmcnt(0)
	s_setprio 1
	s_barrier
	v_mfma_f32_16x16x32_bf16 v[62:65], v[148:151], v[188:191], v[62:65]
	v_mfma_f32_16x16x32_bf16 v[54:57], v[164:167], v[188:191], v[54:57]
	v_mfma_f32_16x16x32_bf16 v[46:49], v[148:151], v[196:199], v[46:49]
	v_mfma_f32_16x16x32_bf16 v[38:41], v[164:167], v[196:199], v[38:41]
	v_mfma_f32_16x16x32_bf16 v[30:33], v[148:151], v[204:207], v[30:33]
	v_mfma_f32_16x16x32_bf16 v[22:25], v[164:167], v[204:207], v[22:25]
	v_mfma_f32_16x16x32_bf16 v[14:17], v[148:151], v[212:215], v[14:17]
	v_mfma_f32_16x16x32_bf16 v[6:9], v[164:167], v[212:215], v[6:9]
	v_mfma_f32_16x16x32_bf16 v[62:65], v[160:163], v[192:195], v[62:65]
	v_mfma_f32_16x16x32_bf16 v[54:57], v[168:171], v[192:195], v[54:57]
	v_mfma_f32_16x16x32_bf16 v[46:49], v[160:163], v[200:203], v[46:49]
	v_mfma_f32_16x16x32_bf16 v[38:41], v[168:171], v[200:203], v[38:41]
	v_mfma_f32_16x16x32_bf16 v[30:33], v[160:163], v[208:211], v[30:33]
	v_mfma_f32_16x16x32_bf16 v[22:25], v[168:171], v[208:211], v[22:25]
	v_mfma_f32_16x16x32_bf16 v[14:17], v[160:163], v[216:219], v[14:17]
	v_mfma_f32_16x16x32_bf16 v[6:9], v[168:171], v[216:219], v[6:9]
	v_mfma_f32_16x16x32_bf16 v[58:61], v[172:175], v[188:191], v[58:61]
	v_mfma_f32_16x16x32_bf16 v[50:53], v[180:183], v[188:191], v[50:53]
	v_mfma_f32_16x16x32_bf16 v[42:45], v[172:175], v[196:199], v[42:45]
	v_mfma_f32_16x16x32_bf16 v[34:37], v[180:183], v[196:199], v[34:37]
	v_mfma_f32_16x16x32_bf16 v[26:29], v[172:175], v[204:207], v[26:29]
	v_mfma_f32_16x16x32_bf16 v[18:21], v[180:183], v[204:207], v[18:21]
	v_mfma_f32_16x16x32_bf16 v[10:13], v[172:175], v[212:215], v[10:13]
	v_mfma_f32_16x16x32_bf16 v[2:5], v[180:183], v[212:215], v[2:5]
	v_mfma_f32_16x16x32_bf16 v[58:61], v[176:179], v[192:195], v[58:61]
	v_mfma_f32_16x16x32_bf16 v[50:53], v[184:187], v[192:195], v[50:53]
	v_mfma_f32_16x16x32_bf16 v[42:45], v[176:179], v[200:203], v[42:45]
	v_mfma_f32_16x16x32_bf16 v[34:37], v[184:187], v[200:203], v[34:37]
	v_mfma_f32_16x16x32_bf16 v[26:29], v[176:179], v[208:211], v[26:29]
	v_mfma_f32_16x16x32_bf16 v[18:21], v[184:187], v[208:211], v[18:21]
	v_mfma_f32_16x16x32_bf16 v[10:13], v[176:179], v[216:219], v[10:13]
	v_mfma_f32_16x16x32_bf16 v[2:5], v[184:187], v[216:219], v[2:5]
	s_barrier
	s_setprio 0
	s_add_i32 s50, s50, 2
	s_add_u32 s24, s24, 0x100
	s_addc_u32 s25, s25, 0
	s_add_u32 s48, s48, 0x100
	s_addc_u32 s49, s49, 0
	s_cmp_gt_u32 s50, 29
	s_cbranch_scc0 .LBB0_1448
	s_and_b64 vcc, exec, s[8:9]
	s_cbranch_vccz .LBB0_1451
	s_barrier

; #define PG8_STAGE(bufoff, gbase, voff) do { _Pragma("unroll") for (int _i = 0; _i < 2; ++_i) \
;         __builtin_amdgcn_global_load_lds((const unsigned*)((const char*)(gbase) + (voff)[_i]), (PG8_LAS unsigned*)(lds + (bufoff) + ldsw + _i * 8192), 16, 0, 0); } while (0)
; #define PG8_WAIT_V(n) asm volatile("s_waitcnt vmcnt(" #n ")" ::: "memory")
; #define PG8_WAIT_L(n) asm volatile("s_waitcnt lgkmcnt(" #n ")" ::: "memory")
; #define PG8_BAR __builtin_amdgcn_s_barrier()
; #define PG8_SCHED __builtin_amdgcn_sched_barrier(0)
;     __device__ __forceinline__ int nt(const pg8::Unit& u) const { return u.kind == 0 ? ntiles : q_nt(u.kind - 1); }
; template <class Epi, class Sched, bool ALIGN_EPI = true, bool SP2 = true>
; __device__ __forceinline__ void gemm_phase(PG8_LAS unsigned char* lds, const int K  , const Sched& S, const Epi& E) {
;     ...
;             const bool last = (t == nt - 2);
;             const char* a1 = cA + (size_t)(t + 1) * kstep;
;             const char* a2 = last ? nA : cA + (size_t)(t + 2) * kstep; const char* b2 = last ? nB : cB + (size_t)(t + 2) * kstep;
;             const char* a3 = a2 + kstep; const char* b3 = b2 + kstep;
;             if constexpr (SP2) {
;             PG8_LDB(B0, 0, 0); PG8_LDB(B1, 0, 1); PG8_SCHED; PG8_LDA(At, 0, 0); PG8_STAGE(PG8_SA(1, 1), a1 + hstep, voffA);
;             PG8_WAIT_V(8); PG8_WAIT_L(0); PG8_BAR; PG8_MMA(0, 0, At, B0); PG8_MMA(0, 1, At, B1); PG8_BAR; PG8_SCHED;
;             PG8_LDA(At, 0, 1); PG8_STAGE(PG8_SB(0, 0), b2, voffB); PG8_STAGE(PG8_SB(0, 1), b2 + hstep, voffB); PG8_STAGE(PG8_SA(0, 0), a2, voffA);
;             PG8_WAIT_V(8); PG8_WAIT_L(0); PG8_BAR; PG8_MMA(1, 0, At, B0); PG8_MMA(1, 1, At, B1); PG8_BAR; PG8_SCHED;
.LBB0_1695:
	ds_read_b128 v[18:21], v233
	ds_read_b128 v[22:25], v233 offset:1024
	ds_read_b128 v[26:29], v233 offset:2048
	ds_read_b128 v[30:33], v233 offset:3072
	ds_read_b128 v[2:5], v234
	ds_read_b128 v[6:9], v234 offset:1024
	ds_read_b128 v[10:13], v234 offset:2048
	ds_read_b128 v[14:17], v234 offset:3072
	s_add_i32 s74, s24, 2
	s_add_u32 s22, s20, 0xfff50080
	s_addc_u32 s23, s21, -1
	s_cmp_eq_u32 s71, s24
	s_cselect_b32 s24, s16, s22
	s_cselect_b32 s25, s17, s23
	s_cselect_b32 s23, s19, s73
	s_cselect_b32 s22, s18, s72
	v_lshl_add_u64 v[186:187], s[20:21], 0, v[198:199]
	s_add_i32 m0, s28, 0xc000
	ds_read_b128 v[162:165], v235
	ds_read_b128 v[166:169], v235 offset:1024
	ds_read_b128 v[170:173], v235 offset:2048
	ds_read_b128 v[174:177], v235 offset:3072
	ds_read_b128 v[178:181], v235 offset:4096
	ds_read_b128 v[182:185], v235 offset:5120
	ds_read_b128 v[206:209], v235 offset:6144
	ds_read_b128 v[210:213], v235 offset:7168
	global_load_lds_dwordx4 v[186:187], off
	v_lshl_add_u64 v[186:187], s[20:21], 0, v[200:201]
	s_add_i32 m0, s28, 0xe000
	s_nop 0
	global_load_lds_dwordx4 v[186:187], off
	s_waitcnt vmcnt(8)
	s_waitcnt lgkmcnt(0)
	s_setprio 1
	s_barrier
	v_mfma_scale_f32_16x16x128_f8f6f4 v[158:161], v[18:25], v[162:169], v[158:161], v229, v229 op_sel_hi:[0,0,0]
	v_mfma_scale_f32_16x16x128_f8f6f4 v[154:157], v[26:33], v[162:169], v[154:157], v229, v229 op_sel_hi:[0,0,0]
	v_mfma_scale_f32_16x16x128_f8f6f4 v[150:153], v[18:25], v[170:177], v[150:153], v229, v229 op_sel_hi:[0,0,0]
	v_mfma_scale_f32_16x16x128_f8f6f4 v[142:145], v[26:33], v[170:177], v[142:145], v229, v229 op_sel_hi:[0,0,0]
	v_mfma_scale_f32_16x16x128_f8f6f4 v[134:137], v[18:25], v[178:185], v[134:137], v229, v229 op_sel_hi:[0,0,0]
	v_mfma_scale_f32_16x16x128_f8f6f4 v[126:129], v[26:33], v[178:185], v[126:129], v229, v229 op_sel_hi:[0,0,0]
	v_mfma_scale_f32_16x16x128_f8f6f4 v[118:121], v[18:25], v[206:213], v[118:121], v229, v229 op_sel_hi:[0,0,0]
	v_mfma_scale_f32_16x16x128_f8f6f4 v[110:113], v[26:33], v[206:213], v[110:113], v229, v229 op_sel_hi:[0,0,0]
	v_mfma_scale_f32_16x16x128_f8f6f4 v[146:149], v[2:9], v[162:169], v[146:149], v229, v229 op_sel_hi:[0,0,0]
	v_mfma_scale_f32_16x16x128_f8f6f4 v[138:141], v[10:17], v[162:169], v[138:141], v229, v229 op_sel_hi:[0,0,0]
	v_mfma_scale_f32_16x16x128_f8f6f4 v[130:133], v[2:9], v[170:177], v[130:133], v229, v229 op_sel_hi:[0,0,0]
	v_mfma_scale_f32_16x16x128_f8f6f4 v[122:125], v[10:17], v[170:177], v[122:125], v229, v229 op_sel_hi:[0,0,0]
	v_mfma_scale_f32_16x16x128_f8f6f4 v[114:117], v[2:9], v[178:185], v[114:117], v229, v229 op_sel_hi:[0,0,0]
	v_mfma_scale_f32_16x16x128_f8f6f4 v[106:109], v[10:17], v[178:185], v[106:109], v229, v229 op_sel_hi:[0,0,0]
	v_mfma_scale_f32_16x16x128_f8f6f4 v[102:105], v[2:9], v[206:213], v[102:105], v229, v229 op_sel_hi:[0,0,0]
	v_mfma_scale_f32_16x16x128_f8f6f4 v[98:101], v[10:17], v[206:213], v[98:101], v229, v229 op_sel_hi:[0,0,0]
	s_barrier
	s_setprio 0
	s_add_i32 s75, s40, s27
	v_lshl_add_u64 v[162:163], s[22:23], 0, v[192:193]
	s_mov_b32 m0, s75
	ds_read_b128 v[170:173], v235 offset:16384
	ds_read_b128 v[174:177], v235 offset:17408
	ds_read_b128 v[178:181], v235 offset:18432
	ds_read_b128 v[182:185], v235 offset:19456
	ds_read_b128 v[206:209], v235 offset:20480
	ds_read_b128 v[210:213], v235 offset:21504
	ds_read_b128 v[214:217], v235 offset:22528
	ds_read_b128 v[218:221], v235 offset:23552
	global_load_lds_dwordx4 v[162:163], off
	s_add_i32 m0, s75, 0x2000
	s_add_u32 s78, s22, 0xb0000
	v_lshl_add_u64 v[164:165], s[22:23], 0, v[196:197]
	s_addc_u32 s79, s23, 0
	s_add_i32 s75, s41, s27
	global_load_lds_dwordx4 v[164:165], off
	v_lshl_add_u64 v[166:167], s[78:79], 0, v[192:193]
	s_mov_b32 m0, s75
	v_lshl_add_u64 v[168:169], s[24:25], 0, v[194:195]
	global_load_lds_dwordx4 v[166:167], off
	v_lshl_add_u64 v[166:167], s[78:79], 0, v[196:197]
	s_add_i32 m0, s75, 0x2000
	s_nop 0
	global_load_lds_dwordx4 v[166:167], off
	v_lshl_add_u64 v[166:167], s[24:25], 0, v[190:191]
	s_mov_b32 m0, s28
	s_nop 0
	global_load_lds_dwordx4 v[166:167], off
	s_mov_b32 m0, s29
	s_nop 0
	global_load_lds_dwordx4 v[168:169], off
	s_waitcnt vmcnt(8)
	s_waitcnt lgkmcnt(0)
	s_setprio 1
	s_barrier
	v_mfma_scale_f32_16x16x128_f8f6f4 v[94:97], v[18:25], v[170:177], v[94:97], v229, v229 op_sel_hi:[0,0,0]
	v_mfma_scale_f32_16x16x128_f8f6f4 v[90:93], v[26:33], v[170:177], v[90:93], v229, v229 op_sel_hi:[0,0,0]
	v_mfma_scale_f32_16x16x128_f8f6f4 v[86:89], v[18:25], v[178:185], v[86:89], v229, v229 op_sel_hi:[0,0,0]
	v_mfma_scale_f32_16x16x128_f8f6f4 v[78:81], v[26:33], v[178:185], v[78:81], v229, v229 op_sel_hi:[0,0,0]
	v_mfma_scale_f32_16x16x128_f8f6f4 v[70:73], v[18:25], v[206:213], v[70:73], v229, v229 op_sel_hi:[0,0,0]
	v_mfma_scale_f32_16x16x128_f8f6f4 v[62:65], v[26:33], v[206:213], v[62:65], v229, v229 op_sel_hi:[0,0,0]
	v_mfma_scale_f32_16x16x128_f8f6f4 v[54:57], v[18:25], v[214:221], v[54:57], v229, v229 op_sel_hi:[0,0,0]
	v_mfma_scale_f32_16x16x128_f8f6f4 v[46:49], v[26:33], v[214:221], v[46:49], v229, v229 op_sel_hi:[0,0,0]
	v_mfma_scale_f32_16x16x128_f8f6f4 v[82:85], v[2:9], v[170:177], v[82:85], v229, v229 op_sel_hi:[0,0,0]
	v_mfma_scale_f32_16x16x128_f8f6f4 v[74:77], v[10:17], v[170:177], v[74:77], v229, v229 op_sel_hi:[0,0,0]
	v_mfma_scale_f32_16x16x128_f8f6f4 v[66:69], v[2:9], v[178:185], v[66:69], v229, v229 op_sel_hi:[0,0,0]
	v_mfma_scale_f32_16x16x128_f8f6f4 v[58:61], v[10:17], v[178:185], v[58:61], v229, v229 op_sel_hi:[0,0,0]
	v_mfma_scale_f32_16x16x128_f8f6f4 v[50:53], v[2:9], v[206:213], v[50:53], v229, v229 op_sel_hi:[0,0,0]
	v_mfma_scale_f32_16x16x128_f8f6f4 v[42:45], v[10:17], v[206:213], v[42:45], v229, v229 op_sel_hi:[0,0,0]
	v_mfma_scale_f32_16x16x128_f8f6f4 v[38:41], v[2:9], v[214:221], v[38:41], v229, v229 op_sel_hi:[0,0,0]
	v_mfma_scale_f32_16x16x128_f8f6f4 v[34:37], v[10:17], v[214:221], v[34:37], v229, v229 op_sel_hi:[0,0,0]
	s_barrier
; #define PG8_STAGE(bufoff, gbase, voff) do { _Pragma("unroll") for (int _i = 0; _i < 2; ++_i) \
;         __builtin_amdgcn_global_load_lds((const unsigned*)((const char*)(gbase) + (voff)[_i]), (PG8_LAS unsigned*)(lds + (bufoff) + ldsw + _i * 8192), 16, 0, 0); } while (0)
; #define PG8_WAIT_V(n) asm volatile("s_waitcnt vmcnt(" #n ")" ::: "memory")
; #define PG8_WAIT_L(n) asm volatile("s_waitcnt lgkmcnt(" #n ")" ::: "memory")
; #define PG8_BAR __builtin_amdgcn_s_barrier()
; #define PG8_SCHED __builtin_amdgcn_sched_barrier(0)
; template <class Epi, class Sched, bool ALIGN_EPI = true, bool SP2 = true>
; __device__ __forceinline__ void gemm_phase(PG8_LAS unsigned char* lds, const int K  , const Sched& S, const Epi& E) {
;     ...
;             PG8_LDB(B0, 1, 0); PG8_LDB(B1, 1, 1); PG8_SCHED; PG8_LDA(At, 1, 0); PG8_STAGE(PG8_SA(0, 1), a2 + hstep, voffA);
;             PG8_WAIT_V(8); PG8_WAIT_L(0); PG8_BAR; PG8_MMA(0, 0, At, B0); PG8_MMA(0, 1, At, B1); PG8_BAR; PG8_SCHED;
;             PG8_LDA(At, 1, 1); PG8_STAGE(PG8_SB(1, 0), b3, voffB); PG8_STAGE(PG8_SB(1, 1), b3 + hstep, voffB); PG8_STAGE(PG8_SA(1, 0), a3, voffA);
;             PG8_WAIT_V(8); PG8_WAIT_L(0); PG8_BAR; PG8_MMA(1, 0, At, B0); PG8_MMA(1, 1, At, B1); PG8_BAR; PG8_SCHED;
;     ...
;         if constexpr (Epi::FP8) asm volatile("s_nop 15\n\ts_nop 15\n\ts_nop 15\n\ts_nop 15\n\ts_nop 15" ::: "memory");
;         if constexpr (ALIGN_EPI) { if (wr == 0) PG8_BAR; }
	s_setprio 0
	s_add_i32 s75, 0, 0x18000
	s_add_i32 s78, 0, 0x1c000
	v_add_u32_e32 v14, s75, v231
	v_add_u32_e32 v30, s78, v231
	ds_read_b128 v[2:5], v14
	ds_read_b128 v[6:9], v14 offset:1024
	ds_read_b128 v[10:13], v14 offset:2048
	ds_read_b128 v[14:17], v14 offset:3072
	ds_read_b128 v[18:21], v30
	ds_read_b128 v[22:25], v30 offset:1024
	ds_read_b128 v[26:29], v30 offset:2048
	ds_read_b128 v[30:33], v30 offset:3072
	s_add_u32 s24, s24, 0xb0000
	s_addc_u32 s25, s25, 0
	s_mov_b32 m0, s30
	v_lshl_add_u64 v[186:187], s[24:25], 0, v[190:191]
	ds_read_b128 v[170:173], v235 offset:32768
	ds_read_b128 v[174:177], v235 offset:33792
	ds_read_b128 v[178:181], v235 offset:34816
	ds_read_b128 v[182:185], v235 offset:35840
	ds_read_b128 v[206:209], v235 offset:36864
	ds_read_b128 v[210:213], v235 offset:37888
	ds_read_b128 v[214:217], v235 offset:38912
	ds_read_b128 v[218:221], v235 offset:39936
	global_load_lds_dwordx4 v[186:187], off
	v_lshl_add_u64 v[186:187], s[24:25], 0, v[194:195]
	s_mov_b32 m0, s31
	s_nop 0
	global_load_lds_dwordx4 v[186:187], off
	s_waitcnt vmcnt(8)
	s_waitcnt lgkmcnt(0)
	s_setprio 1
	s_barrier
	v_mfma_scale_f32_16x16x128_f8f6f4 v[158:161], v[2:9], v[170:177], v[158:161], v229, v229 op_sel_hi:[0,0,0]
	v_mfma_scale_f32_16x16x128_f8f6f4 v[154:157], v[10:17], v[170:177], v[154:157], v229, v229 op_sel_hi:[0,0,0]
	v_mfma_scale_f32_16x16x128_f8f6f4 v[150:153], v[2:9], v[178:185], v[150:153], v229, v229 op_sel_hi:[0,0,0]
	v_mfma_scale_f32_16x16x128_f8f6f4 v[142:145], v[10:17], v[178:185], v[142:145], v229, v229 op_sel_hi:[0,0,0]
	v_mfma_scale_f32_16x16x128_f8f6f4 v[134:137], v[2:9], v[206:213], v[134:137], v229, v229 op_sel_hi:[0,0,0]
	v_mfma_scale_f32_16x16x128_f8f6f4 v[126:129], v[10:17], v[206:213], v[126:129], v229, v229 op_sel_hi:[0,0,0]
	v_mfma_scale_f32_16x16x128_f8f6f4 v[118:121], v[2:9], v[214:221], v[118:121], v229, v229 op_sel_hi:[0,0,0]
	v_mfma_scale_f32_16x16x128_f8f6f4 v[110:113], v[10:17], v[214:221], v[110:113], v229, v229 op_sel_hi:[0,0,0]
	v_mfma_scale_f32_16x16x128_f8f6f4 v[146:149], v[18:25], v[170:177], v[146:149], v229, v229 op_sel_hi:[0,0,0]
	v_mfma_scale_f32_16x16x128_f8f6f4 v[138:141], v[26:33], v[170:177], v[138:141], v229, v229 op_sel_hi:[0,0,0]
	v_mfma_scale_f32_16x16x128_f8f6f4 v[130:133], v[18:25], v[178:185], v[130:133], v229, v229 op_sel_hi:[0,0,0]
	v_mfma_scale_f32_16x16x128_f8f6f4 v[122:125], v[26:33], v[178:185], v[122:125], v229, v229 op_sel_hi:[0,0,0]
	v_mfma_scale_f32_16x16x128_f8f6f4 v[114:117], v[18:25], v[206:213], v[114:117], v229, v229 op_sel_hi:[0,0,0]
	v_mfma_scale_f32_16x16x128_f8f6f4 v[106:109], v[26:33], v[206:213], v[106:109], v229, v229 op_sel_hi:[0,0,0]
	v_mfma_scale_f32_16x16x128_f8f6f4 v[102:105], v[18:25], v[214:221], v[102:105], v229, v229 op_sel_hi:[0,0,0]
	v_mfma_scale_f32_16x16x128_f8f6f4 v[98:101], v[26:33], v[214:221], v[98:101], v229, v229 op_sel_hi:[0,0,0]
	s_barrier
	s_setprio 0
	s_add_i32 s24, s75, s27
	v_lshl_add_u64 v[162:163], v[162:163], 0, s[10:11]
	s_mov_b32 m0, s24
	ds_read_b128 v[170:173], v235 offset:49152
	ds_read_b128 v[174:177], v235 offset:50176
	ds_read_b128 v[178:181], v235 offset:51200
	ds_read_b128 v[182:185], v235 offset:52224
	ds_read_b128 v[206:209], v235 offset:53248
	ds_read_b128 v[210:213], v235 offset:54272
	ds_read_b128 v[214:217], v235 offset:55296
	ds_read_b128 v[218:221], v235 offset:56320
	global_load_lds_dwordx4 v[162:163], off
	s_add_i32 m0, s24, 0x2000
	s_add_u32 s22, s22, 0xb0080
	v_lshl_add_u64 v[162:163], v[164:165], 0, s[10:11]
	s_addc_u32 s23, s23, 0
	s_add_i32 s24, s78, s27
	global_load_lds_dwordx4 v[162:163], off
	v_lshl_add_u64 v[162:163], s[22:23], 0, v[192:193]
	s_mov_b32 m0, s24
	s_nop 0
	global_load_lds_dwordx4 v[162:163], off
	v_lshl_add_u64 v[162:163], s[22:23], 0, v[196:197]
	s_add_i32 m0, s24, 0x2000
	s_nop 0
	global_load_lds_dwordx4 v[162:163], off
	v_lshl_add_u64 v[162:163], v[166:167], 0, s[10:11]
	s_mov_b32 m0, s36
	s_nop 0
	global_load_lds_dwordx4 v[162:163], off
	v_lshl_add_u64 v[162:163], v[168:169], 0, s[10:11]
	s_mov_b32 m0, s37
	s_nop 0
	global_load_lds_dwordx4 v[162:163], off
	s_waitcnt vmcnt(8)
	s_waitcnt lgkmcnt(0)
	s_setprio 1
	s_barrier
	v_mfma_scale_f32_16x16x128_f8f6f4 v[94:97], v[2:9], v[170:177], v[94:97], v229, v229 op_sel_hi:[0,0,0]
	v_mfma_scale_f32_16x16x128_f8f6f4 v[90:93], v[10:17], v[170:177], v[90:93], v229, v229 op_sel_hi:[0,0,0]
	v_mfma_scale_f32_16x16x128_f8f6f4 v[86:89], v[2:9], v[178:185], v[86:89], v229, v229 op_sel_hi:[0,0,0]
	v_mfma_scale_f32_16x16x128_f8f6f4 v[78:81], v[10:17], v[178:185], v[78:81], v229, v229 op_sel_hi:[0,0,0]
	v_mfma_scale_f32_16x16x128_f8f6f4 v[70:73], v[2:9], v[206:213], v[70:73], v229, v229 op_sel_hi:[0,0,0]
	v_mfma_scale_f32_16x16x128_f8f6f4 v[62:65], v[10:17], v[206:213], v[62:65], v229, v229 op_sel_hi:[0,0,0]
	v_mfma_scale_f32_16x16x128_f8f6f4 v[54:57], v[2:9], v[214:221], v[54:57], v229, v229 op_sel_hi:[0,0,0]
	v_mfma_scale_f32_16x16x128_f8f6f4 v[46:49], v[10:17], v[214:221], v[46:49], v229, v229 op_sel_hi:[0,0,0]
	v_mfma_scale_f32_16x16x128_f8f6f4 v[82:85], v[18:25], v[170:177], v[82:85], v229, v229 op_sel_hi:[0,0,0]
	v_mfma_scale_f32_16x16x128_f8f6f4 v[74:77], v[26:33], v[170:177], v[74:77], v229, v229 op_sel_hi:[0,0,0]
	v_mfma_scale_f32_16x16x128_f8f6f4 v[66:69], v[18:25], v[178:185], v[66:69], v229, v229 op_sel_hi:[0,0,0]
	v_mfma_scale_f32_16x16x128_f8f6f4 v[58:61], v[26:33], v[178:185], v[58:61], v229, v229 op_sel_hi:[0,0,0]
	v_mfma_scale_f32_16x16x128_f8f6f4 v[50:53], v[18:25], v[206:213], v[50:53], v229, v229 op_sel_hi:[0,0,0]
	v_mfma_scale_f32_16x16x128_f8f6f4 v[42:45], v[26:33], v[206:213], v[42:45], v229, v229 op_sel_hi:[0,0,0]
	v_mfma_scale_f32_16x16x128_f8f6f4 v[38:41], v[18:25], v[214:221], v[38:41], v229, v229 op_sel_hi:[0,0,0]
	v_mfma_scale_f32_16x16x128_f8f6f4 v[34:37], v[26:33], v[214:221], v[34:37], v229, v229 op_sel_hi:[0,0,0]
	s_barrier
	s_setprio 0
	s_add_u32 s20, s20, 0x100
	s_addc_u32 s21, s21, 0
	s_add_u32 s72, s72, 0x100
	s_addc_u32 s73, s73, 0
	s_cmp_ge_u32 s74, s4
	s_mov_b32 s24, s74
	s_cbranch_scc0 .LBB0_1695
	s_nop 15
	s_nop 15
	s_nop 15
	s_nop 15
	s_nop 15
	s_and_b64 vcc, exec, s[12:13]
	s_cbranch_vccz .LBB0_1698
	s_barrier

; #define PG8_STAGE(bufoff, gbase, voff) do { _Pragma("unroll") for (int _i = 0; _i < 2; ++_i) \
;         __builtin_amdgcn_global_load_lds((const unsigned*)((const char*)(gbase) + (voff)[_i]), (PG8_LAS unsigned*)(lds + (bufoff) + ldsw + _i * 8192), 16, 0, 0); } while (0)
; #define PG8_WAIT_V(n) asm volatile("s_waitcnt vmcnt(" #n ")" ::: "memory")
; #define PG8_WAIT_L(n) asm volatile("s_waitcnt lgkmcnt(" #n ")" ::: "memory")
; #define PG8_BAR __builtin_amdgcn_s_barrier()
; #define PG8_SCHED __builtin_amdgcn_sched_barrier(0)
;     __device__ __forceinline__ int nt(const pg8::Unit& u) const { return u.kind == 0 ? ntiles : q_nt(u.kind - 1); }
; template <class Epi, class Sched, bool ALIGN_EPI = true, bool SP2 = true>
; __device__ __forceinline__ void gemm_phase(PG8_LAS unsigned char* lds, const int K  , const Sched& S, const Epi& E) {
;     ...
;             const bool last = (t == nt - 2);
;             const char* a1 = cA + (size_t)(t + 1) * kstep;
;             const char* a2 = last ? nA : cA + (size_t)(t + 2) * kstep; const char* b2 = last ? nB : cB + (size_t)(t + 2) * kstep;
;             const char* a3 = a2 + kstep; const char* b3 = b2 + kstep;
;             if constexpr (SP2) {
;             PG8_LDB(B0, 0, 0); PG8_LDB(B1, 0, 1); PG8_SCHED; PG8_LDA(At, 0, 0); PG8_STAGE(PG8_SA(1, 1), a1 + hstep, voffA);
;             PG8_WAIT_V(8); PG8_WAIT_L(0); PG8_BAR; PG8_MMA(0, 0, At, B0); PG8_MMA(0, 1, At, B1); PG8_BAR; PG8_SCHED;
;             PG8_LDA(At, 0, 1); PG8_STAGE(PG8_SB(0, 0), b2, voffB); PG8_STAGE(PG8_SB(0, 1), b2 + hstep, voffB); PG8_STAGE(PG8_SA(0, 0), a2, voffA);
.LBB0_1847:
	ds_read_b128 v[130:133], v176
	ds_read_b128 v[134:137], v176 offset:1024
	ds_read_b128 v[138:141], v176 offset:2048
	ds_read_b128 v[142:145], v176 offset:3072
	ds_read_b128 v[168:171], v177
	ds_read_b128 v[184:187], v177 offset:1024
	ds_read_b128 v[188:191], v177 offset:2048
	ds_read_b128 v[192:195], v177 offset:3072
	s_add_u32 s22, s0, 0xfff80080
	s_addc_u32 s23, s1, -1
	s_cmp_eq_u32 s51, 28
	s_cselect_b32 s25, s7, s23
	s_cselect_b32 s24, s47, s22
	s_cselect_b32 s23, s11, s50
	s_cselect_b32 s22, s48, s49
	v_lshl_add_u64 v[230:231], s[0:1], 0, v[160:161]
	s_add_i32 m0, s27, 0xc000
	ds_read_b128 v[196:199], v178
	ds_read_b128 v[200:203], v178 offset:1024
	ds_read_b128 v[204:207], v178 offset:2048
	ds_read_b128 v[208:211], v178 offset:3072
	ds_read_b128 v[212:215], v178 offset:4096
	ds_read_b128 v[216:219], v178 offset:5120
	ds_read_b128 v[220:223], v178 offset:6144
	ds_read_b128 v[224:227], v178 offset:7168
	global_load_lds_dwordx4 v[230:231], off
	v_lshl_add_u64 v[230:231], s[0:1], 0, v[162:163]
	s_add_i32 m0, s27, 0xe000
	s_nop 0
	global_load_lds_dwordx4 v[230:231], off
	s_waitcnt vmcnt(8)
	s_waitcnt lgkmcnt(0)
	s_setprio 1
	s_barrier
	v_mfma_f32_16x16x32_bf16 v[126:129], v[130:133], v[196:199], v[126:129]
	v_mfma_f32_16x16x32_bf16 v[122:125], v[138:141], v[196:199], v[122:125]
	v_mfma_f32_16x16x32_bf16 v[110:113], v[130:133], v[204:207], v[110:113]
	v_mfma_f32_16x16x32_bf16 v[106:109], v[138:141], v[204:207], v[106:109]
	v_mfma_f32_16x16x32_bf16 v[94:97], v[130:133], v[212:215], v[94:97]
	v_mfma_f32_16x16x32_bf16 v[90:93], v[138:141], v[212:215], v[90:93]
	v_mfma_f32_16x16x32_bf16 v[78:81], v[130:133], v[220:223], v[78:81]
	v_mfma_f32_16x16x32_bf16 v[74:77], v[138:141], v[220:223], v[74:77]
	v_mfma_f32_16x16x32_bf16 v[126:129], v[134:137], v[200:203], v[126:129]
	v_mfma_f32_16x16x32_bf16 v[122:125], v[142:145], v[200:203], v[122:125]
	v_mfma_f32_16x16x32_bf16 v[110:113], v[134:137], v[208:211], v[110:113]
	v_mfma_f32_16x16x32_bf16 v[106:109], v[142:145], v[208:211], v[106:109]
	v_mfma_f32_16x16x32_bf16 v[94:97], v[134:137], v[216:219], v[94:97]
	v_mfma_f32_16x16x32_bf16 v[90:93], v[142:145], v[216:219], v[90:93]
	v_mfma_f32_16x16x32_bf16 v[78:81], v[134:137], v[224:227], v[78:81]
	v_mfma_f32_16x16x32_bf16 v[74:77], v[142:145], v[224:227], v[74:77]
	v_mfma_f32_16x16x32_bf16 v[118:121], v[168:171], v[196:199], v[118:121]
	v_mfma_f32_16x16x32_bf16 v[114:117], v[188:191], v[196:199], v[114:117]
	v_mfma_f32_16x16x32_bf16 v[102:105], v[168:171], v[204:207], v[102:105]
	v_mfma_f32_16x16x32_bf16 v[98:101], v[188:191], v[204:207], v[98:101]
	v_mfma_f32_16x16x32_bf16 v[86:89], v[168:171], v[212:215], v[86:89]
	v_mfma_f32_16x16x32_bf16 v[82:85], v[188:191], v[212:215], v[82:85]
	v_mfma_f32_16x16x32_bf16 v[70:73], v[168:171], v[220:223], v[70:73]
	v_mfma_f32_16x16x32_bf16 v[66:69], v[188:191], v[220:223], v[66:69]
	v_mfma_f32_16x16x32_bf16 v[118:121], v[184:187], v[200:203], v[118:121]
	v_mfma_f32_16x16x32_bf16 v[114:117], v[192:195], v[200:203], v[114:117]
	v_mfma_f32_16x16x32_bf16 v[102:105], v[184:187], v[208:211], v[102:105]
	v_mfma_f32_16x16x32_bf16 v[98:101], v[192:195], v[208:211], v[98:101]
	v_mfma_f32_16x16x32_bf16 v[86:89], v[184:187], v[216:219], v[86:89]
	v_mfma_f32_16x16x32_bf16 v[82:85], v[192:195], v[216:219], v[82:85]
	v_mfma_f32_16x16x32_bf16 v[70:73], v[184:187], v[224:227], v[70:73]
	v_mfma_f32_16x16x32_bf16 v[66:69], v[192:195], v[224:227], v[66:69]
	s_barrier
	s_setprio 0
	s_add_i32 s68, s39, s26
	v_lshl_add_u64 v[230:231], s[22:23], 0, v[150:151]
	s_mov_b32 m0, s68
	ds_read_b128 v[196:199], v178 offset:16384
	ds_read_b128 v[200:203], v178 offset:17408
	ds_read_b128 v[204:207], v178 offset:18432
	ds_read_b128 v[208:211], v178 offset:19456
	ds_read_b128 v[212:215], v178 offset:20480
	ds_read_b128 v[216:219], v178 offset:21504
	ds_read_b128 v[220:223], v178 offset:22528
	ds_read_b128 v[224:227], v178 offset:23552
	global_load_lds_dwordx4 v[230:231], off
	s_add_i32 m0, s68, 0x2000
	s_add_u32 s68, s22, 0x80000
	v_lshl_add_u64 v[232:233], s[22:23], 0, v[154:155]
	s_addc_u32 s69, s23, 0
	s_add_i32 s70, s40, s26
	global_load_lds_dwordx4 v[232:233], off
	v_lshl_add_u64 v[234:235], s[68:69], 0, v[150:151]
	s_mov_b32 m0, s70
	v_lshl_add_u64 v[236:237], s[24:25], 0, v[152:153]
	global_load_lds_dwordx4 v[234:235], off
	v_lshl_add_u64 v[234:235], s[68:69], 0, v[154:155]
	s_add_i32 m0, s70, 0x2000
	s_nop 0
	global_load_lds_dwordx4 v[234:235], off
	v_lshl_add_u64 v[234:235], s[24:25], 0, v[148:149]
	s_mov_b32 m0, s27
	s_nop 0
	global_load_lds_dwordx4 v[234:235], off
	s_mov_b32 m0, s28
	s_nop 0
	global_load_lds_dwordx4 v[236:237], off
	s_waitcnt vmcnt(8)
	s_waitcnt lgkmcnt(0)
	s_setprio 1
	s_barrier
; #define PG8_STAGE(bufoff, gbase, voff) do { _Pragma("unroll") for (int _i = 0; _i < 2; ++_i) \
;         __builtin_amdgcn_global_load_lds((const unsigned*)((const char*)(gbase) + (voff)[_i]), (PG8_LAS unsigned*)(lds + (bufoff) + ldsw + _i * 8192), 16, 0, 0); } while (0)
; #define PG8_WAIT_V(n) asm volatile("s_waitcnt vmcnt(" #n ")" ::: "memory")
; #define PG8_WAIT_L(n) asm volatile("s_waitcnt lgkmcnt(" #n ")" ::: "memory")
; #define PG8_BAR __builtin_amdgcn_s_barrier()
; #define PG8_SCHED __builtin_amdgcn_sched_barrier(0)
; template <class Epi, class Sched, bool ALIGN_EPI = true, bool SP2 = true>
; __device__ __forceinline__ void gemm_phase(PG8_LAS unsigned char* lds, const int K  , const Sched& S, const Epi& E) {
;     ...
;             PG8_WAIT_V(8); PG8_WAIT_L(0); PG8_BAR; PG8_MMA(1, 0, At, B0); PG8_MMA(1, 1, At, B1); PG8_BAR; PG8_SCHED;
;             PG8_LDB(B0, 1, 0); PG8_LDB(B1, 1, 1); PG8_SCHED; PG8_LDA(At, 1, 0); PG8_STAGE(PG8_SA(0, 1), a2 + hstep, voffA);
;             PG8_WAIT_V(8); PG8_WAIT_L(0); PG8_BAR; PG8_MMA(0, 0, At, B0); PG8_MMA(0, 1, At, B1); PG8_BAR; PG8_SCHED;
	v_mfma_f32_16x16x32_bf16 v[62:65], v[130:133], v[196:199], v[62:65]
	v_mfma_f32_16x16x32_bf16 v[58:61], v[138:141], v[196:199], v[58:61]
	v_mfma_f32_16x16x32_bf16 v[46:49], v[130:133], v[204:207], v[46:49]
	v_mfma_f32_16x16x32_bf16 v[42:45], v[138:141], v[204:207], v[42:45]
	v_mfma_f32_16x16x32_bf16 v[30:33], v[130:133], v[212:215], v[30:33]
	v_mfma_f32_16x16x32_bf16 v[26:29], v[138:141], v[212:215], v[26:29]
	v_mfma_f32_16x16x32_bf16 v[14:17], v[130:133], v[220:223], v[14:17]
	v_mfma_f32_16x16x32_bf16 v[10:13], v[138:141], v[220:223], v[10:13]
	v_mfma_f32_16x16x32_bf16 v[62:65], v[134:137], v[200:203], v[62:65]
	v_mfma_f32_16x16x32_bf16 v[58:61], v[142:145], v[200:203], v[58:61]
	v_mfma_f32_16x16x32_bf16 v[46:49], v[134:137], v[208:211], v[46:49]
	v_mfma_f32_16x16x32_bf16 v[42:45], v[142:145], v[208:211], v[42:45]
	v_mfma_f32_16x16x32_bf16 v[30:33], v[134:137], v[216:219], v[30:33]
	v_mfma_f32_16x16x32_bf16 v[26:29], v[142:145], v[216:219], v[26:29]
	v_mfma_f32_16x16x32_bf16 v[14:17], v[134:137], v[224:227], v[14:17]
	v_mfma_f32_16x16x32_bf16 v[10:13], v[142:145], v[224:227], v[10:13]
	v_mfma_f32_16x16x32_bf16 v[54:57], v[168:171], v[196:199], v[54:57]
	v_mfma_f32_16x16x32_bf16 v[50:53], v[188:191], v[196:199], v[50:53]
	v_mfma_f32_16x16x32_bf16 v[38:41], v[168:171], v[204:207], v[38:41]
	v_mfma_f32_16x16x32_bf16 v[34:37], v[188:191], v[204:207], v[34:37]
	v_mfma_f32_16x16x32_bf16 v[22:25], v[168:171], v[212:215], v[22:25]
	v_mfma_f32_16x16x32_bf16 v[18:21], v[188:191], v[212:215], v[18:21]
	v_mfma_f32_16x16x32_bf16 v[6:9], v[168:171], v[220:223], v[6:9]
	v_mfma_f32_16x16x32_bf16 v[2:5], v[188:191], v[220:223], v[2:5]
	v_mfma_f32_16x16x32_bf16 v[54:57], v[184:187], v[200:203], v[54:57]
	v_mfma_f32_16x16x32_bf16 v[50:53], v[192:195], v[200:203], v[50:53]
	v_mfma_f32_16x16x32_bf16 v[38:41], v[184:187], v[208:211], v[38:41]
	v_mfma_f32_16x16x32_bf16 v[34:37], v[192:195], v[208:211], v[34:37]
	v_mfma_f32_16x16x32_bf16 v[22:25], v[184:187], v[216:219], v[22:25]
	v_mfma_f32_16x16x32_bf16 v[18:21], v[192:195], v[216:219], v[18:21]
	v_mfma_f32_16x16x32_bf16 v[6:9], v[184:187], v[224:227], v[6:9]
	v_mfma_f32_16x16x32_bf16 v[2:5], v[192:195], v[224:227], v[2:5]
	s_barrier
	s_setprio 0
	s_add_i32 s68, 0, 0x18000
	s_add_i32 s69, 0, 0x1c000
	v_add_u32_e32 v142, s68, v172
	v_add_u32_e32 v192, s69, v172
	ds_read_b128 v[130:133], v142
	ds_read_b128 v[134:137], v142 offset:1024
	ds_read_b128 v[138:141], v142 offset:2048
	ds_read_b128 v[142:145], v142 offset:3072
	ds_read_b128 v[168:171], v192
	ds_read_b128 v[184:187], v192 offset:1024
	ds_read_b128 v[188:191], v192 offset:2048
	ds_read_b128 v[192:195], v192 offset:3072
	s_add_u32 s24, s24, 0x80000
	s_addc_u32 s25, s25, 0
	s_mov_b32 m0, s29
	v_lshl_add_u64 v[238:239], s[24:25], 0, v[148:149]
	ds_read_b128 v[196:199], v178 offset:32768
	ds_read_b128 v[200:203], v178 offset:33792
	ds_read_b128 v[204:207], v178 offset:34816
	ds_read_b128 v[208:211], v178 offset:35840
	ds_read_b128 v[212:215], v178 offset:36864
	ds_read_b128 v[216:219], v178 offset:37888
	ds_read_b128 v[220:223], v178 offset:38912
	ds_read_b128 v[224:227], v178 offset:39936
	global_load_lds_dwordx4 v[238:239], off
	v_lshl_add_u64 v[238:239], s[24:25], 0, v[152:153]
	s_mov_b32 m0, s30
	s_nop 0
	global_load_lds_dwordx4 v[238:239], off
	s_waitcnt vmcnt(8)
	s_waitcnt lgkmcnt(0)
	s_setprio 1
	s_barrier
	v_mfma_f32_16x16x32_bf16 v[126:129], v[130:133], v[196:199], v[126:129]
	v_mfma_f32_16x16x32_bf16 v[122:125], v[138:141], v[196:199], v[122:125]
	v_mfma_f32_16x16x32_bf16 v[110:113], v[130:133], v[204:207], v[110:113]
	v_mfma_f32_16x16x32_bf16 v[106:109], v[138:141], v[204:207], v[106:109]
	v_mfma_f32_16x16x32_bf16 v[94:97], v[130:133], v[212:215], v[94:97]
	v_mfma_f32_16x16x32_bf16 v[90:93], v[138:141], v[212:215], v[90:93]
	v_mfma_f32_16x16x32_bf16 v[78:81], v[130:133], v[220:223], v[78:81]
	v_mfma_f32_16x16x32_bf16 v[74:77], v[138:141], v[220:223], v[74:77]
	v_mfma_f32_16x16x32_bf16 v[126:129], v[134:137], v[200:203], v[126:129]
	v_mfma_f32_16x16x32_bf16 v[122:125], v[142:145], v[200:203], v[122:125]
	v_mfma_f32_16x16x32_bf16 v[110:113], v[134:137], v[208:211], v[110:113]
	v_mfma_f32_16x16x32_bf16 v[106:109], v[142:145], v[208:211], v[106:109]
	v_mfma_f32_16x16x32_bf16 v[94:97], v[134:137], v[216:219], v[94:97]
	v_mfma_f32_16x16x32_bf16 v[90:93], v[142:145], v[216:219], v[90:93]
	v_mfma_f32_16x16x32_bf16 v[78:81], v[134:137], v[224:227], v[78:81]
	v_mfma_f32_16x16x32_bf16 v[74:77], v[142:145], v[224:227], v[74:77]
	v_mfma_f32_16x16x32_bf16 v[118:121], v[168:171], v[196:199], v[118:121]
	v_mfma_f32_16x16x32_bf16 v[114:117], v[188:191], v[196:199], v[114:117]
	v_mfma_f32_16x16x32_bf16 v[102:105], v[168:171], v[204:207], v[102:105]
	v_mfma_f32_16x16x32_bf16 v[98:101], v[188:191], v[204:207], v[98:101]
	v_mfma_f32_16x16x32_bf16 v[86:89], v[168:171], v[212:215], v[86:89]
	v_mfma_f32_16x16x32_bf16 v[82:85], v[188:191], v[212:215], v[82:85]
	v_mfma_f32_16x16x32_bf16 v[70:73], v[168:171], v[220:223], v[70:73]
	v_mfma_f32_16x16x32_bf16 v[66:69], v[188:191], v[220:223], v[66:69]
	v_mfma_f32_16x16x32_bf16 v[118:121], v[184:187], v[200:203], v[118:121]
	v_mfma_f32_16x16x32_bf16 v[114:117], v[192:195], v[200:203], v[114:117]
	v_mfma_f32_16x16x32_bf16 v[102:105], v[184:187], v[208:211], v[102:105]
	v_mfma_f32_16x16x32_bf16 v[98:101], v[192:195], v[208:211], v[98:101]
	v_mfma_f32_16x16x32_bf16 v[86:89], v[184:187], v[216:219], v[86:89]
	v_mfma_f32_16x16x32_bf16 v[82:85], v[192:195], v[216:219], v[82:85]
	v_mfma_f32_16x16x32_bf16 v[70:73], v[184:187], v[224:227], v[70:73]
	v_mfma_f32_16x16x32_bf16 v[66:69], v[192:195], v[224:227], v[66:69]
	s_barrier
; #define PG8_STAGE(bufoff, gbase, voff) do { _Pragma("unroll") for (int _i = 0; _i < 2; ++_i) \
;         __builtin_amdgcn_global_load_lds((const unsigned*)((const char*)(gbase) + (voff)[_i]), (PG8_LAS unsigned*)(lds + (bufoff) + ldsw + _i * 8192), 16, 0, 0); } while (0)
; #define PG8_WAIT_V(n) asm volatile("s_waitcnt vmcnt(" #n ")" ::: "memory")
; #define PG8_WAIT_L(n) asm volatile("s_waitcnt lgkmcnt(" #n ")" ::: "memory")
; #define PG8_BAR __builtin_amdgcn_s_barrier()
; #define PG8_SCHED __builtin_amdgcn_sched_barrier(0)
; template <class Epi, class Sched, bool ALIGN_EPI = true, bool SP2 = true>
; __device__ __forceinline__ void gemm_phase(PG8_LAS unsigned char* lds, const int K  , const Sched& S, const Epi& E) {
;     ...
;             PG8_LDA(At, 1, 1); PG8_STAGE(PG8_SB(1, 0), b3, voffB); PG8_STAGE(PG8_SB(1, 1), b3 + hstep, voffB); PG8_STAGE(PG8_SA(1, 0), a3, voffA);
;             PG8_WAIT_V(8); PG8_WAIT_L(0); PG8_BAR; PG8_MMA(1, 0, At, B0); PG8_MMA(1, 1, At, B1); PG8_BAR; PG8_SCHED;
;     ...
;         }
;         if constexpr (Epi::FP8) asm volatile("s_nop 15\n\ts_nop 15\n\ts_nop 15\n\ts_nop 15\n\ts_nop 15" ::: "memory");
;         if constexpr (ALIGN_EPI) { if (wr == 0) PG8_BAR; }
	s_setprio 0
	s_add_i32 s24, s68, s26
	v_lshl_add_u64 v[230:231], v[230:231], 0, s[4:5]
	s_mov_b32 m0, s24
	ds_read_b128 v[196:199], v178 offset:49152
	ds_read_b128 v[200:203], v178 offset:50176
	ds_read_b128 v[204:207], v178 offset:51200
	ds_read_b128 v[208:211], v178 offset:52224
	ds_read_b128 v[212:215], v178 offset:53248
	ds_read_b128 v[216:219], v178 offset:54272
	ds_read_b128 v[220:223], v178 offset:55296
	ds_read_b128 v[224:227], v178 offset:56320
	global_load_lds_dwordx4 v[230:231], off
	s_add_i32 m0, s24, 0x2000
	s_add_u32 s22, s22, 0x80080
	v_lshl_add_u64 v[230:231], v[232:233], 0, s[4:5]
	s_addc_u32 s23, s23, 0
	s_add_i32 s24, s69, s26
	global_load_lds_dwordx4 v[230:231], off
	v_lshl_add_u64 v[230:231], s[22:23], 0, v[150:151]
	s_mov_b32 m0, s24
	s_nop 0
	global_load_lds_dwordx4 v[230:231], off
	v_lshl_add_u64 v[230:231], s[22:23], 0, v[154:155]
	s_add_i32 m0, s24, 0x2000
	s_nop 0
	global_load_lds_dwordx4 v[230:231], off
	v_lshl_add_u64 v[230:231], v[234:235], 0, s[4:5]
	s_mov_b32 m0, s35
	s_nop 0
	global_load_lds_dwordx4 v[230:231], off
	v_lshl_add_u64 v[230:231], v[236:237], 0, s[4:5]
	s_mov_b32 m0, s36
	s_nop 0
	global_load_lds_dwordx4 v[230:231], off
	s_waitcnt vmcnt(8)
	s_waitcnt lgkmcnt(0)
	s_setprio 1
	s_barrier
	v_mfma_f32_16x16x32_bf16 v[62:65], v[130:133], v[196:199], v[62:65]
	v_mfma_f32_16x16x32_bf16 v[58:61], v[138:141], v[196:199], v[58:61]
	v_mfma_f32_16x16x32_bf16 v[46:49], v[130:133], v[204:207], v[46:49]
	v_mfma_f32_16x16x32_bf16 v[42:45], v[138:141], v[204:207], v[42:45]
	v_mfma_f32_16x16x32_bf16 v[30:33], v[130:133], v[212:215], v[30:33]
	v_mfma_f32_16x16x32_bf16 v[26:29], v[138:141], v[212:215], v[26:29]
	v_mfma_f32_16x16x32_bf16 v[14:17], v[130:133], v[220:223], v[14:17]
	v_mfma_f32_16x16x32_bf16 v[10:13], v[138:141], v[220:223], v[10:13]
	v_mfma_f32_16x16x32_bf16 v[62:65], v[134:137], v[200:203], v[62:65]
	v_mfma_f32_16x16x32_bf16 v[58:61], v[142:145], v[200:203], v[58:61]
	v_mfma_f32_16x16x32_bf16 v[46:49], v[134:137], v[208:211], v[46:49]
	v_mfma_f32_16x16x32_bf16 v[42:45], v[142:145], v[208:211], v[42:45]
	v_mfma_f32_16x16x32_bf16 v[30:33], v[134:137], v[216:219], v[30:33]
	v_mfma_f32_16x16x32_bf16 v[26:29], v[142:145], v[216:219], v[26:29]
	v_mfma_f32_16x16x32_bf16 v[14:17], v[134:137], v[224:227], v[14:17]
	v_mfma_f32_16x16x32_bf16 v[10:13], v[142:145], v[224:227], v[10:13]
	v_mfma_f32_16x16x32_bf16 v[54:57], v[168:171], v[196:199], v[54:57]
	v_mfma_f32_16x16x32_bf16 v[50:53], v[188:191], v[196:199], v[50:53]
	v_mfma_f32_16x16x32_bf16 v[38:41], v[168:171], v[204:207], v[38:41]
	v_mfma_f32_16x16x32_bf16 v[34:37], v[188:191], v[204:207], v[34:37]
	v_mfma_f32_16x16x32_bf16 v[22:25], v[168:171], v[212:215], v[22:25]
	v_mfma_f32_16x16x32_bf16 v[18:21], v[188:191], v[212:215], v[18:21]
	v_mfma_f32_16x16x32_bf16 v[6:9], v[168:171], v[220:223], v[6:9]
	v_mfma_f32_16x16x32_bf16 v[2:5], v[188:191], v[220:223], v[2:5]
	v_mfma_f32_16x16x32_bf16 v[54:57], v[184:187], v[200:203], v[54:57]
	v_mfma_f32_16x16x32_bf16 v[50:53], v[192:195], v[200:203], v[50:53]
	v_mfma_f32_16x16x32_bf16 v[38:41], v[184:187], v[208:211], v[38:41]
	v_mfma_f32_16x16x32_bf16 v[34:37], v[192:195], v[208:211], v[34:37]
	v_mfma_f32_16x16x32_bf16 v[22:25], v[184:187], v[216:219], v[22:25]
	v_mfma_f32_16x16x32_bf16 v[18:21], v[192:195], v[216:219], v[18:21]
	v_mfma_f32_16x16x32_bf16 v[6:9], v[184:187], v[224:227], v[6:9]
	v_mfma_f32_16x16x32_bf16 v[2:5], v[192:195], v[224:227], v[2:5]
	s_barrier
	s_setprio 0
	s_add_i32 s51, s51, 2
	s_add_u32 s0, s0, 0x100
	s_addc_u32 s1, s1, 0
	s_add_u32 s49, s49, 0x100
	s_addc_u32 s50, s50, 0
	s_cmp_gt_u32 s51, 29
	s_cbranch_scc0 .LBB0_1847
	s_and_b64 vcc, exec, s[8:9]
	s_cbranch_vccz .LBB0_1850
	s_barrier

; #define PG8_STAGE(bufoff, gbase, voff) do { _Pragma("unroll") for (int _i = 0; _i < 2; ++_i) \
;         __builtin_amdgcn_global_load_lds((const unsigned*)((const char*)(gbase) + (voff)[_i]), (PG8_LAS unsigned*)(lds + (bufoff) + ldsw + _i * 8192), 16, 0, 0); } while (0)
; #define PG8_WAIT_V(n) asm volatile("s_waitcnt vmcnt(" #n ")" ::: "memory")
; #define PG8_WAIT_L(n) asm volatile("s_waitcnt lgkmcnt(" #n ")" ::: "memory")
; #define PG8_BAR __builtin_amdgcn_s_barrier()
; #define PG8_SCHED __builtin_amdgcn_sched_barrier(0)
;     __device__ __forceinline__ int nt(const pg8::Unit& u) const { return u.kind == 0 ? ntiles : q_nt(u.kind - 1); }
; template <class Epi, class Sched, bool ALIGN_EPI = true, bool SP2 = true>
; __device__ __forceinline__ void gemm_phase(PG8_LAS unsigned char* lds, const int K  , const Sched& S, const Epi& E) {
;     ...
;             const bool last = (t == nt - 2);
;             const char* a1 = cA + (size_t)(t + 1) * kstep;
;             const char* a2 = last ? nA : cA + (size_t)(t + 2) * kstep; const char* b2 = last ? nB : cB + (size_t)(t + 2) * kstep;
;             const char* a3 = a2 + kstep; const char* b3 = b2 + kstep;
;             if constexpr (SP2) {
;             PG8_LDB(B0, 0, 0); PG8_LDB(B1, 0, 1); PG8_SCHED; PG8_LDA(At, 0, 0); PG8_STAGE(PG8_SA(1, 1), a1 + hstep, voffA);
;             PG8_WAIT_V(8); PG8_WAIT_L(0); PG8_BAR; PG8_MMA(0, 0, At, B0); PG8_MMA(0, 1, At, B1); PG8_BAR; PG8_SCHED;
;             PG8_LDA(At, 0, 1); PG8_STAGE(PG8_SB(0, 0), b2, voffB); PG8_STAGE(PG8_SB(0, 1), b2 + hstep, voffB); PG8_STAGE(PG8_SA(0, 0), a2, voffA);
.LBB0_2296:
	ds_read_b128 v[130:133], v203
	ds_read_b128 v[134:137], v203 offset:1024
	ds_read_b128 v[138:141], v203 offset:2048
	ds_read_b128 v[142:145], v203 offset:3072
	ds_read_b128 v[146:149], v204
	ds_read_b128 v[150:153], v204 offset:1024
	ds_read_b128 v[154:157], v204 offset:2048
	ds_read_b128 v[158:161], v204 offset:3072
	s_add_u32 s22, s20, 0xfff80080
	s_addc_u32 s23, s21, -1
	s_cmp_eq_u32 s54, 28
	s_cselect_b32 s25, s13, s23
	s_cselect_b32 s24, s50, s22
	s_cselect_b32 s23, s11, s53
	s_cselect_b32 s22, s51, s52
	v_lshl_add_u64 v[198:199], s[20:21], 0, v[190:191]
	s_add_i32 m0, s19, 0xc000
	ds_read_b128 v[162:165], v205
	ds_read_b128 v[166:169], v205 offset:1024
	ds_read_b128 v[170:173], v205 offset:2048
	ds_read_b128 v[174:177], v205 offset:3072
	ds_read_b128 v[178:181], v205 offset:4096
	ds_read_b128 v[206:209], v205 offset:5120
	ds_read_b128 v[210:213], v205 offset:6144
	ds_read_b128 v[214:217], v205 offset:7168
	global_load_lds_dwordx4 v[198:199], off
	v_lshl_add_u64 v[198:199], s[20:21], 0, v[192:193]
	s_add_i32 m0, s19, 0xe000
	s_nop 0
	global_load_lds_dwordx4 v[198:199], off
	s_waitcnt vmcnt(8)
	s_waitcnt lgkmcnt(0)
	s_setprio 1
	s_barrier
	v_mfma_f32_16x16x32_bf16 v[126:129], v[130:133], v[162:165], v[126:129]
	v_mfma_f32_16x16x32_bf16 v[122:125], v[138:141], v[162:165], v[122:125]
	v_mfma_f32_16x16x32_bf16 v[114:117], v[130:133], v[170:173], v[114:117]
	v_mfma_f32_16x16x32_bf16 v[106:109], v[138:141], v[170:173], v[106:109]
	v_mfma_f32_16x16x32_bf16 v[98:101], v[130:133], v[178:181], v[98:101]
	v_mfma_f32_16x16x32_bf16 v[90:93], v[138:141], v[178:181], v[90:93]
	v_mfma_f32_16x16x32_bf16 v[82:85], v[130:133], v[210:213], v[82:85]
	v_mfma_f32_16x16x32_bf16 v[74:77], v[138:141], v[210:213], v[74:77]
	v_mfma_f32_16x16x32_bf16 v[126:129], v[134:137], v[166:169], v[126:129]
	v_mfma_f32_16x16x32_bf16 v[122:125], v[142:145], v[166:169], v[122:125]
	v_mfma_f32_16x16x32_bf16 v[114:117], v[134:137], v[174:177], v[114:117]
	v_mfma_f32_16x16x32_bf16 v[106:109], v[142:145], v[174:177], v[106:109]
	v_mfma_f32_16x16x32_bf16 v[98:101], v[134:137], v[206:209], v[98:101]
	v_mfma_f32_16x16x32_bf16 v[90:93], v[142:145], v[206:209], v[90:93]
	v_mfma_f32_16x16x32_bf16 v[82:85], v[134:137], v[214:217], v[82:85]
	v_mfma_f32_16x16x32_bf16 v[74:77], v[142:145], v[214:217], v[74:77]
	v_mfma_f32_16x16x32_bf16 v[118:121], v[146:149], v[162:165], v[118:121]
	v_mfma_f32_16x16x32_bf16 v[110:113], v[154:157], v[162:165], v[110:113]
	v_mfma_f32_16x16x32_bf16 v[102:105], v[146:149], v[170:173], v[102:105]
	v_mfma_f32_16x16x32_bf16 v[94:97], v[154:157], v[170:173], v[94:97]
	v_mfma_f32_16x16x32_bf16 v[86:89], v[146:149], v[178:181], v[86:89]
	v_mfma_f32_16x16x32_bf16 v[78:81], v[154:157], v[178:181], v[78:81]
	v_mfma_f32_16x16x32_bf16 v[70:73], v[146:149], v[210:213], v[70:73]
	v_mfma_f32_16x16x32_bf16 v[66:69], v[154:157], v[210:213], v[66:69]
	v_mfma_f32_16x16x32_bf16 v[118:121], v[150:153], v[166:169], v[118:121]
	v_mfma_f32_16x16x32_bf16 v[110:113], v[158:161], v[166:169], v[110:113]
	v_mfma_f32_16x16x32_bf16 v[102:105], v[150:153], v[174:177], v[102:105]
	v_mfma_f32_16x16x32_bf16 v[94:97], v[158:161], v[174:177], v[94:97]
	v_mfma_f32_16x16x32_bf16 v[86:89], v[150:153], v[206:209], v[86:89]
	v_mfma_f32_16x16x32_bf16 v[78:81], v[158:161], v[206:209], v[78:81]
	v_mfma_f32_16x16x32_bf16 v[70:73], v[150:153], v[214:217], v[70:73]
	v_mfma_f32_16x16x32_bf16 v[66:69], v[158:161], v[214:217], v[66:69]
	s_barrier
	s_setprio 0
	s_add_i32 s55, s42, s29
	v_lshl_add_u64 v[198:199], s[22:23], 0, v[184:185]
	s_mov_b32 m0, s55
	ds_read_b128 v[162:165], v205 offset:16384
	ds_read_b128 v[166:169], v205 offset:17408
	ds_read_b128 v[170:173], v205 offset:18432
	ds_read_b128 v[174:177], v205 offset:19456
	ds_read_b128 v[178:181], v205 offset:20480
	ds_read_b128 v[206:209], v205 offset:21504
	ds_read_b128 v[210:213], v205 offset:22528
	ds_read_b128 v[214:217], v205 offset:23552
	global_load_lds_dwordx4 v[198:199], off
	s_add_i32 m0, s55, 0x2000
	s_add_u32 s56, s22, 0x80000
	v_lshl_add_u64 v[218:219], s[22:23], 0, v[188:189]
	s_addc_u32 s57, s23, 0
	s_add_i32 s55, s43, s29
	global_load_lds_dwordx4 v[218:219], off
	v_lshl_add_u64 v[220:221], s[56:57], 0, v[184:185]
	s_mov_b32 m0, s55
	v_lshl_add_u64 v[222:223], s[24:25], 0, v[186:187]
	global_load_lds_dwordx4 v[220:221], off
	v_lshl_add_u64 v[220:221], s[56:57], 0, v[188:189]
	s_add_i32 m0, s55, 0x2000
	s_nop 0
	global_load_lds_dwordx4 v[220:221], off
	v_lshl_add_u64 v[220:221], s[24:25], 0, v[182:183]
	s_mov_b32 m0, s19
	s_nop 0
	global_load_lds_dwordx4 v[220:221], off
	s_mov_b32 m0, s30
	s_nop 0
	global_load_lds_dwordx4 v[222:223], off
	s_waitcnt vmcnt(8)
	s_waitcnt lgkmcnt(0)
	s_setprio 1
	s_barrier
; #define PG8_STAGE(bufoff, gbase, voff) do { _Pragma("unroll") for (int _i = 0; _i < 2; ++_i) \
;         __builtin_amdgcn_global_load_lds((const unsigned*)((const char*)(gbase) + (voff)[_i]), (PG8_LAS unsigned*)(lds + (bufoff) + ldsw + _i * 8192), 16, 0, 0); } while (0)
; #define PG8_WAIT_V(n) asm volatile("s_waitcnt vmcnt(" #n ")" ::: "memory")
; #define PG8_WAIT_L(n) asm volatile("s_waitcnt lgkmcnt(" #n ")" ::: "memory")
; #define PG8_BAR __builtin_amdgcn_s_barrier()
; #define PG8_SCHED __builtin_amdgcn_sched_barrier(0)
; template <class Epi, class Sched, bool ALIGN_EPI = true, bool SP2 = true>
; __device__ __forceinline__ void gemm_phase(PG8_LAS unsigned char* lds, const int K  , const Sched& S, const Epi& E) {
;     ...
;             PG8_WAIT_V(8); PG8_WAIT_L(0); PG8_BAR; PG8_MMA(1, 0, At, B0); PG8_MMA(1, 1, At, B1); PG8_BAR; PG8_SCHED;
;             PG8_LDB(B0, 1, 0); PG8_LDB(B1, 1, 1); PG8_SCHED; PG8_LDA(At, 1, 0); PG8_STAGE(PG8_SA(0, 1), a2 + hstep, voffA);
;             PG8_WAIT_V(8); PG8_WAIT_L(0); PG8_BAR; PG8_MMA(0, 0, At, B0); PG8_MMA(0, 1, At, B1); PG8_BAR; PG8_SCHED;
	v_mfma_f32_16x16x32_bf16 v[62:65], v[130:133], v[162:165], v[62:65]
	v_mfma_f32_16x16x32_bf16 v[58:61], v[138:141], v[162:165], v[58:61]
	v_mfma_f32_16x16x32_bf16 v[50:53], v[130:133], v[170:173], v[50:53]
	v_mfma_f32_16x16x32_bf16 v[42:45], v[138:141], v[170:173], v[42:45]
	v_mfma_f32_16x16x32_bf16 v[34:37], v[130:133], v[178:181], v[34:37]
	v_mfma_f32_16x16x32_bf16 v[26:29], v[138:141], v[178:181], v[26:29]
	v_mfma_f32_16x16x32_bf16 v[18:21], v[130:133], v[210:213], v[18:21]
	v_mfma_f32_16x16x32_bf16 v[10:13], v[138:141], v[210:213], v[10:13]
	v_mfma_f32_16x16x32_bf16 v[62:65], v[134:137], v[166:169], v[62:65]
	v_mfma_f32_16x16x32_bf16 v[58:61], v[142:145], v[166:169], v[58:61]
	v_mfma_f32_16x16x32_bf16 v[50:53], v[134:137], v[174:177], v[50:53]
	v_mfma_f32_16x16x32_bf16 v[42:45], v[142:145], v[174:177], v[42:45]
	v_mfma_f32_16x16x32_bf16 v[34:37], v[134:137], v[206:209], v[34:37]
	v_mfma_f32_16x16x32_bf16 v[26:29], v[142:145], v[206:209], v[26:29]
	v_mfma_f32_16x16x32_bf16 v[18:21], v[134:137], v[214:217], v[18:21]
	v_mfma_f32_16x16x32_bf16 v[10:13], v[142:145], v[214:217], v[10:13]
	v_mfma_f32_16x16x32_bf16 v[54:57], v[146:149], v[162:165], v[54:57]
	v_mfma_f32_16x16x32_bf16 v[46:49], v[154:157], v[162:165], v[46:49]
	v_mfma_f32_16x16x32_bf16 v[38:41], v[146:149], v[170:173], v[38:41]
	v_mfma_f32_16x16x32_bf16 v[30:33], v[154:157], v[170:173], v[30:33]
	v_mfma_f32_16x16x32_bf16 v[22:25], v[146:149], v[178:181], v[22:25]
	v_mfma_f32_16x16x32_bf16 v[14:17], v[154:157], v[178:181], v[14:17]
	v_mfma_f32_16x16x32_bf16 v[6:9], v[146:149], v[210:213], v[6:9]
	v_mfma_f32_16x16x32_bf16 v[2:5], v[154:157], v[210:213], v[2:5]
	v_mfma_f32_16x16x32_bf16 v[54:57], v[150:153], v[166:169], v[54:57]
	v_mfma_f32_16x16x32_bf16 v[46:49], v[158:161], v[166:169], v[46:49]
	v_mfma_f32_16x16x32_bf16 v[38:41], v[150:153], v[174:177], v[38:41]
	v_mfma_f32_16x16x32_bf16 v[30:33], v[158:161], v[174:177], v[30:33]
	v_mfma_f32_16x16x32_bf16 v[22:25], v[150:153], v[206:209], v[22:25]
	v_mfma_f32_16x16x32_bf16 v[14:17], v[158:161], v[206:209], v[14:17]
	v_mfma_f32_16x16x32_bf16 v[6:9], v[150:153], v[214:217], v[6:9]
	v_mfma_f32_16x16x32_bf16 v[2:5], v[158:161], v[214:217], v[2:5]
	s_barrier
	s_setprio 0
	s_add_i32 s55, 0, 0x18000
	s_add_i32 s56, 0, 0x1c000
	v_add_u32_e32 v142, s55, v201
	v_add_u32_e32 v158, s56, v201
	ds_read_b128 v[130:133], v142
	ds_read_b128 v[134:137], v142 offset:1024
	ds_read_b128 v[138:141], v142 offset:2048
	ds_read_b128 v[142:145], v142 offset:3072
	ds_read_b128 v[146:149], v158
	ds_read_b128 v[150:153], v158 offset:1024
	ds_read_b128 v[154:157], v158 offset:2048
	ds_read_b128 v[158:161], v158 offset:3072
	s_add_u32 s24, s24, 0x80000
	s_addc_u32 s25, s25, 0
	s_mov_b32 m0, s31
	v_lshl_add_u64 v[224:225], s[24:25], 0, v[182:183]
	ds_read_b128 v[162:165], v205 offset:32768
	ds_read_b128 v[166:169], v205 offset:33792
	ds_read_b128 v[170:173], v205 offset:34816
	ds_read_b128 v[174:177], v205 offset:35840
	ds_read_b128 v[178:181], v205 offset:36864
	ds_read_b128 v[206:209], v205 offset:37888
	ds_read_b128 v[210:213], v205 offset:38912
	ds_read_b128 v[214:217], v205 offset:39936
	global_load_lds_dwordx4 v[224:225], off
	v_lshl_add_u64 v[224:225], s[24:25], 0, v[186:187]
	s_mov_b32 m0, s33
	s_nop 0
	global_load_lds_dwordx4 v[224:225], off
	s_waitcnt vmcnt(8)
	s_waitcnt lgkmcnt(0)
	s_setprio 1
	s_barrier
	v_mfma_f32_16x16x32_bf16 v[126:129], v[130:133], v[162:165], v[126:129]
	v_mfma_f32_16x16x32_bf16 v[122:125], v[138:141], v[162:165], v[122:125]
	v_mfma_f32_16x16x32_bf16 v[114:117], v[130:133], v[170:173], v[114:117]
	v_mfma_f32_16x16x32_bf16 v[106:109], v[138:141], v[170:173], v[106:109]
	v_mfma_f32_16x16x32_bf16 v[98:101], v[130:133], v[178:181], v[98:101]
	v_mfma_f32_16x16x32_bf16 v[90:93], v[138:141], v[178:181], v[90:93]
	v_mfma_f32_16x16x32_bf16 v[82:85], v[130:133], v[210:213], v[82:85]
	v_mfma_f32_16x16x32_bf16 v[74:77], v[138:141], v[210:213], v[74:77]
	v_mfma_f32_16x16x32_bf16 v[126:129], v[134:137], v[166:169], v[126:129]
	v_mfma_f32_16x16x32_bf16 v[122:125], v[142:145], v[166:169], v[122:125]
	v_mfma_f32_16x16x32_bf16 v[114:117], v[134:137], v[174:177], v[114:117]
	v_mfma_f32_16x16x32_bf16 v[106:109], v[142:145], v[174:177], v[106:109]
	v_mfma_f32_16x16x32_bf16 v[98:101], v[134:137], v[206:209], v[98:101]
	v_mfma_f32_16x16x32_bf16 v[90:93], v[142:145], v[206:209], v[90:93]
	v_mfma_f32_16x16x32_bf16 v[82:85], v[134:137], v[214:217], v[82:85]
	v_mfma_f32_16x16x32_bf16 v[74:77], v[142:145], v[214:217], v[74:77]
	v_mfma_f32_16x16x32_bf16 v[118:121], v[146:149], v[162:165], v[118:121]
	v_mfma_f32_16x16x32_bf16 v[110:113], v[154:157], v[162:165], v[110:113]
	v_mfma_f32_16x16x32_bf16 v[102:105], v[146:149], v[170:173], v[102:105]
	v_mfma_f32_16x16x32_bf16 v[94:97], v[154:157], v[170:173], v[94:97]
	v_mfma_f32_16x16x32_bf16 v[86:89], v[146:149], v[178:181], v[86:89]
	v_mfma_f32_16x16x32_bf16 v[78:81], v[154:157], v[178:181], v[78:81]
	v_mfma_f32_16x16x32_bf16 v[70:73], v[146:149], v[210:213], v[70:73]
	v_mfma_f32_16x16x32_bf16 v[66:69], v[154:157], v[210:213], v[66:69]
	v_mfma_f32_16x16x32_bf16 v[118:121], v[150:153], v[166:169], v[118:121]
	v_mfma_f32_16x16x32_bf16 v[110:113], v[158:161], v[166:169], v[110:113]
	v_mfma_f32_16x16x32_bf16 v[102:105], v[150:153], v[174:177], v[102:105]
	v_mfma_f32_16x16x32_bf16 v[94:97], v[158:161], v[174:177], v[94:97]
	v_mfma_f32_16x16x32_bf16 v[86:89], v[150:153], v[206:209], v[86:89]
	v_mfma_f32_16x16x32_bf16 v[78:81], v[158:161], v[206:209], v[78:81]
	v_mfma_f32_16x16x32_bf16 v[70:73], v[150:153], v[214:217], v[70:73]
	v_mfma_f32_16x16x32_bf16 v[66:69], v[158:161], v[214:217], v[66:69]
	s_barrier
; #define PG8_STAGE(bufoff, gbase, voff) do { _Pragma("unroll") for (int _i = 0; _i < 2; ++_i) \
;         __builtin_amdgcn_global_load_lds((const unsigned*)((const char*)(gbase) + (voff)[_i]), (PG8_LAS unsigned*)(lds + (bufoff) + ldsw + _i * 8192), 16, 0, 0); } while (0)
; #define PG8_WAIT_V(n) asm volatile("s_waitcnt vmcnt(" #n ")" ::: "memory")
; #define PG8_WAIT_L(n) asm volatile("s_waitcnt lgkmcnt(" #n ")" ::: "memory")
; #define PG8_BAR __builtin_amdgcn_s_barrier()
; #define PG8_SCHED __builtin_amdgcn_sched_barrier(0)
; template <class Epi, class Sched, bool ALIGN_EPI = true, bool SP2 = true>
; __device__ __forceinline__ void gemm_phase(PG8_LAS unsigned char* lds, const int K  , const Sched& S, const Epi& E) {
;     ...
;             PG8_LDA(At, 1, 1); PG8_STAGE(PG8_SB(1, 0), b3, voffB); PG8_STAGE(PG8_SB(1, 1), b3 + hstep, voffB); PG8_STAGE(PG8_SA(1, 0), a3, voffA);
;             PG8_WAIT_V(8); PG8_WAIT_L(0); PG8_BAR; PG8_MMA(1, 0, At, B0); PG8_MMA(1, 1, At, B1); PG8_BAR; PG8_SCHED;
	s_setprio 0
	s_add_i32 s24, s55, s29
	v_lshl_add_u64 v[198:199], v[198:199], 0, s[6:7]
	s_mov_b32 m0, s24
	ds_read_b128 v[162:165], v205 offset:49152
	ds_read_b128 v[166:169], v205 offset:50176
	ds_read_b128 v[170:173], v205 offset:51200
	ds_read_b128 v[174:177], v205 offset:52224
	ds_read_b128 v[178:181], v205 offset:53248
	ds_read_b128 v[206:209], v205 offset:54272
	ds_read_b128 v[210:213], v205 offset:55296
	ds_read_b128 v[214:217], v205 offset:56320
	global_load_lds_dwordx4 v[198:199], off
	s_add_i32 m0, s24, 0x2000
	s_add_u32 s22, s22, 0x80080
	v_lshl_add_u64 v[198:199], v[218:219], 0, s[6:7]
	s_addc_u32 s23, s23, 0
	s_add_i32 s24, s56, s29
	global_load_lds_dwordx4 v[198:199], off
	v_lshl_add_u64 v[198:199], s[22:23], 0, v[184:185]
	s_mov_b32 m0, s24
	s_nop 0
	global_load_lds_dwordx4 v[198:199], off
	v_lshl_add_u64 v[198:199], s[22:23], 0, v[188:189]
	s_add_i32 m0, s24, 0x2000
	s_nop 0
	global_load_lds_dwordx4 v[198:199], off
	v_lshl_add_u64 v[198:199], v[220:221], 0, s[6:7]
	s_mov_b32 m0, s38
	s_nop 0
	global_load_lds_dwordx4 v[198:199], off
	v_lshl_add_u64 v[198:199], v[222:223], 0, s[6:7]
	s_mov_b32 m0, s39
	s_nop 0
	global_load_lds_dwordx4 v[198:199], off
	s_waitcnt vmcnt(8)
	s_waitcnt lgkmcnt(0)
	s_setprio 1
	s_barrier
	v_mfma_f32_16x16x32_bf16 v[62:65], v[130:133], v[162:165], v[62:65]
	v_mfma_f32_16x16x32_bf16 v[58:61], v[138:141], v[162:165], v[58:61]
	v_mfma_f32_16x16x32_bf16 v[50:53], v[130:133], v[170:173], v[50:53]
	v_mfma_f32_16x16x32_bf16 v[42:45], v[138:141], v[170:173], v[42:45]
	v_mfma_f32_16x16x32_bf16 v[34:37], v[130:133], v[178:181], v[34:37]
	v_mfma_f32_16x16x32_bf16 v[26:29], v[138:141], v[178:181], v[26:29]
	v_mfma_f32_16x16x32_bf16 v[18:21], v[130:133], v[210:213], v[18:21]
	v_mfma_f32_16x16x32_bf16 v[10:13], v[138:141], v[210:213], v[10:13]
	v_mfma_f32_16x16x32_bf16 v[62:65], v[134:137], v[166:169], v[62:65]
	v_mfma_f32_16x16x32_bf16 v[58:61], v[142:145], v[166:169], v[58:61]
	v_mfma_f32_16x16x32_bf16 v[50:53], v[134:137], v[174:177], v[50:53]
	v_mfma_f32_16x16x32_bf16 v[42:45], v[142:145], v[174:177], v[42:45]
	v_mfma_f32_16x16x32_bf16 v[34:37], v[134:137], v[206:209], v[34:37]
	v_mfma_f32_16x16x32_bf16 v[26:29], v[142:145], v[206:209], v[26:29]
	v_mfma_f32_16x16x32_bf16 v[18:21], v[134:137], v[214:217], v[18:21]
	v_mfma_f32_16x16x32_bf16 v[10:13], v[142:145], v[214:217], v[10:13]
	v_mfma_f32_16x16x32_bf16 v[54:57], v[146:149], v[162:165], v[54:57]
	v_mfma_f32_16x16x32_bf16 v[46:49], v[154:157], v[162:165], v[46:49]
	v_mfma_f32_16x16x32_bf16 v[38:41], v[146:149], v[170:173], v[38:41]
	v_mfma_f32_16x16x32_bf16 v[30:33], v[154:157], v[170:173], v[30:33]
	v_mfma_f32_16x16x32_bf16 v[22:25], v[146:149], v[178:181], v[22:25]
	v_mfma_f32_16x16x32_bf16 v[14:17], v[154:157], v[178:181], v[14:17]
	v_mfma_f32_16x16x32_bf16 v[6:9], v[146:149], v[210:213], v[6:9]
	v_mfma_f32_16x16x32_bf16 v[2:5], v[154:157], v[210:213], v[2:5]
	v_mfma_f32_16x16x32_bf16 v[54:57], v[150:153], v[166:169], v[54:57]
	v_mfma_f32_16x16x32_bf16 v[46:49], v[158:161], v[166:169], v[46:49]
	v_mfma_f32_16x16x32_bf16 v[38:41], v[150:153], v[174:177], v[38:41]
	v_mfma_f32_16x16x32_bf16 v[30:33], v[158:161], v[174:177], v[30:33]
	v_mfma_f32_16x16x32_bf16 v[22:25], v[150:153], v[206:209], v[22:25]
	v_mfma_f32_16x16x32_bf16 v[14:17], v[158:161], v[206:209], v[14:17]
	v_mfma_f32_16x16x32_bf16 v[6:9], v[150:153], v[214:217], v[6:9]
	v_mfma_f32_16x16x32_bf16 v[2:5], v[158:161], v[214:217], v[2:5]
	s_barrier
	s_setprio 0
	s_add_i32 s54, s54, 2
	s_add_u32 s20, s20, 0x100
	s_addc_u32 s21, s21, 0
	s_add_u32 s52, s52, 0x100
	s_addc_u32 s53, s53, 0
	s_cmp_gt_u32 s54, 29
	s_cbranch_scc0 .LBB0_2296
	s_and_b64 vcc, exec, s[8:9]
	s_cbranch_vccz .LBB0_2299
	s_barrier

; #define PG8_STAGE(bufoff, gbase, voff) do { _Pragma("unroll") for (int _i = 0; _i < 2; ++_i) \
;         __builtin_amdgcn_global_load_lds((const unsigned*)((const char*)(gbase) + (voff)[_i]), (PG8_LAS unsigned*)(lds + (bufoff) + ldsw + _i * 8192), 16, 0, 0); } while (0)
; #define PG8_WAIT_V(n) asm volatile("s_waitcnt vmcnt(" #n ")" ::: "memory")
; #define PG8_WAIT_L(n) asm volatile("s_waitcnt lgkmcnt(" #n ")" ::: "memory")
; #define PG8_BAR __builtin_amdgcn_s_barrier()
; #define PG8_SCHED __builtin_amdgcn_sched_barrier(0)
;     __device__ __forceinline__ int nt(const pg8::Unit& u) const { return u.kind == 0 ? ntiles : q_nt(u.kind - 1); }
; template <class Epi, class Sched, bool ALIGN_EPI = true, bool SP2 = true>
; __device__ __forceinline__ void gemm_phase(PG8_LAS unsigned char* lds, const int K  , const Sched& S, const Epi& E) {
;     ...
;             const bool last = (t == nt - 2);
;             const char* a1 = cA + (size_t)(t + 1) * kstep;
;             const char* a2 = last ? nA : cA + (size_t)(t + 2) * kstep; const char* b2 = last ? nB : cB + (size_t)(t + 2) * kstep;
;             const char* a3 = a2 + kstep; const char* b3 = b2 + kstep;
;             if constexpr (SP2) {
;             PG8_LDB(B0, 0, 0); PG8_LDB(B1, 0, 1); PG8_SCHED; PG8_LDA(At, 0, 0); PG8_STAGE(PG8_SA(1, 1), a1 + hstep, voffA);
;             PG8_WAIT_V(8); PG8_WAIT_L(0); PG8_BAR; PG8_MMA(0, 0, At, B0); PG8_MMA(0, 1, At, B1); PG8_BAR; PG8_SCHED;
;             PG8_LDA(At, 0, 1); PG8_STAGE(PG8_SB(0, 0), b2, voffB); PG8_STAGE(PG8_SB(0, 1), b2 + hstep, voffB); PG8_STAGE(PG8_SA(0, 0), a2, voffA);
.LBB0_2433:
	ds_read_b128 v[146:149], v152
	ds_read_b128 v[158:161], v152 offset:1024
	ds_read_b128 v[162:165], v152 offset:2048
	ds_read_b128 v[166:169], v152 offset:3072
	ds_read_b128 v[170:173], v153
	ds_read_b128 v[174:177], v153 offset:1024
	ds_read_b128 v[178:181], v153 offset:2048
	ds_read_b128 v[182:185], v153 offset:3072
	s_add_u32 s22, s20, 0xfff80080
	s_addc_u32 s23, s21, -1
	s_cmp_eq_u32 s48, 28
	s_cselect_b32 s25, s13, s23
	s_cselect_b32 s24, s44, s22
	s_cselect_b32 s23, s11, s47
	s_cselect_b32 s22, s45, s46
	v_lshl_add_u64 v[218:219], s[20:21], 0, v[138:139]
	s_add_i32 m0, s19, 0xc000
	ds_read_b128 v[186:189], v154
	ds_read_b128 v[190:193], v154 offset:1024
	ds_read_b128 v[194:197], v154 offset:2048
	ds_read_b128 v[198:201], v154 offset:3072
	ds_read_b128 v[202:205], v154 offset:4096
	ds_read_b128 v[206:209], v154 offset:5120
	ds_read_b128 v[210:213], v154 offset:6144
	ds_read_b128 v[214:217], v154 offset:7168
	global_load_lds_dwordx4 v[218:219], off
	v_lshl_add_u64 v[218:219], s[20:21], 0, v[140:141]
	s_add_i32 m0, s19, 0xe000
	s_nop 0
	global_load_lds_dwordx4 v[218:219], off
	s_waitcnt vmcnt(8)
	s_waitcnt lgkmcnt(0)
	s_setprio 1
	s_barrier
	v_mfma_f32_16x16x32_bf16 v[126:129], v[146:149], v[186:189], v[126:129]
	v_mfma_f32_16x16x32_bf16 v[118:121], v[162:165], v[186:189], v[118:121]
	v_mfma_f32_16x16x32_bf16 v[110:113], v[146:149], v[194:197], v[110:113]
	v_mfma_f32_16x16x32_bf16 v[102:105], v[162:165], v[194:197], v[102:105]
	v_mfma_f32_16x16x32_bf16 v[94:97], v[146:149], v[202:205], v[94:97]
	v_mfma_f32_16x16x32_bf16 v[86:89], v[162:165], v[202:205], v[86:89]
	v_mfma_f32_16x16x32_bf16 v[78:81], v[146:149], v[210:213], v[78:81]
	v_mfma_f32_16x16x32_bf16 v[70:73], v[162:165], v[210:213], v[70:73]
	v_mfma_f32_16x16x32_bf16 v[126:129], v[158:161], v[190:193], v[126:129]
	v_mfma_f32_16x16x32_bf16 v[118:121], v[166:169], v[190:193], v[118:121]
	v_mfma_f32_16x16x32_bf16 v[110:113], v[158:161], v[198:201], v[110:113]
	v_mfma_f32_16x16x32_bf16 v[102:105], v[166:169], v[198:201], v[102:105]
	v_mfma_f32_16x16x32_bf16 v[94:97], v[158:161], v[206:209], v[94:97]
	v_mfma_f32_16x16x32_bf16 v[86:89], v[166:169], v[206:209], v[86:89]
	v_mfma_f32_16x16x32_bf16 v[78:81], v[158:161], v[214:217], v[78:81]
	v_mfma_f32_16x16x32_bf16 v[70:73], v[166:169], v[214:217], v[70:73]
	v_mfma_f32_16x16x32_bf16 v[122:125], v[170:173], v[186:189], v[122:125]
	v_mfma_f32_16x16x32_bf16 v[114:117], v[178:181], v[186:189], v[114:117]
	v_mfma_f32_16x16x32_bf16 v[106:109], v[170:173], v[194:197], v[106:109]
	v_mfma_f32_16x16x32_bf16 v[98:101], v[178:181], v[194:197], v[98:101]
	v_mfma_f32_16x16x32_bf16 v[90:93], v[170:173], v[202:205], v[90:93]
	v_mfma_f32_16x16x32_bf16 v[82:85], v[178:181], v[202:205], v[82:85]
	v_mfma_f32_16x16x32_bf16 v[74:77], v[170:173], v[210:213], v[74:77]
	v_mfma_f32_16x16x32_bf16 v[66:69], v[178:181], v[210:213], v[66:69]
	v_mfma_f32_16x16x32_bf16 v[122:125], v[174:177], v[190:193], v[122:125]
	v_mfma_f32_16x16x32_bf16 v[114:117], v[182:185], v[190:193], v[114:117]
	v_mfma_f32_16x16x32_bf16 v[106:109], v[174:177], v[198:201], v[106:109]
	v_mfma_f32_16x16x32_bf16 v[98:101], v[182:185], v[198:201], v[98:101]
	v_mfma_f32_16x16x32_bf16 v[90:93], v[174:177], v[206:209], v[90:93]
	v_mfma_f32_16x16x32_bf16 v[82:85], v[182:185], v[206:209], v[82:85]
	v_mfma_f32_16x16x32_bf16 v[74:77], v[174:177], v[214:217], v[74:77]
	v_mfma_f32_16x16x32_bf16 v[66:69], v[182:185], v[214:217], v[66:69]
	s_barrier
	s_setprio 0
	s_add_i32 s49, s39, s28
	v_lshl_add_u64 v[218:219], s[22:23], 0, v[134:135]
	s_mov_b32 m0, s49
	ds_read_b128 v[186:189], v154 offset:16384
	ds_read_b128 v[190:193], v154 offset:17408
	ds_read_b128 v[194:197], v154 offset:18432
	ds_read_b128 v[198:201], v154 offset:19456
	ds_read_b128 v[202:205], v154 offset:20480
	ds_read_b128 v[206:209], v154 offset:21504
	ds_read_b128 v[210:213], v154 offset:22528
	ds_read_b128 v[214:217], v154 offset:23552
	global_load_lds_dwordx4 v[218:219], off
	s_add_i32 m0, s49, 0x2000
	s_add_u32 s50, s22, 0x80000
	v_lshl_add_u64 v[220:221], s[22:23], 0, v[130:131]
	s_addc_u32 s51, s23, 0
	s_add_i32 s49, s40, s28
	global_load_lds_dwordx4 v[220:221], off
	v_lshl_add_u64 v[222:223], s[50:51], 0, v[134:135]
	s_mov_b32 m0, s49
	v_lshl_add_u64 v[224:225], s[24:25], 0, v[132:133]
	global_load_lds_dwordx4 v[222:223], off
	v_lshl_add_u64 v[222:223], s[50:51], 0, v[130:131]
	s_add_i32 m0, s49, 0x2000
	s_nop 0
	global_load_lds_dwordx4 v[222:223], off
	v_lshl_add_u64 v[222:223], s[24:25], 0, v[136:137]
	s_mov_b32 m0, s19
	s_nop 0
	global_load_lds_dwordx4 v[222:223], off
	s_mov_b32 m0, s31
	s_nop 0
	global_load_lds_dwordx4 v[224:225], off
	s_waitcnt vmcnt(8)
	s_waitcnt lgkmcnt(0)
	s_setprio 1
	s_barrier
; #define PG8_STAGE(bufoff, gbase, voff) do { _Pragma("unroll") for (int _i = 0; _i < 2; ++_i) \
;         __builtin_amdgcn_global_load_lds((const unsigned*)((const char*)(gbase) + (voff)[_i]), (PG8_LAS unsigned*)(lds + (bufoff) + ldsw + _i * 8192), 16, 0, 0); } while (0)
; #define PG8_WAIT_V(n) asm volatile("s_waitcnt vmcnt(" #n ")" ::: "memory")
; #define PG8_WAIT_L(n) asm volatile("s_waitcnt lgkmcnt(" #n ")" ::: "memory")
; #define PG8_BAR __builtin_amdgcn_s_barrier()
; #define PG8_SCHED __builtin_amdgcn_sched_barrier(0)
; template <class Epi, class Sched, bool ALIGN_EPI = true, bool SP2 = true>
; __device__ __forceinline__ void gemm_phase(PG8_LAS unsigned char* lds, const int K  , const Sched& S, const Epi& E) {
;     ...
;             PG8_WAIT_V(8); PG8_WAIT_L(0); PG8_BAR; PG8_MMA(1, 0, At, B0); PG8_MMA(1, 1, At, B1); PG8_BAR; PG8_SCHED;
;             PG8_LDB(B0, 1, 0); PG8_LDB(B1, 1, 1); PG8_SCHED; PG8_LDA(At, 1, 0); PG8_STAGE(PG8_SA(0, 1), a2 + hstep, voffA);
;             PG8_WAIT_V(8); PG8_WAIT_L(0); PG8_BAR; PG8_MMA(0, 0, At, B0); PG8_MMA(0, 1, At, B1); PG8_BAR; PG8_SCHED;
	v_mfma_f32_16x16x32_bf16 v[62:65], v[146:149], v[186:189], v[62:65]
	v_mfma_f32_16x16x32_bf16 v[54:57], v[162:165], v[186:189], v[54:57]
	v_mfma_f32_16x16x32_bf16 v[46:49], v[146:149], v[194:197], v[46:49]
	v_mfma_f32_16x16x32_bf16 v[38:41], v[162:165], v[194:197], v[38:41]
	v_mfma_f32_16x16x32_bf16 v[30:33], v[146:149], v[202:205], v[30:33]
	v_mfma_f32_16x16x32_bf16 v[22:25], v[162:165], v[202:205], v[22:25]
	v_mfma_f32_16x16x32_bf16 v[14:17], v[146:149], v[210:213], v[14:17]
	v_mfma_f32_16x16x32_bf16 v[6:9], v[162:165], v[210:213], v[6:9]
	v_mfma_f32_16x16x32_bf16 v[62:65], v[158:161], v[190:193], v[62:65]
	v_mfma_f32_16x16x32_bf16 v[54:57], v[166:169], v[190:193], v[54:57]
	v_mfma_f32_16x16x32_bf16 v[46:49], v[158:161], v[198:201], v[46:49]
	v_mfma_f32_16x16x32_bf16 v[38:41], v[166:169], v[198:201], v[38:41]
	v_mfma_f32_16x16x32_bf16 v[30:33], v[158:161], v[206:209], v[30:33]
	v_mfma_f32_16x16x32_bf16 v[22:25], v[166:169], v[206:209], v[22:25]
	v_mfma_f32_16x16x32_bf16 v[14:17], v[158:161], v[214:217], v[14:17]
	v_mfma_f32_16x16x32_bf16 v[6:9], v[166:169], v[214:217], v[6:9]
	v_mfma_f32_16x16x32_bf16 v[58:61], v[170:173], v[186:189], v[58:61]
	v_mfma_f32_16x16x32_bf16 v[50:53], v[178:181], v[186:189], v[50:53]
	v_mfma_f32_16x16x32_bf16 v[42:45], v[170:173], v[194:197], v[42:45]
	v_mfma_f32_16x16x32_bf16 v[34:37], v[178:181], v[194:197], v[34:37]
	v_mfma_f32_16x16x32_bf16 v[26:29], v[170:173], v[202:205], v[26:29]
	v_mfma_f32_16x16x32_bf16 v[18:21], v[178:181], v[202:205], v[18:21]
	v_mfma_f32_16x16x32_bf16 v[10:13], v[170:173], v[210:213], v[10:13]
	v_mfma_f32_16x16x32_bf16 v[2:5], v[178:181], v[210:213], v[2:5]
	v_mfma_f32_16x16x32_bf16 v[58:61], v[174:177], v[190:193], v[58:61]
	v_mfma_f32_16x16x32_bf16 v[50:53], v[182:185], v[190:193], v[50:53]
	v_mfma_f32_16x16x32_bf16 v[42:45], v[174:177], v[198:201], v[42:45]
	v_mfma_f32_16x16x32_bf16 v[34:37], v[182:185], v[198:201], v[34:37]
	v_mfma_f32_16x16x32_bf16 v[26:29], v[174:177], v[206:209], v[26:29]
	v_mfma_f32_16x16x32_bf16 v[18:21], v[182:185], v[206:209], v[18:21]
	v_mfma_f32_16x16x32_bf16 v[10:13], v[174:177], v[214:217], v[10:13]
	v_mfma_f32_16x16x32_bf16 v[2:5], v[182:185], v[214:217], v[2:5]
	s_barrier
	s_setprio 0
	s_add_i32 s49, 0, 0x18000
	v_add_u32_e32 v157, s49, v150
	s_add_i32 s50, 0, 0x1c000
	ds_read_b128 v[146:149], v157
	ds_read_b128 v[158:161], v157 offset:1024
	ds_read_b128 v[162:165], v157 offset:2048
	ds_read_b128 v[166:169], v157 offset:3072
	v_add_u32_e32 v157, s50, v150
	ds_read_b128 v[170:173], v157
	ds_read_b128 v[174:177], v157 offset:1024
	ds_read_b128 v[178:181], v157 offset:2048
	ds_read_b128 v[182:185], v157 offset:3072
	s_add_u32 s24, s24, 0x80000
	s_addc_u32 s25, s25, 0
	s_mov_b32 m0, s33
	v_lshl_add_u64 v[226:227], s[24:25], 0, v[136:137]
	ds_read_b128 v[186:189], v154 offset:32768
	ds_read_b128 v[190:193], v154 offset:33792
	ds_read_b128 v[194:197], v154 offset:34816
	ds_read_b128 v[198:201], v154 offset:35840
	ds_read_b128 v[202:205], v154 offset:36864
	ds_read_b128 v[206:209], v154 offset:37888
	ds_read_b128 v[210:213], v154 offset:38912
	ds_read_b128 v[214:217], v154 offset:39936
	global_load_lds_dwordx4 v[226:227], off
	v_lshl_add_u64 v[226:227], s[24:25], 0, v[132:133]
	s_mov_b32 m0, s34
	s_nop 0
	global_load_lds_dwordx4 v[226:227], off
	s_waitcnt vmcnt(8)
	s_waitcnt lgkmcnt(0)
	s_setprio 1
	s_barrier
	v_mfma_f32_16x16x32_bf16 v[126:129], v[146:149], v[186:189], v[126:129]
	v_mfma_f32_16x16x32_bf16 v[118:121], v[162:165], v[186:189], v[118:121]
	v_mfma_f32_16x16x32_bf16 v[110:113], v[146:149], v[194:197], v[110:113]
	v_mfma_f32_16x16x32_bf16 v[102:105], v[162:165], v[194:197], v[102:105]
	v_mfma_f32_16x16x32_bf16 v[94:97], v[146:149], v[202:205], v[94:97]
	v_mfma_f32_16x16x32_bf16 v[86:89], v[162:165], v[202:205], v[86:89]
	v_mfma_f32_16x16x32_bf16 v[78:81], v[146:149], v[210:213], v[78:81]
	v_mfma_f32_16x16x32_bf16 v[70:73], v[162:165], v[210:213], v[70:73]
	v_mfma_f32_16x16x32_bf16 v[126:129], v[158:161], v[190:193], v[126:129]
	v_mfma_f32_16x16x32_bf16 v[118:121], v[166:169], v[190:193], v[118:121]
	v_mfma_f32_16x16x32_bf16 v[110:113], v[158:161], v[198:201], v[110:113]
	v_mfma_f32_16x16x32_bf16 v[102:105], v[166:169], v[198:201], v[102:105]
	v_mfma_f32_16x16x32_bf16 v[94:97], v[158:161], v[206:209], v[94:97]
	v_mfma_f32_16x16x32_bf16 v[86:89], v[166:169], v[206:209], v[86:89]
	v_mfma_f32_16x16x32_bf16 v[78:81], v[158:161], v[214:217], v[78:81]
	v_mfma_f32_16x16x32_bf16 v[70:73], v[166:169], v[214:217], v[70:73]
	v_mfma_f32_16x16x32_bf16 v[122:125], v[170:173], v[186:189], v[122:125]
	v_mfma_f32_16x16x32_bf16 v[114:117], v[178:181], v[186:189], v[114:117]
	v_mfma_f32_16x16x32_bf16 v[106:109], v[170:173], v[194:197], v[106:109]
	v_mfma_f32_16x16x32_bf16 v[98:101], v[178:181], v[194:197], v[98:101]
	v_mfma_f32_16x16x32_bf16 v[90:93], v[170:173], v[202:205], v[90:93]
	v_mfma_f32_16x16x32_bf16 v[82:85], v[178:181], v[202:205], v[82:85]
	v_mfma_f32_16x16x32_bf16 v[74:77], v[170:173], v[210:213], v[74:77]
	v_mfma_f32_16x16x32_bf16 v[66:69], v[178:181], v[210:213], v[66:69]
	v_mfma_f32_16x16x32_bf16 v[122:125], v[174:177], v[190:193], v[122:125]
	v_mfma_f32_16x16x32_bf16 v[114:117], v[182:185], v[190:193], v[114:117]
	v_mfma_f32_16x16x32_bf16 v[106:109], v[174:177], v[198:201], v[106:109]
	v_mfma_f32_16x16x32_bf16 v[98:101], v[182:185], v[198:201], v[98:101]
	v_mfma_f32_16x16x32_bf16 v[90:93], v[174:177], v[206:209], v[90:93]
	v_mfma_f32_16x16x32_bf16 v[82:85], v[182:185], v[206:209], v[82:85]
	v_mfma_f32_16x16x32_bf16 v[74:77], v[174:177], v[214:217], v[74:77]
	v_mfma_f32_16x16x32_bf16 v[66:69], v[182:185], v[214:217], v[66:69]
	s_barrier
; #define PG8_STAGE(bufoff, gbase, voff) do { _Pragma("unroll") for (int _i = 0; _i < 2; ++_i) \
;         __builtin_amdgcn_global_load_lds((const unsigned*)((const char*)(gbase) + (voff)[_i]), (PG8_LAS unsigned*)(lds + (bufoff) + ldsw + _i * 8192), 16, 0, 0); } while (0)
; #define PG8_WAIT_V(n) asm volatile("s_waitcnt vmcnt(" #n ")" ::: "memory")
; #define PG8_WAIT_L(n) asm volatile("s_waitcnt lgkmcnt(" #n ")" ::: "memory")
; #define PG8_BAR __builtin_amdgcn_s_barrier()
; #define PG8_SCHED __builtin_amdgcn_sched_barrier(0)
; template <class Epi, class Sched, bool ALIGN_EPI = true, bool SP2 = true>
; __device__ __forceinline__ void gemm_phase(PG8_LAS unsigned char* lds, const int K  , const Sched& S, const Epi& E) {
;     ...
;             PG8_LDA(At, 1, 1); PG8_STAGE(PG8_SB(1, 0), b3, voffB); PG8_STAGE(PG8_SB(1, 1), b3 + hstep, voffB); PG8_STAGE(PG8_SA(1, 0), a3, voffA);
;             PG8_WAIT_V(8); PG8_WAIT_L(0); PG8_BAR; PG8_MMA(1, 0, At, B0); PG8_MMA(1, 1, At, B1); PG8_BAR; PG8_SCHED;
	s_setprio 0
	s_add_i32 s24, s49, s28
	v_lshl_add_u64 v[218:219], v[218:219], 0, s[6:7]
	s_mov_b32 m0, s24
	ds_read_b128 v[186:189], v154 offset:49152
	ds_read_b128 v[190:193], v154 offset:50176
	ds_read_b128 v[194:197], v154 offset:51200
	ds_read_b128 v[198:201], v154 offset:52224
	ds_read_b128 v[202:205], v154 offset:53248
	ds_read_b128 v[206:209], v154 offset:54272
	ds_read_b128 v[210:213], v154 offset:55296
	ds_read_b128 v[214:217], v154 offset:56320
	global_load_lds_dwordx4 v[218:219], off
	s_add_i32 m0, s24, 0x2000
	s_add_u32 s22, s22, 0x80080
	v_lshl_add_u64 v[218:219], v[220:221], 0, s[6:7]
	s_addc_u32 s23, s23, 0
	s_add_i32 s24, s50, s28
	global_load_lds_dwordx4 v[218:219], off
	v_lshl_add_u64 v[218:219], s[22:23], 0, v[134:135]
	s_mov_b32 m0, s24
	s_nop 0
	global_load_lds_dwordx4 v[218:219], off
	v_lshl_add_u64 v[218:219], s[22:23], 0, v[130:131]
	s_add_i32 m0, s24, 0x2000
	s_nop 0
	global_load_lds_dwordx4 v[218:219], off
	v_lshl_add_u64 v[218:219], v[222:223], 0, s[6:7]
	s_mov_b32 m0, s36
	s_nop 0
	global_load_lds_dwordx4 v[218:219], off
	v_lshl_add_u64 v[218:219], v[224:225], 0, s[6:7]
	s_mov_b32 m0, s37
	s_nop 0
	global_load_lds_dwordx4 v[218:219], off
	s_waitcnt vmcnt(8)
	s_waitcnt lgkmcnt(0)
	s_setprio 1
	s_barrier
	v_mfma_f32_16x16x32_bf16 v[62:65], v[146:149], v[186:189], v[62:65]
	v_mfma_f32_16x16x32_bf16 v[54:57], v[162:165], v[186:189], v[54:57]
	v_mfma_f32_16x16x32_bf16 v[46:49], v[146:149], v[194:197], v[46:49]
	v_mfma_f32_16x16x32_bf16 v[38:41], v[162:165], v[194:197], v[38:41]
	v_mfma_f32_16x16x32_bf16 v[30:33], v[146:149], v[202:205], v[30:33]
	v_mfma_f32_16x16x32_bf16 v[22:25], v[162:165], v[202:205], v[22:25]
	v_mfma_f32_16x16x32_bf16 v[14:17], v[146:149], v[210:213], v[14:17]
	v_mfma_f32_16x16x32_bf16 v[6:9], v[162:165], v[210:213], v[6:9]
	v_mfma_f32_16x16x32_bf16 v[62:65], v[158:161], v[190:193], v[62:65]
	v_mfma_f32_16x16x32_bf16 v[54:57], v[166:169], v[190:193], v[54:57]
	v_mfma_f32_16x16x32_bf16 v[46:49], v[158:161], v[198:201], v[46:49]
	v_mfma_f32_16x16x32_bf16 v[38:41], v[166:169], v[198:201], v[38:41]
	v_mfma_f32_16x16x32_bf16 v[30:33], v[158:161], v[206:209], v[30:33]
	v_mfma_f32_16x16x32_bf16 v[22:25], v[166:169], v[206:209], v[22:25]
	v_mfma_f32_16x16x32_bf16 v[14:17], v[158:161], v[214:217], v[14:17]
	v_mfma_f32_16x16x32_bf16 v[6:9], v[166:169], v[214:217], v[6:9]
	v_mfma_f32_16x16x32_bf16 v[58:61], v[170:173], v[186:189], v[58:61]
	v_mfma_f32_16x16x32_bf16 v[50:53], v[178:181], v[186:189], v[50:53]
	v_mfma_f32_16x16x32_bf16 v[42:45], v[170:173], v[194:197], v[42:45]
	v_mfma_f32_16x16x32_bf16 v[34:37], v[178:181], v[194:197], v[34:37]
	v_mfma_f32_16x16x32_bf16 v[26:29], v[170:173], v[202:205], v[26:29]
	v_mfma_f32_16x16x32_bf16 v[18:21], v[178:181], v[202:205], v[18:21]
	v_mfma_f32_16x16x32_bf16 v[10:13], v[170:173], v[210:213], v[10:13]
	v_mfma_f32_16x16x32_bf16 v[2:5], v[178:181], v[210:213], v[2:5]
	v_mfma_f32_16x16x32_bf16 v[58:61], v[174:177], v[190:193], v[58:61]
	v_mfma_f32_16x16x32_bf16 v[50:53], v[182:185], v[190:193], v[50:53]
	v_mfma_f32_16x16x32_bf16 v[42:45], v[174:177], v[198:201], v[42:45]
	v_mfma_f32_16x16x32_bf16 v[34:37], v[182:185], v[198:201], v[34:37]
	v_mfma_f32_16x16x32_bf16 v[26:29], v[174:177], v[206:209], v[26:29]
	v_mfma_f32_16x16x32_bf16 v[18:21], v[182:185], v[206:209], v[18:21]
	v_mfma_f32_16x16x32_bf16 v[10:13], v[174:177], v[214:217], v[10:13]
	v_mfma_f32_16x16x32_bf16 v[2:5], v[182:185], v[214:217], v[2:5]
	s_barrier
	s_setprio 0
	s_add_i32 s48, s48, 2
	s_add_u32 s20, s20, 0x100
	s_addc_u32 s21, s21, 0
	s_add_u32 s46, s46, 0x100
	s_addc_u32 s47, s47, 0
	s_cmp_gt_u32 s48, 29
	s_cbranch_scc0 .LBB0_2433
	s_and_b64 vcc, exec, s[8:9]
	s_cbranch_vccz .LBB0_2436
	s_barrier

; #define PG8_STAGE(bufoff, gbase, voff) do { _Pragma("unroll") for (int _i = 0; _i < 2; ++_i) \
;         __builtin_amdgcn_global_load_lds((const unsigned*)((const char*)(gbase) + (voff)[_i]), (PG8_LAS unsigned*)(lds + (bufoff) + ldsw + _i * 8192), 16, 0, 0); } while (0)
; #define PG8_WAIT_V(n) asm volatile("s_waitcnt vmcnt(" #n ")" ::: "memory")
; #define PG8_WAIT_L(n) asm volatile("s_waitcnt lgkmcnt(" #n ")" ::: "memory")
; #define PG8_BAR __builtin_amdgcn_s_barrier()
; #define PG8_SCHED __builtin_amdgcn_sched_barrier(0)
;     __device__ __forceinline__ int nt(const pg8::Unit& u) const { return u.kind == 0 ? ntiles : q_nt(u.kind - 1); }
; template <class Epi, class Sched, bool ALIGN_EPI = true, bool SP2 = true>
; __device__ __forceinline__ void gemm_phase(PG8_LAS unsigned char* lds, const int K  , const Sched& S, const Epi& E) {
;     ...
;             const bool last = (t == nt - 2);
;             const char* a1 = cA + (size_t)(t + 1) * kstep;
;             const char* a2 = last ? nA : cA + (size_t)(t + 2) * kstep; const char* b2 = last ? nB : cB + (size_t)(t + 2) * kstep;
;             const char* a3 = a2 + kstep; const char* b3 = b2 + kstep;
;             if constexpr (SP2) {
;             PG8_LDB(B0, 0, 0); PG8_LDB(B1, 0, 1); PG8_SCHED; PG8_LDA(At, 0, 0); PG8_STAGE(PG8_SA(1, 1), a1 + hstep, voffA);
;             PG8_WAIT_V(8); PG8_WAIT_L(0); PG8_BAR; PG8_MMA(0, 0, At, B0); PG8_MMA(0, 1, At, B1); PG8_BAR; PG8_SCHED;
;             PG8_LDA(At, 0, 1); PG8_STAGE(PG8_SB(0, 0), b2, voffB); PG8_STAGE(PG8_SB(0, 1), b2 + hstep, voffB); PG8_STAGE(PG8_SA(0, 0), a2, voffA);
;             PG8_WAIT_V(8); PG8_WAIT_L(0); PG8_BAR; PG8_MMA(1, 0, At, B0); PG8_MMA(1, 1, At, B1); PG8_BAR; PG8_SCHED;
.LBB0_2516:
	ds_read_b128 v[16:19], v206
	ds_read_b128 v[20:23], v206 offset:1024
	ds_read_b128 v[24:27], v206 offset:2048
	ds_read_b128 v[28:31], v206 offset:3072
	ds_read_b128 v[0:3], v207
	ds_read_b128 v[4:7], v207 offset:1024
	ds_read_b128 v[8:11], v207 offset:2048
	ds_read_b128 v[12:15], v207 offset:3072
	s_add_u32 s18, s16, 0xfff50080
	s_addc_u32 s19, s17, -1
	s_cmp_eq_u32 s57, 40
	s_cselect_b32 s21, s7, s19
	s_cselect_b32 s20, s6, s18
	s_cselect_b32 s19, s15, s56
	s_cselect_b32 s18, s14, s55
	v_lshl_add_u64 v[200:201], s[16:17], 0, v[176:177]
	s_add_i32 m0, s25, 0xc000
	ds_read_b128 v[160:163], v208
	ds_read_b128 v[164:167], v208 offset:1024
	ds_read_b128 v[184:187], v208 offset:2048
	ds_read_b128 v[188:191], v208 offset:3072
	ds_read_b128 v[192:195], v208 offset:4096
	ds_read_b128 v[196:199], v208 offset:5120
	ds_read_b128 v[210:213], v208 offset:6144
	ds_read_b128 v[214:217], v208 offset:7168
	global_load_lds_dwordx4 v[200:201], off
	v_lshl_add_u64 v[200:201], s[16:17], 0, v[178:179]
	s_add_i32 m0, s25, 0xe000
	s_nop 0
	global_load_lds_dwordx4 v[200:201], off
	s_waitcnt vmcnt(8)
	s_waitcnt lgkmcnt(0)
	s_setprio 1
	s_barrier
	v_mfma_scale_f32_16x16x128_f8f6f4 v[156:159], v[16:23], v[160:167], v[156:159], v202, v202 op_sel_hi:[0,0,0]
	v_mfma_scale_f32_16x16x128_f8f6f4 v[152:155], v[24:31], v[160:167], v[152:155], v202, v202 op_sel_hi:[0,0,0]
	v_mfma_scale_f32_16x16x128_f8f6f4 v[140:143], v[16:23], v[184:191], v[140:143], v202, v202 op_sel_hi:[0,0,0]
	v_mfma_scale_f32_16x16x128_f8f6f4 v[136:139], v[24:31], v[184:191], v[136:139], v202, v202 op_sel_hi:[0,0,0]
	v_mfma_scale_f32_16x16x128_f8f6f4 v[124:127], v[16:23], v[192:199], v[124:127], v202, v202 op_sel_hi:[0,0,0]
	v_mfma_scale_f32_16x16x128_f8f6f4 v[120:123], v[24:31], v[192:199], v[120:123], v202, v202 op_sel_hi:[0,0,0]
	v_mfma_scale_f32_16x16x128_f8f6f4 v[108:111], v[16:23], v[210:217], v[108:111], v202, v202 op_sel_hi:[0,0,0]
	v_mfma_scale_f32_16x16x128_f8f6f4 v[104:107], v[24:31], v[210:217], v[104:107], v202, v202 op_sel_hi:[0,0,0]
	v_mfma_scale_f32_16x16x128_f8f6f4 v[148:151], v[0:7], v[160:167], v[148:151], v202, v202 op_sel_hi:[0,0,0]
	v_mfma_scale_f32_16x16x128_f8f6f4 v[144:147], v[8:15], v[160:167], v[144:147], v202, v202 op_sel_hi:[0,0,0]
	v_mfma_scale_f32_16x16x128_f8f6f4 v[132:135], v[0:7], v[184:191], v[132:135], v202, v202 op_sel_hi:[0,0,0]
	v_mfma_scale_f32_16x16x128_f8f6f4 v[128:131], v[8:15], v[184:191], v[128:131], v202, v202 op_sel_hi:[0,0,0]
	v_mfma_scale_f32_16x16x128_f8f6f4 v[116:119], v[0:7], v[192:199], v[116:119], v202, v202 op_sel_hi:[0,0,0]
	v_mfma_scale_f32_16x16x128_f8f6f4 v[112:115], v[8:15], v[192:199], v[112:115], v202, v202 op_sel_hi:[0,0,0]
	v_mfma_scale_f32_16x16x128_f8f6f4 v[100:103], v[0:7], v[210:217], v[100:103], v202, v202 op_sel_hi:[0,0,0]
	v_mfma_scale_f32_16x16x128_f8f6f4 v[96:99], v[8:15], v[210:217], v[96:99], v202, v202 op_sel_hi:[0,0,0]
	s_barrier
	s_setprio 0
	s_add_i32 s58, s38, s24
	v_lshl_add_u64 v[160:161], s[18:19], 0, v[170:171]
	s_mov_b32 m0, s58
	ds_read_b128 v[184:187], v208 offset:16384
	ds_read_b128 v[188:191], v208 offset:17408
	ds_read_b128 v[192:195], v208 offset:18432
	ds_read_b128 v[196:199], v208 offset:19456
	ds_read_b128 v[210:213], v208 offset:20480
	ds_read_b128 v[214:217], v208 offset:21504
	ds_read_b128 v[218:221], v208 offset:22528
	ds_read_b128 v[222:225], v208 offset:23552
	global_load_lds_dwordx4 v[160:161], off
	s_add_i32 m0, s58, 0x2000
	s_add_u32 s58, s18, 0xb0000
	v_lshl_add_u64 v[162:163], s[18:19], 0, v[174:175]
	s_addc_u32 s59, s19, 0
	s_add_i32 s60, s39, s24
	global_load_lds_dwordx4 v[162:163], off
	v_lshl_add_u64 v[164:165], s[58:59], 0, v[170:171]
	s_mov_b32 m0, s60
	v_lshl_add_u64 v[166:167], s[20:21], 0, v[172:173]
	global_load_lds_dwordx4 v[164:165], off
	v_lshl_add_u64 v[164:165], s[58:59], 0, v[174:175]
	s_add_i32 m0, s60, 0x2000
	s_nop 0
	global_load_lds_dwordx4 v[164:165], off
	v_lshl_add_u64 v[164:165], s[20:21], 0, v[168:169]
	s_mov_b32 m0, s25
	s_nop 0
	global_load_lds_dwordx4 v[164:165], off
	s_mov_b32 m0, s26
	s_nop 0
	global_load_lds_dwordx4 v[166:167], off
	s_waitcnt vmcnt(8)
	s_waitcnt lgkmcnt(0)
	s_setprio 1
	s_barrier
	v_mfma_scale_f32_16x16x128_f8f6f4 v[92:95], v[16:23], v[184:191], v[92:95], v202, v202 op_sel_hi:[0,0,0]
	v_mfma_scale_f32_16x16x128_f8f6f4 v[88:91], v[24:31], v[184:191], v[88:91], v202, v202 op_sel_hi:[0,0,0]
	v_mfma_scale_f32_16x16x128_f8f6f4 v[76:79], v[16:23], v[192:199], v[76:79], v202, v202 op_sel_hi:[0,0,0]
	v_mfma_scale_f32_16x16x128_f8f6f4 v[72:75], v[24:31], v[192:199], v[72:75], v202, v202 op_sel_hi:[0,0,0]
	v_mfma_scale_f32_16x16x128_f8f6f4 v[60:63], v[16:23], v[210:217], v[60:63], v202, v202 op_sel_hi:[0,0,0]
	v_mfma_scale_f32_16x16x128_f8f6f4 v[56:59], v[24:31], v[210:217], v[56:59], v202, v202 op_sel_hi:[0,0,0]
	v_mfma_scale_f32_16x16x128_f8f6f4 v[44:47], v[16:23], v[218:225], v[44:47], v202, v202 op_sel_hi:[0,0,0]
	v_mfma_scale_f32_16x16x128_f8f6f4 v[40:43], v[24:31], v[218:225], v[40:43], v202, v202 op_sel_hi:[0,0,0]
	v_mfma_scale_f32_16x16x128_f8f6f4 v[84:87], v[0:7], v[184:191], v[84:87], v202, v202 op_sel_hi:[0,0,0]
	v_mfma_scale_f32_16x16x128_f8f6f4 v[80:83], v[8:15], v[184:191], v[80:83], v202, v202 op_sel_hi:[0,0,0]
	v_mfma_scale_f32_16x16x128_f8f6f4 v[68:71], v[0:7], v[192:199], v[68:71], v202, v202 op_sel_hi:[0,0,0]
	v_mfma_scale_f32_16x16x128_f8f6f4 v[64:67], v[8:15], v[192:199], v[64:67], v202, v202 op_sel_hi:[0,0,0]
	v_mfma_scale_f32_16x16x128_f8f6f4 v[52:55], v[0:7], v[210:217], v[52:55], v202, v202 op_sel_hi:[0,0,0]
	v_mfma_scale_f32_16x16x128_f8f6f4 v[48:51], v[8:15], v[210:217], v[48:51], v202, v202 op_sel_hi:[0,0,0]
	v_mfma_scale_f32_16x16x128_f8f6f4 v[36:39], v[0:7], v[218:225], v[36:39], v202, v202 op_sel_hi:[0,0,0]
	v_mfma_scale_f32_16x16x128_f8f6f4 v[32:35], v[8:15], v[218:225], v[32:35], v202, v202 op_sel_hi:[0,0,0]
	s_barrier
; #define PG8_WAIT_V(n) asm volatile("s_waitcnt vmcnt(" #n ")" ::: "memory")
; #define PG8_WAIT_L(n) asm volatile("s_waitcnt lgkmcnt(" #n ")" ::: "memory")
; #define PG8_BAR __builtin_amdgcn_s_barrier()
; template <class Epi, class Sched, bool ALIGN_EPI = true, bool SP2 = true>
; __device__ __forceinline__ void gemm_phase(PG8_LAS unsigned char* lds, const int K  , const Sched& S, const Epi& E) {
;     ...
;             PG8_LDB(B0, 1, 0); PG8_LDB(B1, 1, 1); PG8_SCHED; PG8_LDA(At, 1, 0); PG8_STAGE(PG8_SA(0, 1), a2 + hstep, voffA);
;             PG8_WAIT_V(8); PG8_WAIT_L(0); PG8_BAR; PG8_MMA(0, 0, At, B0); PG8_MMA(0, 1, At, B1); PG8_BAR; PG8_SCHED;
;             PG8_LDA(At, 1, 1); PG8_STAGE(PG8_SB(1, 0), b3, voffB); PG8_STAGE(PG8_SB(1, 1), b3 + hstep, voffB); PG8_STAGE(PG8_SA(1, 0), a3, voffA);
;             PG8_WAIT_V(8); PG8_WAIT_L(0); PG8_BAR; PG8_MMA(1, 0, At, B0); PG8_MMA(1, 1, At, B1); PG8_BAR; PG8_SCHED;
;             } else {
;             PG8_LDB(B0, 0, 0); PG8_SCHED; PG8_LDA(At, 0, 0); PG8_STAGE(PG8_SA(1, 1), a1 + hstep, voffA);
;             PG8_WAIT_L(8); PG8_BAR; PG8_WAIT_L(0); PG8_MMA(0, 0, At, B0); PG8_BAR; PG8_SCHED;
;             PG8_LDB(B1, 0, 1); PG8_STAGE(PG8_SB(0, 0), b2, voffB);
;             PG8_BAR; PG8_WAIT_L(0); PG8_MMA(0, 1, At, B1); PG8_BAR;
;             PG8_LDA(At, 0, 1); PG8_STAGE(PG8_SA(0, 0), a2, voffA);
;             PG8_BAR; PG8_WAIT_L(0); PG8_MMA(1, 0, At, B0); PG8_BAR; PG8_SCHED;
;             PG8_STAGE(PG8_SB(0, 1), b2 + hstep, voffB);
;             PG8_WAIT_V(6); PG8_BAR; PG8_MMA(1, 1, At, B1); PG8_BAR;
;             PG8_LDB(B0, 1, 0); PG8_SCHED; PG8_LDA(At, 1, 0); PG8_STAGE(PG8_SA(0, 1), a2 + hstep, voffA);
;             PG8_WAIT_L(8); PG8_BAR; PG8_WAIT_L(0); PG8_MMA(0, 0, At, B0); PG8_BAR; PG8_SCHED;
;             PG8_LDB(B1, 1, 1); PG8_STAGE(PG8_SB(1, 0), b3, voffB);
;             PG8_BAR; PG8_WAIT_L(0); PG8_MMA(0, 1, At, B1); PG8_BAR;
;             PG8_LDA(At, 1, 1); PG8_STAGE(PG8_SA(1, 0), a3, voffA);
;             PG8_BAR; PG8_WAIT_L(0); PG8_MMA(1, 0, At, B0); PG8_BAR; PG8_SCHED;
;             PG8_STAGE(PG8_SB(1, 1), b3 + hstep, voffB);
;             PG8_WAIT_V(6); PG8_BAR; PG8_MMA(1, 1, At, B1); PG8_BAR;
;             }
;         }
;         if constexpr (Epi::FP8) asm volatile("s_nop 15\n\ts_nop 15\n\ts_nop 15\n\ts_nop 15\n\ts_nop 15" ::: "memory");
;         if constexpr (ALIGN_EPI) { if (wr == 0) PG8_BAR; }
	s_setprio 0
	s_add_i32 s58, 0, 0x18000
	s_add_i32 s59, 0, 0x1c000
	v_add_u32_e32 v12, s58, v204
	v_add_u32_e32 v28, s59, v204
	ds_read_b128 v[0:3], v12
	ds_read_b128 v[4:7], v12 offset:1024
	ds_read_b128 v[8:11], v12 offset:2048
	ds_read_b128 v[12:15], v12 offset:3072
	ds_read_b128 v[16:19], v28
	ds_read_b128 v[20:23], v28 offset:1024
	ds_read_b128 v[24:27], v28 offset:2048
	ds_read_b128 v[28:31], v28 offset:3072
	s_add_u32 s20, s20, 0xb0000
	s_addc_u32 s21, s21, 0
	s_mov_b32 m0, s27
	v_lshl_add_u64 v[200:201], s[20:21], 0, v[168:169]
	ds_read_b128 v[184:187], v208 offset:32768
	ds_read_b128 v[188:191], v208 offset:33792
	ds_read_b128 v[192:195], v208 offset:34816
	ds_read_b128 v[196:199], v208 offset:35840
	ds_read_b128 v[210:213], v208 offset:36864
	ds_read_b128 v[214:217], v208 offset:37888
	ds_read_b128 v[218:221], v208 offset:38912
	ds_read_b128 v[222:225], v208 offset:39936
	global_load_lds_dwordx4 v[200:201], off
	v_lshl_add_u64 v[200:201], s[20:21], 0, v[172:173]
	s_mov_b32 m0, s28
	s_nop 0
	global_load_lds_dwordx4 v[200:201], off
	s_waitcnt vmcnt(8)
	s_waitcnt lgkmcnt(0)
	s_setprio 1
	s_barrier
	v_mfma_scale_f32_16x16x128_f8f6f4 v[156:159], v[0:7], v[184:191], v[156:159], v202, v202 op_sel_hi:[0,0,0]
	v_mfma_scale_f32_16x16x128_f8f6f4 v[152:155], v[8:15], v[184:191], v[152:155], v202, v202 op_sel_hi:[0,0,0]
	v_mfma_scale_f32_16x16x128_f8f6f4 v[140:143], v[0:7], v[192:199], v[140:143], v202, v202 op_sel_hi:[0,0,0]
	v_mfma_scale_f32_16x16x128_f8f6f4 v[136:139], v[8:15], v[192:199], v[136:139], v202, v202 op_sel_hi:[0,0,0]
	v_mfma_scale_f32_16x16x128_f8f6f4 v[124:127], v[0:7], v[210:217], v[124:127], v202, v202 op_sel_hi:[0,0,0]
	v_mfma_scale_f32_16x16x128_f8f6f4 v[120:123], v[8:15], v[210:217], v[120:123], v202, v202 op_sel_hi:[0,0,0]
	v_mfma_scale_f32_16x16x128_f8f6f4 v[108:111], v[0:7], v[218:225], v[108:111], v202, v202 op_sel_hi:[0,0,0]
	v_mfma_scale_f32_16x16x128_f8f6f4 v[104:107], v[8:15], v[218:225], v[104:107], v202, v202 op_sel_hi:[0,0,0]
	v_mfma_scale_f32_16x16x128_f8f6f4 v[148:151], v[16:23], v[184:191], v[148:151], v202, v202 op_sel_hi:[0,0,0]
	v_mfma_scale_f32_16x16x128_f8f6f4 v[144:147], v[24:31], v[184:191], v[144:147], v202, v202 op_sel_hi:[0,0,0]
	v_mfma_scale_f32_16x16x128_f8f6f4 v[132:135], v[16:23], v[192:199], v[132:135], v202, v202 op_sel_hi:[0,0,0]
	v_mfma_scale_f32_16x16x128_f8f6f4 v[128:131], v[24:31], v[192:199], v[128:131], v202, v202 op_sel_hi:[0,0,0]
	v_mfma_scale_f32_16x16x128_f8f6f4 v[116:119], v[16:23], v[210:217], v[116:119], v202, v202 op_sel_hi:[0,0,0]
	v_mfma_scale_f32_16x16x128_f8f6f4 v[112:115], v[24:31], v[210:217], v[112:115], v202, v202 op_sel_hi:[0,0,0]
	v_mfma_scale_f32_16x16x128_f8f6f4 v[100:103], v[16:23], v[218:225], v[100:103], v202, v202 op_sel_hi:[0,0,0]
	v_mfma_scale_f32_16x16x128_f8f6f4 v[96:99], v[24:31], v[218:225], v[96:99], v202, v202 op_sel_hi:[0,0,0]
	s_barrier
	s_setprio 0
	s_add_i32 s20, s58, s24
	v_lshl_add_u64 v[160:161], v[160:161], 0, s[8:9]
	s_mov_b32 m0, s20
	ds_read_b128 v[184:187], v208 offset:49152
	ds_read_b128 v[188:191], v208 offset:50176
	ds_read_b128 v[192:195], v208 offset:51200
	ds_read_b128 v[196:199], v208 offset:52224
	ds_read_b128 v[210:213], v208 offset:53248
	ds_read_b128 v[214:217], v208 offset:54272
	ds_read_b128 v[218:221], v208 offset:55296
	ds_read_b128 v[222:225], v208 offset:56320
	global_load_lds_dwordx4 v[160:161], off
	s_add_i32 m0, s20, 0x2000
	s_add_u32 s18, s18, 0xb0080
	v_lshl_add_u64 v[160:161], v[162:163], 0, s[8:9]
	s_addc_u32 s19, s19, 0
	s_add_i32 s20, s59, s24
	global_load_lds_dwordx4 v[160:161], off
	v_lshl_add_u64 v[160:161], s[18:19], 0, v[170:171]
	s_mov_b32 m0, s20
	s_nop 0
	global_load_lds_dwordx4 v[160:161], off
	v_lshl_add_u64 v[160:161], s[18:19], 0, v[174:175]
	s_add_i32 m0, s20, 0x2000
	s_nop 0
	global_load_lds_dwordx4 v[160:161], off
	v_lshl_add_u64 v[160:161], v[164:165], 0, s[8:9]
	s_mov_b32 m0, s35
	s_nop 0
	global_load_lds_dwordx4 v[160:161], off
	v_lshl_add_u64 v[160:161], v[166:167], 0, s[8:9]
	s_mov_b32 m0, s36
	s_nop 0
	global_load_lds_dwordx4 v[160:161], off
	s_waitcnt vmcnt(8)
	s_waitcnt lgkmcnt(0)
	s_setprio 1
	s_barrier
	v_mfma_scale_f32_16x16x128_f8f6f4 v[92:95], v[0:7], v[184:191], v[92:95], v202, v202 op_sel_hi:[0,0,0]
	v_mfma_scale_f32_16x16x128_f8f6f4 v[88:91], v[8:15], v[184:191], v[88:91], v202, v202 op_sel_hi:[0,0,0]
	v_mfma_scale_f32_16x16x128_f8f6f4 v[76:79], v[0:7], v[192:199], v[76:79], v202, v202 op_sel_hi:[0,0,0]
	v_mfma_scale_f32_16x16x128_f8f6f4 v[72:75], v[8:15], v[192:199], v[72:75], v202, v202 op_sel_hi:[0,0,0]
	v_mfma_scale_f32_16x16x128_f8f6f4 v[60:63], v[0:7], v[210:217], v[60:63], v202, v202 op_sel_hi:[0,0,0]
	v_mfma_scale_f32_16x16x128_f8f6f4 v[56:59], v[8:15], v[210:217], v[56:59], v202, v202 op_sel_hi:[0,0,0]
	v_mfma_scale_f32_16x16x128_f8f6f4 v[44:47], v[0:7], v[218:225], v[44:47], v202, v202 op_sel_hi:[0,0,0]
	v_mfma_scale_f32_16x16x128_f8f6f4 v[40:43], v[8:15], v[218:225], v[40:43], v202, v202 op_sel_hi:[0,0,0]
	v_mfma_scale_f32_16x16x128_f8f6f4 v[84:87], v[16:23], v[184:191], v[84:87], v202, v202 op_sel_hi:[0,0,0]
	v_mfma_scale_f32_16x16x128_f8f6f4 v[80:83], v[24:31], v[184:191], v[80:83], v202, v202 op_sel_hi:[0,0,0]
	v_mfma_scale_f32_16x16x128_f8f6f4 v[68:71], v[16:23], v[192:199], v[68:71], v202, v202 op_sel_hi:[0,0,0]
	v_mfma_scale_f32_16x16x128_f8f6f4 v[64:67], v[24:31], v[192:199], v[64:67], v202, v202 op_sel_hi:[0,0,0]
	v_mfma_scale_f32_16x16x128_f8f6f4 v[52:55], v[16:23], v[210:217], v[52:55], v202, v202 op_sel_hi:[0,0,0]
	v_mfma_scale_f32_16x16x128_f8f6f4 v[48:51], v[24:31], v[210:217], v[48:51], v202, v202 op_sel_hi:[0,0,0]
	v_mfma_scale_f32_16x16x128_f8f6f4 v[36:39], v[16:23], v[218:225], v[36:39], v202, v202 op_sel_hi:[0,0,0]
	v_mfma_scale_f32_16x16x128_f8f6f4 v[32:35], v[24:31], v[218:225], v[32:35], v202, v202 op_sel_hi:[0,0,0]
	s_barrier
	s_setprio 0
	s_add_i32 s57, s57, 2
	s_add_u32 s16, s16, 0x100
	s_addc_u32 s17, s17, 0
	s_add_u32 s55, s55, 0x100
	s_addc_u32 s56, s56, 0
	s_cmp_gt_u32 s57, 41
	s_cbranch_scc0 .LBB0_2516
	s_nop 15
	s_nop 15
	s_nop 15
	s_nop 15
	s_nop 15
	s_and_b64 vcc, exec, s[10:11]
	s_cbranch_vccz .LBB0_2519
	s_barrier
